# GEMM K-loops: first MFMA of each segment issued before s_setprio 1 (on top of setprio-0-after-barrier)
# speedup vs baseline: 1.0004x; 1.0004x over previous
; #define PG8_STAGE(bufoff, gbase, voff) do { _Pragma("unroll") for (int _i = 0; _i < 2; ++_i) \
;         __builtin_amdgcn_global_load_lds((const unsigned*)((const char*)(gbase) + (voff)[_i]), (LAS unsigned*)(lds + (bufoff) + ldsw + _i * 8192), 16, 0, 0); } while (0)
; #define PG8_LDA(dst, b, h) do { _Pragma("unroll") for (int m = 0; m < 4; ++m) _Pragma("unroll") for (int k = 0; k < 2; ++k) dst[m][k] = *(const LAS bf16x8*)(lds + PG8_SA(b, h) + aoff + m * 2048 + k * 1024); } while (0)
; #define PG8_LDB(dst, b, h) do { _Pragma("unroll") for (int n = 0; n < 2; ++n) _Pragma("unroll") for (int k = 0; k < 2; ++k) dst[n][k] = *(const LAS bf16x8*)(lds + PG8_SB(b, h) + boff + n * 2048 + k * 1024); } while (0)
; #define PG8_MMA(ai, bj, At, Bt) do { __builtin_amdgcn_s_setprio(1); _Pragma("unroll") for (int m = 0; m < 4; ++m) _Pragma("unroll") for (int n = 0; n < 2; ++n) _Pragma("unroll") for (int k = 0; k < 2; ++k) \
;         acc[ai][bj][m][n] = __builtin_amdgcn_mfma_f32_16x16x32_bf16(Bt[n][k], At[m][k], acc[ai][bj][m][n], 0, 0, 0); __builtin_amdgcn_s_setprio(0); } while (0)
; #define PG8_WAIT_V(n) asm volatile("s_waitcnt vmcnt(" #n ")" ::: "memory")
; #define PG8_WAIT_L(n) asm volatile("s_waitcnt lgkmcnt(" #n ")" ::: "memory")
; template <class Epi, class Sched, bool ALIGN_EPI, bool LAST_FUSED = false, bool PERM = false, bool CARRY = false>
; __device__ __forceinline__ void gemm_phase(LAS unsigned char* lds, const int tid, const int K, const int lda, const int ldb, const Sched& S, const Epi& E) {
;     ...
;         for (int t = 0; t < nt; t += 2) {
;             const bool last = (t == nt - 2);
;             const char* a1 = cA + (size_t)(t + 1) * kstep;
;             const char* a2 = last ? nA : cA + (size_t)(t + 2) * kstep; const char* b2 = last ? nB : cB + (size_t)(t + 2) * kstep;
;             const char* a3 = a2 + kstep; const char* b3 = b2 + kstep;
;             PG8_LDB(B0, 0, 0); PG8_LDB(B1, 0, 1); PG8_SCHED; PG8_LDA(At, 0, 0); PG8_STAGE(PG8_SA(1, 1), a1 + hstepA, voffA);
;             PG8_WAIT_V(8); PG8_WAIT_L(0); PG8_BAR; PG8_MMA(0, 0, At, B0); PG8_MMA(0, 1, At, B1); PG8_BAR; PG8_SCHED;
;             PG8_LDA(At, 0, 1); PG8_STAGE(PG8_SB(0, 0), b2, voffB); PG8_STAGE(PG8_SB(0, 1), b2 + hstepB, voffB); PG8_STAGE(PG8_SA(0, 0), a2, voffA);
;             PG8_WAIT_V(8); PG8_WAIT_L(0); PG8_BAR; PG8_MMA(1, 0, At, B0); PG8_MMA(1, 1, At, B1); PG8_BAR; PG8_SCHED;
.LBB0_279:
	s_add_u32 s4, s2, 0xfff80080
	s_addc_u32 s5, s3, -1
	s_add_i32 s28, 0, 0x10000
	s_cmp_eq_u32 s27, 28
	s_cselect_b32 s37, s43, s5
	s_cselect_b32 s36, s42, s4
	s_cselect_b32 s5, s71, s23
	s_cselect_b32 s4, s70, s22
	s_add_i32 s31, 0, 0x14000
	v_add_u32_e32 v154, s28, v144
	v_add_u32_e32 v170, s31, v144
	ds_read_b128 v[136:139], v154
	ds_read_b128 v[146:149], v154 offset:1024
	ds_read_b128 v[150:153], v154 offset:2048
	ds_read_b128 v[154:157], v154 offset:3072
	ds_read_b128 v[158:161], v170
	ds_read_b128 v[162:165], v170 offset:1024
	ds_read_b128 v[166:169], v170 offset:2048
	ds_read_b128 v[170:173], v170 offset:3072
	v_lshl_add_u64 v[206:207], s[2:3], 0, v[132:133]
	s_add_i32 m0, s52, 0xc000
	ds_read_b128 v[174:177], v145
	ds_read_b128 v[178:181], v145 offset:1024
	ds_read_b128 v[182:185], v145 offset:2048
	ds_read_b128 v[186:189], v145 offset:3072
	ds_read_b128 v[190:193], v145 offset:4096
	ds_read_b128 v[194:197], v145 offset:5120
	ds_read_b128 v[198:201], v145 offset:6144
	ds_read_b128 v[202:205], v145 offset:7168
	global_load_lds_dwordx4 v[206:207], off
	v_lshl_add_u64 v[206:207], s[2:3], 0, v[134:135]
	s_add_i32 m0, s52, 0xe000
	s_nop 0
	global_load_lds_dwordx4 v[206:207], off
	s_waitcnt vmcnt(8)
	s_waitcnt lgkmcnt(0)
	s_barrier
	v_mfma_f32_16x16x32_bf16 v[126:129], v[136:139], v[174:177], v[126:129]
	s_setprio 1
	v_mfma_f32_16x16x32_bf16 v[122:125], v[150:153], v[174:177], v[122:125]
	v_mfma_f32_16x16x32_bf16 v[110:113], v[136:139], v[182:185], v[110:113]
	v_mfma_f32_16x16x32_bf16 v[106:109], v[150:153], v[182:185], v[106:109]
	v_mfma_f32_16x16x32_bf16 v[94:97], v[136:139], v[190:193], v[94:97]
	v_mfma_f32_16x16x32_bf16 v[90:93], v[150:153], v[190:193], v[90:93]
	v_mfma_f32_16x16x32_bf16 v[78:81], v[136:139], v[198:201], v[78:81]
	v_mfma_f32_16x16x32_bf16 v[74:77], v[150:153], v[198:201], v[74:77]
	v_mfma_f32_16x16x32_bf16 v[126:129], v[146:149], v[178:181], v[126:129]
	v_mfma_f32_16x16x32_bf16 v[122:125], v[154:157], v[178:181], v[122:125]
	v_mfma_f32_16x16x32_bf16 v[110:113], v[146:149], v[186:189], v[110:113]
	v_mfma_f32_16x16x32_bf16 v[106:109], v[154:157], v[186:189], v[106:109]
	v_mfma_f32_16x16x32_bf16 v[94:97], v[146:149], v[194:197], v[94:97]
	v_mfma_f32_16x16x32_bf16 v[90:93], v[154:157], v[194:197], v[90:93]
	v_mfma_f32_16x16x32_bf16 v[78:81], v[146:149], v[202:205], v[78:81]
	v_mfma_f32_16x16x32_bf16 v[74:77], v[154:157], v[202:205], v[74:77]
	s_setprio 0
	s_setprio 1
	v_mfma_f32_16x16x32_bf16 v[118:121], v[158:161], v[174:177], v[118:121]
	v_mfma_f32_16x16x32_bf16 v[114:117], v[166:169], v[174:177], v[114:117]
	v_mfma_f32_16x16x32_bf16 v[102:105], v[158:161], v[182:185], v[102:105]
	v_mfma_f32_16x16x32_bf16 v[98:101], v[166:169], v[182:185], v[98:101]
	v_mfma_f32_16x16x32_bf16 v[86:89], v[158:161], v[190:193], v[86:89]
	v_mfma_f32_16x16x32_bf16 v[82:85], v[166:169], v[190:193], v[82:85]
	v_mfma_f32_16x16x32_bf16 v[70:73], v[158:161], v[198:201], v[70:73]
	v_mfma_f32_16x16x32_bf16 v[66:69], v[166:169], v[198:201], v[66:69]
	v_mfma_f32_16x16x32_bf16 v[118:121], v[162:165], v[178:181], v[118:121]
	v_mfma_f32_16x16x32_bf16 v[114:117], v[170:173], v[178:181], v[114:117]
	v_mfma_f32_16x16x32_bf16 v[102:105], v[162:165], v[186:189], v[102:105]
	v_mfma_f32_16x16x32_bf16 v[98:101], v[170:173], v[186:189], v[98:101]
	v_mfma_f32_16x16x32_bf16 v[86:89], v[162:165], v[194:197], v[86:89]
	v_mfma_f32_16x16x32_bf16 v[82:85], v[170:173], v[194:197], v[82:85]
	v_mfma_f32_16x16x32_bf16 v[70:73], v[162:165], v[202:205], v[70:73]
	v_mfma_f32_16x16x32_bf16 v[66:69], v[170:173], v[202:205], v[66:69]
	s_barrier
	s_setprio 0
	s_add_i32 s28, s28, s51
	v_lshl_add_u64 v[206:207], s[4:5], 0, v[0:1]
	s_mov_b32 m0, s28
	ds_read_b128 v[174:177], v145 offset:16384
	ds_read_b128 v[178:181], v145 offset:17408
	ds_read_b128 v[182:185], v145 offset:18432
	ds_read_b128 v[186:189], v145 offset:19456
	ds_read_b128 v[190:193], v145 offset:20480
	ds_read_b128 v[194:197], v145 offset:21504
	ds_read_b128 v[198:201], v145 offset:22528
	ds_read_b128 v[202:205], v145 offset:23552
	global_load_lds_dwordx4 v[206:207], off
	s_add_i32 m0, s28, 0x2000
	s_add_u32 s28, s4, 0x80000
	v_lshl_add_u64 v[208:209], s[4:5], 0, v[130:131]
	s_addc_u32 s29, s5, 0
	s_add_i32 s31, s31, s51
	global_load_lds_dwordx4 v[208:209], off
	v_lshl_add_u64 v[210:211], s[28:29], 0, v[0:1]
	s_mov_b32 m0, s31
	v_lshl_add_u64 v[212:213], s[36:37], 0, v[130:131]
	global_load_lds_dwordx4 v[210:211], off
	v_lshl_add_u64 v[210:211], s[28:29], 0, v[130:131]
	s_add_i32 m0, s31, 0x2000
	s_nop 0
	global_load_lds_dwordx4 v[210:211], off
	v_lshl_add_u64 v[210:211], s[36:37], 0, v[0:1]
	s_mov_b32 m0, s52
	s_nop 0
	global_load_lds_dwordx4 v[210:211], off
	s_mov_b32 m0, s53
	s_nop 0
	global_load_lds_dwordx4 v[212:213], off
	s_waitcnt vmcnt(8)
	s_waitcnt lgkmcnt(0)
	s_barrier
; #define PG8_STAGE(bufoff, gbase, voff) do { _Pragma("unroll") for (int _i = 0; _i < 2; ++_i) \
;         __builtin_amdgcn_global_load_lds((const unsigned*)((const char*)(gbase) + (voff)[_i]), (LAS unsigned*)(lds + (bufoff) + ldsw + _i * 8192), 16, 0, 0); } while (0)
; #define PG8_LDA(dst, b, h) do { _Pragma("unroll") for (int m = 0; m < 4; ++m) _Pragma("unroll") for (int k = 0; k < 2; ++k) dst[m][k] = *(const LAS bf16x8*)(lds + PG8_SA(b, h) + aoff + m * 2048 + k * 1024); } while (0)
; #define PG8_LDB(dst, b, h) do { _Pragma("unroll") for (int n = 0; n < 2; ++n) _Pragma("unroll") for (int k = 0; k < 2; ++k) dst[n][k] = *(const LAS bf16x8*)(lds + PG8_SB(b, h) + boff + n * 2048 + k * 1024); } while (0)
; #define PG8_MMA(ai, bj, At, Bt) do { __builtin_amdgcn_s_setprio(1); _Pragma("unroll") for (int m = 0; m < 4; ++m) _Pragma("unroll") for (int n = 0; n < 2; ++n) _Pragma("unroll") for (int k = 0; k < 2; ++k) \
;         acc[ai][bj][m][n] = __builtin_amdgcn_mfma_f32_16x16x32_bf16(Bt[n][k], At[m][k], acc[ai][bj][m][n], 0, 0, 0); __builtin_amdgcn_s_setprio(0); } while (0)
; #define PG8_WAIT_V(n) asm volatile("s_waitcnt vmcnt(" #n ")" ::: "memory")
; #define PG8_WAIT_L(n) asm volatile("s_waitcnt lgkmcnt(" #n ")" ::: "memory")
; #define PG8_BAR __builtin_amdgcn_s_barrier()
; #define PG8_SCHED __builtin_amdgcn_sched_barrier(0)
; template <class Epi, class Sched, bool ALIGN_EPI, bool LAST_FUSED = false, bool PERM = false, bool CARRY = false>
; __device__ __forceinline__ void gemm_phase(LAS unsigned char* lds, const int tid, const int K, const int lda, const int ldb, const Sched& S, const Epi& E) {
;     ...
;             PG8_WAIT_V(8); PG8_WAIT_L(0); PG8_BAR; PG8_MMA(1, 0, At, B0); PG8_MMA(1, 1, At, B1); PG8_BAR; PG8_SCHED;
;             PG8_LDB(B0, 1, 0); PG8_LDB(B1, 1, 1); PG8_SCHED; PG8_LDA(At, 1, 0); PG8_STAGE(PG8_SA(0, 1), a2 + hstepA, voffA);
;             PG8_WAIT_V(8); PG8_WAIT_L(0); PG8_BAR; PG8_MMA(0, 0, At, B0); PG8_MMA(0, 1, At, B1); PG8_BAR; PG8_SCHED;
	v_mfma_f32_16x16x32_bf16 v[62:65], v[136:139], v[174:177], v[62:65]
	s_setprio 1
	v_mfma_f32_16x16x32_bf16 v[58:61], v[150:153], v[174:177], v[58:61]
	v_mfma_f32_16x16x32_bf16 v[46:49], v[136:139], v[182:185], v[46:49]
	v_mfma_f32_16x16x32_bf16 v[42:45], v[150:153], v[182:185], v[42:45]
	v_mfma_f32_16x16x32_bf16 v[30:33], v[136:139], v[190:193], v[30:33]
	v_mfma_f32_16x16x32_bf16 v[26:29], v[150:153], v[190:193], v[26:29]
	v_mfma_f32_16x16x32_bf16 v[14:17], v[136:139], v[198:201], v[14:17]
	v_mfma_f32_16x16x32_bf16 v[10:13], v[150:153], v[198:201], v[10:13]
	v_mfma_f32_16x16x32_bf16 v[62:65], v[146:149], v[178:181], v[62:65]
	v_mfma_f32_16x16x32_bf16 v[58:61], v[154:157], v[178:181], v[58:61]
	v_mfma_f32_16x16x32_bf16 v[46:49], v[146:149], v[186:189], v[46:49]
	v_mfma_f32_16x16x32_bf16 v[42:45], v[154:157], v[186:189], v[42:45]
	v_mfma_f32_16x16x32_bf16 v[30:33], v[146:149], v[194:197], v[30:33]
	v_mfma_f32_16x16x32_bf16 v[26:29], v[154:157], v[194:197], v[26:29]
	v_mfma_f32_16x16x32_bf16 v[14:17], v[146:149], v[202:205], v[14:17]
	v_mfma_f32_16x16x32_bf16 v[10:13], v[154:157], v[202:205], v[10:13]
	s_setprio 0
	s_setprio 1
	v_mfma_f32_16x16x32_bf16 v[54:57], v[158:161], v[174:177], v[54:57]
	v_mfma_f32_16x16x32_bf16 v[50:53], v[166:169], v[174:177], v[50:53]
	v_mfma_f32_16x16x32_bf16 v[38:41], v[158:161], v[182:185], v[38:41]
	v_mfma_f32_16x16x32_bf16 v[34:37], v[166:169], v[182:185], v[34:37]
	v_mfma_f32_16x16x32_bf16 v[22:25], v[158:161], v[190:193], v[22:25]
	v_mfma_f32_16x16x32_bf16 v[18:21], v[166:169], v[190:193], v[18:21]
	v_mfma_f32_16x16x32_bf16 v[6:9], v[158:161], v[198:201], v[6:9]
	v_mfma_f32_16x16x32_bf16 v[2:5], v[166:169], v[198:201], v[2:5]
	v_mfma_f32_16x16x32_bf16 v[54:57], v[162:165], v[178:181], v[54:57]
	v_mfma_f32_16x16x32_bf16 v[50:53], v[170:173], v[178:181], v[50:53]
	v_mfma_f32_16x16x32_bf16 v[38:41], v[162:165], v[186:189], v[38:41]
	v_mfma_f32_16x16x32_bf16 v[34:37], v[170:173], v[186:189], v[34:37]
	v_mfma_f32_16x16x32_bf16 v[22:25], v[162:165], v[194:197], v[22:25]
	v_mfma_f32_16x16x32_bf16 v[18:21], v[170:173], v[194:197], v[18:21]
	v_mfma_f32_16x16x32_bf16 v[6:9], v[162:165], v[202:205], v[6:9]
	v_mfma_f32_16x16x32_bf16 v[2:5], v[170:173], v[202:205], v[2:5]
	s_barrier
	s_setprio 0
	s_add_i32 s31, 0, 0x18000
	s_add_i32 s35, 0, 0x1c000
	v_add_u32_e32 v154, s31, v144
	v_add_u32_e32 v170, s35, v144
	ds_read_b128 v[136:139], v154
	ds_read_b128 v[146:149], v154 offset:1024
	ds_read_b128 v[150:153], v154 offset:2048
	ds_read_b128 v[154:157], v154 offset:3072
	ds_read_b128 v[158:161], v170
	ds_read_b128 v[162:165], v170 offset:1024
	ds_read_b128 v[166:169], v170 offset:2048
	ds_read_b128 v[170:173], v170 offset:3072
	s_add_u32 s28, s36, 0x80000
	s_addc_u32 s29, s37, 0
	s_mov_b32 m0, s54
	v_lshl_add_u64 v[214:215], s[28:29], 0, v[0:1]
	ds_read_b128 v[174:177], v145 offset:32768
	ds_read_b128 v[178:181], v145 offset:33792
	ds_read_b128 v[182:185], v145 offset:34816
	ds_read_b128 v[186:189], v145 offset:35840
	ds_read_b128 v[190:193], v145 offset:36864
	ds_read_b128 v[194:197], v145 offset:37888
	ds_read_b128 v[198:201], v145 offset:38912
	ds_read_b128 v[202:205], v145 offset:39936
	global_load_lds_dwordx4 v[214:215], off
	v_lshl_add_u64 v[214:215], s[28:29], 0, v[130:131]
	s_mov_b32 m0, s55
	s_nop 0
	global_load_lds_dwordx4 v[214:215], off
	s_waitcnt vmcnt(8)
	s_waitcnt lgkmcnt(0)
	s_barrier
	v_mfma_f32_16x16x32_bf16 v[126:129], v[136:139], v[174:177], v[126:129]
	s_setprio 1
	v_mfma_f32_16x16x32_bf16 v[122:125], v[150:153], v[174:177], v[122:125]
	v_mfma_f32_16x16x32_bf16 v[110:113], v[136:139], v[182:185], v[110:113]
	v_mfma_f32_16x16x32_bf16 v[106:109], v[150:153], v[182:185], v[106:109]
	v_mfma_f32_16x16x32_bf16 v[94:97], v[136:139], v[190:193], v[94:97]
	v_mfma_f32_16x16x32_bf16 v[90:93], v[150:153], v[190:193], v[90:93]
	v_mfma_f32_16x16x32_bf16 v[78:81], v[136:139], v[198:201], v[78:81]
	v_mfma_f32_16x16x32_bf16 v[74:77], v[150:153], v[198:201], v[74:77]
	v_mfma_f32_16x16x32_bf16 v[126:129], v[146:149], v[178:181], v[126:129]
	v_mfma_f32_16x16x32_bf16 v[122:125], v[154:157], v[178:181], v[122:125]
	v_mfma_f32_16x16x32_bf16 v[110:113], v[146:149], v[186:189], v[110:113]
	v_mfma_f32_16x16x32_bf16 v[106:109], v[154:157], v[186:189], v[106:109]
	v_mfma_f32_16x16x32_bf16 v[94:97], v[146:149], v[194:197], v[94:97]
	v_mfma_f32_16x16x32_bf16 v[90:93], v[154:157], v[194:197], v[90:93]
	v_mfma_f32_16x16x32_bf16 v[78:81], v[146:149], v[202:205], v[78:81]
	v_mfma_f32_16x16x32_bf16 v[74:77], v[154:157], v[202:205], v[74:77]
	s_setprio 0
	s_setprio 1
	v_mfma_f32_16x16x32_bf16 v[118:121], v[158:161], v[174:177], v[118:121]
	v_mfma_f32_16x16x32_bf16 v[114:117], v[166:169], v[174:177], v[114:117]
	v_mfma_f32_16x16x32_bf16 v[102:105], v[158:161], v[182:185], v[102:105]
	v_mfma_f32_16x16x32_bf16 v[98:101], v[166:169], v[182:185], v[98:101]
	v_mfma_f32_16x16x32_bf16 v[86:89], v[158:161], v[190:193], v[86:89]
	v_mfma_f32_16x16x32_bf16 v[82:85], v[166:169], v[190:193], v[82:85]
	v_mfma_f32_16x16x32_bf16 v[70:73], v[158:161], v[198:201], v[70:73]
	v_mfma_f32_16x16x32_bf16 v[66:69], v[166:169], v[198:201], v[66:69]
	v_mfma_f32_16x16x32_bf16 v[118:121], v[162:165], v[178:181], v[118:121]
	v_mfma_f32_16x16x32_bf16 v[114:117], v[170:173], v[178:181], v[114:117]
	v_mfma_f32_16x16x32_bf16 v[102:105], v[162:165], v[186:189], v[102:105]
	v_mfma_f32_16x16x32_bf16 v[98:101], v[170:173], v[186:189], v[98:101]
	v_mfma_f32_16x16x32_bf16 v[86:89], v[162:165], v[194:197], v[86:89]
	v_mfma_f32_16x16x32_bf16 v[82:85], v[170:173], v[194:197], v[82:85]
	v_mfma_f32_16x16x32_bf16 v[70:73], v[162:165], v[202:205], v[70:73]
	v_mfma_f32_16x16x32_bf16 v[66:69], v[170:173], v[202:205], v[66:69]
	s_barrier
; #define PG8_STAGE(bufoff, gbase, voff) do { _Pragma("unroll") for (int _i = 0; _i < 2; ++_i) \
;         __builtin_amdgcn_global_load_lds((const unsigned*)((const char*)(gbase) + (voff)[_i]), (LAS unsigned*)(lds + (bufoff) + ldsw + _i * 8192), 16, 0, 0); } while (0)
; #define PG8_LDA(dst, b, h) do { _Pragma("unroll") for (int m = 0; m < 4; ++m) _Pragma("unroll") for (int k = 0; k < 2; ++k) dst[m][k] = *(const LAS bf16x8*)(lds + PG8_SA(b, h) + aoff + m * 2048 + k * 1024); } while (0)
; #define PG8_MMA(ai, bj, At, Bt) do { __builtin_amdgcn_s_setprio(1); _Pragma("unroll") for (int m = 0; m < 4; ++m) _Pragma("unroll") for (int n = 0; n < 2; ++n) _Pragma("unroll") for (int k = 0; k < 2; ++k) \
;         acc[ai][bj][m][n] = __builtin_amdgcn_mfma_f32_16x16x32_bf16(Bt[n][k], At[m][k], acc[ai][bj][m][n], 0, 0, 0); __builtin_amdgcn_s_setprio(0); } while (0)
; #define PG8_WAIT_V(n) asm volatile("s_waitcnt vmcnt(" #n ")" ::: "memory")
; #define PG8_WAIT_L(n) asm volatile("s_waitcnt lgkmcnt(" #n ")" ::: "memory")
; #define PG8_BAR __builtin_amdgcn_s_barrier()
; #define PG8_SCHED __builtin_amdgcn_sched_barrier(0)
; template <class Epi, class Sched, bool ALIGN_EPI, bool LAST_FUSED = false, bool PERM = false, bool CARRY = false>
; __device__ __forceinline__ void gemm_phase(LAS unsigned char* lds, const int tid, const int K, const int lda, const int ldb, const Sched& S, const Epi& E) {
;     ...
;             PG8_LDA(At, 1, 1); PG8_STAGE(PG8_SB(1, 0), b3, voffB); PG8_STAGE(PG8_SB(1, 1), b3 + hstepB, voffB); PG8_STAGE(PG8_SA(1, 0), a3, voffA);
;             PG8_WAIT_V(8); PG8_WAIT_L(0); PG8_BAR; PG8_MMA(1, 0, At, B0); PG8_MMA(1, 1, At, B1); PG8_BAR; PG8_SCHED;
;         }
;         if constexpr (ALIGN_EPI) { if (wr == 0) PG8_BAR; }
	s_setprio 0
	s_add_i32 s28, s31, s51
	v_lshl_add_u64 v[206:207], v[206:207], 0, s[68:69]
	s_mov_b32 m0, s28
	ds_read_b128 v[174:177], v145 offset:49152
	ds_read_b128 v[178:181], v145 offset:50176
	ds_read_b128 v[182:185], v145 offset:51200
	ds_read_b128 v[186:189], v145 offset:52224
	ds_read_b128 v[190:193], v145 offset:53248
	ds_read_b128 v[194:197], v145 offset:54272
	ds_read_b128 v[198:201], v145 offset:55296
	ds_read_b128 v[202:205], v145 offset:56320
	global_load_lds_dwordx4 v[206:207], off
	s_add_i32 m0, s28, 0x2000
	s_add_u32 s4, s4, 0x80080
	v_lshl_add_u64 v[206:207], v[208:209], 0, s[68:69]
	s_addc_u32 s5, s5, 0
	s_add_i32 s28, s35, s51
	global_load_lds_dwordx4 v[206:207], off
	v_lshl_add_u64 v[206:207], s[4:5], 0, v[0:1]
	s_mov_b32 m0, s28
	s_nop 0
	global_load_lds_dwordx4 v[206:207], off
	v_lshl_add_u64 v[206:207], s[4:5], 0, v[130:131]
	s_add_i32 m0, s28, 0x2000
	s_nop 0
	global_load_lds_dwordx4 v[206:207], off
	v_lshl_add_u64 v[206:207], v[210:211], 0, s[68:69]
	s_mov_b32 m0, s57
	s_nop 0
	global_load_lds_dwordx4 v[206:207], off
	v_lshl_add_u64 v[206:207], v[212:213], 0, s[68:69]
	s_mov_b32 m0, s58
	s_nop 0
	global_load_lds_dwordx4 v[206:207], off
	s_waitcnt vmcnt(8)
	s_waitcnt lgkmcnt(0)
	s_barrier
	v_mfma_f32_16x16x32_bf16 v[62:65], v[136:139], v[174:177], v[62:65]
	s_setprio 1
	v_mfma_f32_16x16x32_bf16 v[58:61], v[150:153], v[174:177], v[58:61]
	v_mfma_f32_16x16x32_bf16 v[46:49], v[136:139], v[182:185], v[46:49]
	v_mfma_f32_16x16x32_bf16 v[42:45], v[150:153], v[182:185], v[42:45]
	v_mfma_f32_16x16x32_bf16 v[30:33], v[136:139], v[190:193], v[30:33]
	v_mfma_f32_16x16x32_bf16 v[26:29], v[150:153], v[190:193], v[26:29]
	v_mfma_f32_16x16x32_bf16 v[14:17], v[136:139], v[198:201], v[14:17]
	v_mfma_f32_16x16x32_bf16 v[10:13], v[150:153], v[198:201], v[10:13]
	v_mfma_f32_16x16x32_bf16 v[62:65], v[146:149], v[178:181], v[62:65]
	v_mfma_f32_16x16x32_bf16 v[58:61], v[154:157], v[178:181], v[58:61]
	v_mfma_f32_16x16x32_bf16 v[46:49], v[146:149], v[186:189], v[46:49]
	v_mfma_f32_16x16x32_bf16 v[42:45], v[154:157], v[186:189], v[42:45]
	v_mfma_f32_16x16x32_bf16 v[30:33], v[146:149], v[194:197], v[30:33]
	v_mfma_f32_16x16x32_bf16 v[26:29], v[154:157], v[194:197], v[26:29]
	v_mfma_f32_16x16x32_bf16 v[14:17], v[146:149], v[202:205], v[14:17]
	v_mfma_f32_16x16x32_bf16 v[10:13], v[154:157], v[202:205], v[10:13]
	s_setprio 0
	s_setprio 1
	v_mfma_f32_16x16x32_bf16 v[54:57], v[158:161], v[174:177], v[54:57]
	v_mfma_f32_16x16x32_bf16 v[50:53], v[166:169], v[174:177], v[50:53]
	v_mfma_f32_16x16x32_bf16 v[38:41], v[158:161], v[182:185], v[38:41]
	v_mfma_f32_16x16x32_bf16 v[34:37], v[166:169], v[182:185], v[34:37]
	v_mfma_f32_16x16x32_bf16 v[22:25], v[158:161], v[190:193], v[22:25]
	v_mfma_f32_16x16x32_bf16 v[18:21], v[166:169], v[190:193], v[18:21]
	v_mfma_f32_16x16x32_bf16 v[6:9], v[158:161], v[198:201], v[6:9]
	v_mfma_f32_16x16x32_bf16 v[2:5], v[166:169], v[198:201], v[2:5]
	v_mfma_f32_16x16x32_bf16 v[54:57], v[162:165], v[178:181], v[54:57]
	v_mfma_f32_16x16x32_bf16 v[50:53], v[170:173], v[178:181], v[50:53]
	v_mfma_f32_16x16x32_bf16 v[38:41], v[162:165], v[186:189], v[38:41]
	v_mfma_f32_16x16x32_bf16 v[34:37], v[170:173], v[186:189], v[34:37]
	v_mfma_f32_16x16x32_bf16 v[22:25], v[162:165], v[194:197], v[22:25]
	v_mfma_f32_16x16x32_bf16 v[18:21], v[170:173], v[194:197], v[18:21]
	v_mfma_f32_16x16x32_bf16 v[6:9], v[162:165], v[202:205], v[6:9]
	v_mfma_f32_16x16x32_bf16 v[2:5], v[170:173], v[202:205], v[2:5]
	s_barrier
	s_setprio 0
	s_add_i32 s27, s27, 2
	s_add_u32 s2, s2, 0x100
	s_addc_u32 s3, s3, 0
	s_add_u32 s22, s22, 0x100
	s_addc_u32 s23, s23, 0
	s_cmp_gt_u32 s27, 29
	s_cbranch_scc0 .LBB0_279
	s_and_b64 vcc, exec, s[18:19]
	s_cbranch_vccz .LBB0_282
	s_barrier

; #define PG8_STAGE(bufoff, gbase, voff) do { _Pragma("unroll") for (int _i = 0; _i < 2; ++_i) \
;         __builtin_amdgcn_global_load_lds((const unsigned*)((const char*)(gbase) + (voff)[_i]), (LAS unsigned*)(lds + (bufoff) + ldsw + _i * 8192), 16, 0, 0); } while (0)
; #define PG8_LDA(dst, b, h) do { _Pragma("unroll") for (int m = 0; m < 4; ++m) _Pragma("unroll") for (int k = 0; k < 2; ++k) dst[m][k] = *(const LAS bf16x8*)(lds + PG8_SA(b, h) + aoff + m * 2048 + k * 1024); } while (0)
; #define PG8_LDB(dst, b, h) do { _Pragma("unroll") for (int n = 0; n < 2; ++n) _Pragma("unroll") for (int k = 0; k < 2; ++k) dst[n][k] = *(const LAS bf16x8*)(lds + PG8_SB(b, h) + boff + n * 2048 + k * 1024); } while (0)
; #define PG8_MMA(ai, bj, At, Bt) do { __builtin_amdgcn_s_setprio(1); _Pragma("unroll") for (int m = 0; m < 4; ++m) _Pragma("unroll") for (int n = 0; n < 2; ++n) _Pragma("unroll") for (int k = 0; k < 2; ++k) \
;         acc[ai][bj][m][n] = __builtin_amdgcn_mfma_f32_16x16x32_bf16(Bt[n][k], At[m][k], acc[ai][bj][m][n], 0, 0, 0); __builtin_amdgcn_s_setprio(0); } while (0)
; #define PG8_WAIT_V(n) asm volatile("s_waitcnt vmcnt(" #n ")" ::: "memory")
; #define PG8_WAIT_L(n) asm volatile("s_waitcnt lgkmcnt(" #n ")" ::: "memory")
; template <class Epi, class Sched, bool ALIGN_EPI, bool LAST_FUSED = false, bool PERM = false, bool CARRY = false>
; __device__ __forceinline__ void gemm_phase(LAS unsigned char* lds, const int tid, const int K, const int lda, const int ldb, const Sched& S, const Epi& E) {
;     ...
;         for (int t = 0; t < nt; t += 2) {
;             const bool last = (t == nt - 2);
;             const char* a1 = cA + (size_t)(t + 1) * kstep;
;             const char* a2 = last ? nA : cA + (size_t)(t + 2) * kstep; const char* b2 = last ? nB : cB + (size_t)(t + 2) * kstep;
;             const char* a3 = a2 + kstep; const char* b3 = b2 + kstep;
;             PG8_LDB(B0, 0, 0); PG8_LDB(B1, 0, 1); PG8_SCHED; PG8_LDA(At, 0, 0); PG8_STAGE(PG8_SA(1, 1), a1 + hstepA, voffA);
;             PG8_WAIT_V(8); PG8_WAIT_L(0); PG8_BAR; PG8_MMA(0, 0, At, B0); PG8_MMA(0, 1, At, B1); PG8_BAR; PG8_SCHED;
;             PG8_LDA(At, 0, 1); PG8_STAGE(PG8_SB(0, 0), b2, voffB); PG8_STAGE(PG8_SB(0, 1), b2 + hstepB, voffB); PG8_STAGE(PG8_SA(0, 0), a2, voffA);
;             PG8_WAIT_V(8); PG8_WAIT_L(0); PG8_BAR; PG8_MMA(1, 0, At, B0); PG8_MMA(1, 1, At, B1); PG8_BAR; PG8_SCHED;
.LBB0_512:
	s_add_u32 s28, s4, 0xfff80080
	s_addc_u32 s29, s5, -1
	s_add_i32 s31, 0, 0x10000
	s_cmp_eq_u32 s24, 28
	s_cselect_b32 s41, s87, s29
	s_cselect_b32 s40, s86, s28
	v_add_u32_e32 v148, s31, v160
	s_cselect_b32 s37, s39, s23
	s_cselect_b32 s36, s38, s22
	s_add_i32 s35, 0, 0x14000
	ds_read_b128 v[140:143], v148
	ds_read_b128 v[144:147], v148 offset:1024
	ds_read_b128 v[162:165], v148 offset:2048
	ds_read_b128 v[166:169], v148 offset:3072
	v_add_u32_e32 v148, s35, v160
	ds_read_b128 v[170:173], v148
	ds_read_b128 v[174:177], v148 offset:1024
	ds_read_b128 v[178:181], v148 offset:2048
	ds_read_b128 v[182:185], v148 offset:3072
	v_lshl_add_u64 v[148:149], s[4:5], 0, v[136:137]
	s_add_i32 m0, s54, 0xc000
	ds_read_b128 v[186:189], v161
	ds_read_b128 v[190:193], v161 offset:1024
	ds_read_b128 v[194:197], v161 offset:2048
	ds_read_b128 v[198:201], v161 offset:3072
	ds_read_b128 v[202:205], v161 offset:4096
	ds_read_b128 v[206:209], v161 offset:5120
	ds_read_b128 v[210:213], v161 offset:6144
	ds_read_b128 v[214:217], v161 offset:7168
	global_load_lds_dwordx4 v[148:149], off
	v_lshl_add_u64 v[148:149], s[4:5], 0, v[138:139]
	s_add_i32 m0, s54, 0xe000
	s_nop 0
	global_load_lds_dwordx4 v[148:149], off
	s_waitcnt vmcnt(8)
	s_waitcnt lgkmcnt(0)
	s_barrier
	v_mfma_f32_16x16x32_bf16 v[126:129], v[140:143], v[186:189], v[126:129]
	s_setprio 1
	v_mfma_f32_16x16x32_bf16 v[122:125], v[162:165], v[186:189], v[122:125]
	v_mfma_f32_16x16x32_bf16 v[110:113], v[140:143], v[194:197], v[110:113]
	v_mfma_f32_16x16x32_bf16 v[106:109], v[162:165], v[194:197], v[106:109]
	v_mfma_f32_16x16x32_bf16 v[94:97], v[140:143], v[202:205], v[94:97]
	v_mfma_f32_16x16x32_bf16 v[90:93], v[162:165], v[202:205], v[90:93]
	v_mfma_f32_16x16x32_bf16 v[78:81], v[140:143], v[210:213], v[78:81]
	v_mfma_f32_16x16x32_bf16 v[74:77], v[162:165], v[210:213], v[74:77]
	v_mfma_f32_16x16x32_bf16 v[126:129], v[144:147], v[190:193], v[126:129]
	v_mfma_f32_16x16x32_bf16 v[122:125], v[166:169], v[190:193], v[122:125]
	v_mfma_f32_16x16x32_bf16 v[110:113], v[144:147], v[198:201], v[110:113]
	v_mfma_f32_16x16x32_bf16 v[106:109], v[166:169], v[198:201], v[106:109]
	v_mfma_f32_16x16x32_bf16 v[94:97], v[144:147], v[206:209], v[94:97]
	v_mfma_f32_16x16x32_bf16 v[90:93], v[166:169], v[206:209], v[90:93]
	v_mfma_f32_16x16x32_bf16 v[78:81], v[144:147], v[214:217], v[78:81]
	v_mfma_f32_16x16x32_bf16 v[74:77], v[166:169], v[214:217], v[74:77]
	s_setprio 0
	s_setprio 1
	v_mfma_f32_16x16x32_bf16 v[118:121], v[170:173], v[186:189], v[118:121]
	v_mfma_f32_16x16x32_bf16 v[114:117], v[178:181], v[186:189], v[114:117]
	v_mfma_f32_16x16x32_bf16 v[102:105], v[170:173], v[194:197], v[102:105]
	v_mfma_f32_16x16x32_bf16 v[98:101], v[178:181], v[194:197], v[98:101]
	v_mfma_f32_16x16x32_bf16 v[86:89], v[170:173], v[202:205], v[86:89]
	v_mfma_f32_16x16x32_bf16 v[82:85], v[178:181], v[202:205], v[82:85]
	v_mfma_f32_16x16x32_bf16 v[70:73], v[170:173], v[210:213], v[70:73]
	v_mfma_f32_16x16x32_bf16 v[66:69], v[178:181], v[210:213], v[66:69]
	v_mfma_f32_16x16x32_bf16 v[118:121], v[174:177], v[190:193], v[118:121]
	v_mfma_f32_16x16x32_bf16 v[114:117], v[182:185], v[190:193], v[114:117]
	v_mfma_f32_16x16x32_bf16 v[102:105], v[174:177], v[198:201], v[102:105]
	v_mfma_f32_16x16x32_bf16 v[98:101], v[182:185], v[198:201], v[98:101]
	v_mfma_f32_16x16x32_bf16 v[86:89], v[174:177], v[206:209], v[86:89]
	v_mfma_f32_16x16x32_bf16 v[82:85], v[182:185], v[206:209], v[82:85]
	v_mfma_f32_16x16x32_bf16 v[70:73], v[174:177], v[214:217], v[70:73]
	v_mfma_f32_16x16x32_bf16 v[66:69], v[182:185], v[214:217], v[66:69]
	s_barrier
	s_setprio 0
	s_add_i32 s28, s31, s52
	v_lshl_add_u64 v[148:149], s[36:37], 0, v[0:1]
	s_mov_b32 m0, s28
	ds_read_b128 v[186:189], v161 offset:16384
	ds_read_b128 v[190:193], v161 offset:17408
	ds_read_b128 v[194:197], v161 offset:18432
	ds_read_b128 v[198:201], v161 offset:19456
	ds_read_b128 v[202:205], v161 offset:20480
	ds_read_b128 v[206:209], v161 offset:21504
	ds_read_b128 v[210:213], v161 offset:22528
	ds_read_b128 v[214:217], v161 offset:23552
	global_load_lds_dwordx4 v[148:149], off
	s_add_i32 m0, s28, 0x2000
	s_add_u32 s28, s36, 0x80000
	v_lshl_add_u64 v[152:153], s[36:37], 0, v[130:131]
	s_addc_u32 s29, s37, 0
	s_add_i32 s31, s35, s52
	global_load_lds_dwordx4 v[152:153], off
	v_lshl_add_u64 v[156:157], s[28:29], 0, v[0:1]
	s_mov_b32 m0, s31
	v_lshl_add_u64 v[218:219], s[40:41], 0, v[132:133]
	global_load_lds_dwordx4 v[156:157], off
	v_lshl_add_u64 v[156:157], s[28:29], 0, v[130:131]
	s_add_i32 m0, s31, 0x2000
	s_nop 0
	global_load_lds_dwordx4 v[156:157], off
	v_lshl_add_u64 v[156:157], s[40:41], 0, v[134:135]
	s_mov_b32 m0, s54
	s_nop 0
	global_load_lds_dwordx4 v[156:157], off
	s_mov_b32 m0, s55
	s_nop 0
	global_load_lds_dwordx4 v[218:219], off
	s_waitcnt vmcnt(8)
	s_waitcnt lgkmcnt(0)
	s_barrier
; #define PG8_STAGE(bufoff, gbase, voff) do { _Pragma("unroll") for (int _i = 0; _i < 2; ++_i) \
;         __builtin_amdgcn_global_load_lds((const unsigned*)((const char*)(gbase) + (voff)[_i]), (LAS unsigned*)(lds + (bufoff) + ldsw + _i * 8192), 16, 0, 0); } while (0)
; #define PG8_LDA(dst, b, h) do { _Pragma("unroll") for (int m = 0; m < 4; ++m) _Pragma("unroll") for (int k = 0; k < 2; ++k) dst[m][k] = *(const LAS bf16x8*)(lds + PG8_SA(b, h) + aoff + m * 2048 + k * 1024); } while (0)
; #define PG8_LDB(dst, b, h) do { _Pragma("unroll") for (int n = 0; n < 2; ++n) _Pragma("unroll") for (int k = 0; k < 2; ++k) dst[n][k] = *(const LAS bf16x8*)(lds + PG8_SB(b, h) + boff + n * 2048 + k * 1024); } while (0)
; #define PG8_MMA(ai, bj, At, Bt) do { __builtin_amdgcn_s_setprio(1); _Pragma("unroll") for (int m = 0; m < 4; ++m) _Pragma("unroll") for (int n = 0; n < 2; ++n) _Pragma("unroll") for (int k = 0; k < 2; ++k) \
;         acc[ai][bj][m][n] = __builtin_amdgcn_mfma_f32_16x16x32_bf16(Bt[n][k], At[m][k], acc[ai][bj][m][n], 0, 0, 0); __builtin_amdgcn_s_setprio(0); } while (0)
; #define PG8_WAIT_V(n) asm volatile("s_waitcnt vmcnt(" #n ")" ::: "memory")
; #define PG8_WAIT_L(n) asm volatile("s_waitcnt lgkmcnt(" #n ")" ::: "memory")
; #define PG8_BAR __builtin_amdgcn_s_barrier()
; #define PG8_SCHED __builtin_amdgcn_sched_barrier(0)
; template <class Epi, class Sched, bool ALIGN_EPI, bool LAST_FUSED = false, bool PERM = false, bool CARRY = false>
; __device__ __forceinline__ void gemm_phase(LAS unsigned char* lds, const int tid, const int K, const int lda, const int ldb, const Sched& S, const Epi& E) {
;     ...
;             PG8_WAIT_V(8); PG8_WAIT_L(0); PG8_BAR; PG8_MMA(1, 0, At, B0); PG8_MMA(1, 1, At, B1); PG8_BAR; PG8_SCHED;
;             PG8_LDB(B0, 1, 0); PG8_LDB(B1, 1, 1); PG8_SCHED; PG8_LDA(At, 1, 0); PG8_STAGE(PG8_SA(0, 1), a2 + hstepA, voffA);
;             PG8_WAIT_V(8); PG8_WAIT_L(0); PG8_BAR; PG8_MMA(0, 0, At, B0); PG8_MMA(0, 1, At, B1); PG8_BAR; PG8_SCHED;
	v_mfma_f32_16x16x32_bf16 v[62:65], v[140:143], v[186:189], v[62:65]
	s_setprio 1
	v_mfma_f32_16x16x32_bf16 v[58:61], v[162:165], v[186:189], v[58:61]
	v_mfma_f32_16x16x32_bf16 v[46:49], v[140:143], v[194:197], v[46:49]
	v_mfma_f32_16x16x32_bf16 v[42:45], v[162:165], v[194:197], v[42:45]
	v_mfma_f32_16x16x32_bf16 v[30:33], v[140:143], v[202:205], v[30:33]
	v_mfma_f32_16x16x32_bf16 v[26:29], v[162:165], v[202:205], v[26:29]
	v_mfma_f32_16x16x32_bf16 v[14:17], v[140:143], v[210:213], v[14:17]
	v_mfma_f32_16x16x32_bf16 v[10:13], v[162:165], v[210:213], v[10:13]
	v_mfma_f32_16x16x32_bf16 v[62:65], v[144:147], v[190:193], v[62:65]
	v_mfma_f32_16x16x32_bf16 v[58:61], v[166:169], v[190:193], v[58:61]
	v_mfma_f32_16x16x32_bf16 v[46:49], v[144:147], v[198:201], v[46:49]
	v_mfma_f32_16x16x32_bf16 v[42:45], v[166:169], v[198:201], v[42:45]
	v_mfma_f32_16x16x32_bf16 v[30:33], v[144:147], v[206:209], v[30:33]
	v_mfma_f32_16x16x32_bf16 v[26:29], v[166:169], v[206:209], v[26:29]
	v_mfma_f32_16x16x32_bf16 v[14:17], v[144:147], v[214:217], v[14:17]
	v_mfma_f32_16x16x32_bf16 v[10:13], v[166:169], v[214:217], v[10:13]
	s_setprio 0
	s_setprio 1
	v_mfma_f32_16x16x32_bf16 v[54:57], v[170:173], v[186:189], v[54:57]
	v_mfma_f32_16x16x32_bf16 v[50:53], v[178:181], v[186:189], v[50:53]
	v_mfma_f32_16x16x32_bf16 v[38:41], v[170:173], v[194:197], v[38:41]
	v_mfma_f32_16x16x32_bf16 v[34:37], v[178:181], v[194:197], v[34:37]
	v_mfma_f32_16x16x32_bf16 v[22:25], v[170:173], v[202:205], v[22:25]
	v_mfma_f32_16x16x32_bf16 v[18:21], v[178:181], v[202:205], v[18:21]
	v_mfma_f32_16x16x32_bf16 v[6:9], v[170:173], v[210:213], v[6:9]
	v_mfma_f32_16x16x32_bf16 v[2:5], v[178:181], v[210:213], v[2:5]
	v_mfma_f32_16x16x32_bf16 v[54:57], v[174:177], v[190:193], v[54:57]
	v_mfma_f32_16x16x32_bf16 v[50:53], v[182:185], v[190:193], v[50:53]
	v_mfma_f32_16x16x32_bf16 v[38:41], v[174:177], v[198:201], v[38:41]
	v_mfma_f32_16x16x32_bf16 v[34:37], v[182:185], v[198:201], v[34:37]
	v_mfma_f32_16x16x32_bf16 v[22:25], v[174:177], v[206:209], v[22:25]
	v_mfma_f32_16x16x32_bf16 v[18:21], v[182:185], v[206:209], v[18:21]
	v_mfma_f32_16x16x32_bf16 v[6:9], v[174:177], v[214:217], v[6:9]
	v_mfma_f32_16x16x32_bf16 v[2:5], v[182:185], v[214:217], v[2:5]
	s_barrier
	s_setprio 0
	s_add_i32 s31, 0, 0x18000
	v_add_u32_e32 v150, s31, v160
	s_add_i32 s35, 0, 0x1c000
	ds_read_b128 v[140:143], v150
	ds_read_b128 v[144:147], v150 offset:1024
	ds_read_b128 v[162:165], v150 offset:2048
	ds_read_b128 v[166:169], v150 offset:3072
	v_add_u32_e32 v150, s35, v160
	ds_read_b128 v[170:173], v150
	ds_read_b128 v[174:177], v150 offset:1024
	ds_read_b128 v[178:181], v150 offset:2048
	ds_read_b128 v[182:185], v150 offset:3072
	s_add_u32 s28, s40, 0x80000
	s_addc_u32 s29, s41, 0
	s_mov_b32 m0, s56
	v_lshl_add_u64 v[220:221], s[28:29], 0, v[134:135]
	ds_read_b128 v[186:189], v161 offset:32768
	ds_read_b128 v[190:193], v161 offset:33792
	ds_read_b128 v[194:197], v161 offset:34816
	ds_read_b128 v[198:201], v161 offset:35840
	ds_read_b128 v[202:205], v161 offset:36864
	ds_read_b128 v[206:209], v161 offset:37888
	ds_read_b128 v[210:213], v161 offset:38912
	ds_read_b128 v[214:217], v161 offset:39936
	global_load_lds_dwordx4 v[220:221], off
	v_lshl_add_u64 v[220:221], s[28:29], 0, v[132:133]
	s_mov_b32 m0, s57
	s_nop 0
	global_load_lds_dwordx4 v[220:221], off
	s_waitcnt vmcnt(8)
	s_waitcnt lgkmcnt(0)
	s_barrier
	v_mfma_f32_16x16x32_bf16 v[126:129], v[140:143], v[186:189], v[126:129]
	s_setprio 1
	v_mfma_f32_16x16x32_bf16 v[122:125], v[162:165], v[186:189], v[122:125]
	v_mfma_f32_16x16x32_bf16 v[110:113], v[140:143], v[194:197], v[110:113]
	v_mfma_f32_16x16x32_bf16 v[106:109], v[162:165], v[194:197], v[106:109]
	v_mfma_f32_16x16x32_bf16 v[94:97], v[140:143], v[202:205], v[94:97]
	v_mfma_f32_16x16x32_bf16 v[90:93], v[162:165], v[202:205], v[90:93]
	v_mfma_f32_16x16x32_bf16 v[78:81], v[140:143], v[210:213], v[78:81]
	v_mfma_f32_16x16x32_bf16 v[74:77], v[162:165], v[210:213], v[74:77]
	v_mfma_f32_16x16x32_bf16 v[126:129], v[144:147], v[190:193], v[126:129]
	v_mfma_f32_16x16x32_bf16 v[122:125], v[166:169], v[190:193], v[122:125]
	v_mfma_f32_16x16x32_bf16 v[110:113], v[144:147], v[198:201], v[110:113]
	v_mfma_f32_16x16x32_bf16 v[106:109], v[166:169], v[198:201], v[106:109]
	v_mfma_f32_16x16x32_bf16 v[94:97], v[144:147], v[206:209], v[94:97]
	v_mfma_f32_16x16x32_bf16 v[90:93], v[166:169], v[206:209], v[90:93]
	v_mfma_f32_16x16x32_bf16 v[78:81], v[144:147], v[214:217], v[78:81]
	v_mfma_f32_16x16x32_bf16 v[74:77], v[166:169], v[214:217], v[74:77]
	s_setprio 0
	s_setprio 1
	v_mfma_f32_16x16x32_bf16 v[118:121], v[170:173], v[186:189], v[118:121]
	v_mfma_f32_16x16x32_bf16 v[114:117], v[178:181], v[186:189], v[114:117]
	v_mfma_f32_16x16x32_bf16 v[102:105], v[170:173], v[194:197], v[102:105]
	v_mfma_f32_16x16x32_bf16 v[98:101], v[178:181], v[194:197], v[98:101]
	v_mfma_f32_16x16x32_bf16 v[86:89], v[170:173], v[202:205], v[86:89]
	v_mfma_f32_16x16x32_bf16 v[82:85], v[178:181], v[202:205], v[82:85]
	v_mfma_f32_16x16x32_bf16 v[70:73], v[170:173], v[210:213], v[70:73]
	v_mfma_f32_16x16x32_bf16 v[66:69], v[178:181], v[210:213], v[66:69]
	v_mfma_f32_16x16x32_bf16 v[118:121], v[174:177], v[190:193], v[118:121]
	v_mfma_f32_16x16x32_bf16 v[114:117], v[182:185], v[190:193], v[114:117]
	v_mfma_f32_16x16x32_bf16 v[102:105], v[174:177], v[198:201], v[102:105]
	v_mfma_f32_16x16x32_bf16 v[98:101], v[182:185], v[198:201], v[98:101]
	v_mfma_f32_16x16x32_bf16 v[86:89], v[174:177], v[206:209], v[86:89]
	v_mfma_f32_16x16x32_bf16 v[82:85], v[182:185], v[206:209], v[82:85]
	v_mfma_f32_16x16x32_bf16 v[70:73], v[174:177], v[214:217], v[70:73]
	v_mfma_f32_16x16x32_bf16 v[66:69], v[182:185], v[214:217], v[66:69]
	s_barrier
; #define PG8_STAGE(bufoff, gbase, voff) do { _Pragma("unroll") for (int _i = 0; _i < 2; ++_i) \
;         __builtin_amdgcn_global_load_lds((const unsigned*)((const char*)(gbase) + (voff)[_i]), (LAS unsigned*)(lds + (bufoff) + ldsw + _i * 8192), 16, 0, 0); } while (0)
; #define PG8_LDA(dst, b, h) do { _Pragma("unroll") for (int m = 0; m < 4; ++m) _Pragma("unroll") for (int k = 0; k < 2; ++k) dst[m][k] = *(const LAS bf16x8*)(lds + PG8_SA(b, h) + aoff + m * 2048 + k * 1024); } while (0)
; #define PG8_MMA(ai, bj, At, Bt) do { __builtin_amdgcn_s_setprio(1); _Pragma("unroll") for (int m = 0; m < 4; ++m) _Pragma("unroll") for (int n = 0; n < 2; ++n) _Pragma("unroll") for (int k = 0; k < 2; ++k) \
;         acc[ai][bj][m][n] = __builtin_amdgcn_mfma_f32_16x16x32_bf16(Bt[n][k], At[m][k], acc[ai][bj][m][n], 0, 0, 0); __builtin_amdgcn_s_setprio(0); } while (0)
; #define PG8_WAIT_V(n) asm volatile("s_waitcnt vmcnt(" #n ")" ::: "memory")
; #define PG8_WAIT_L(n) asm volatile("s_waitcnt lgkmcnt(" #n ")" ::: "memory")
; #define PG8_BAR __builtin_amdgcn_s_barrier()
; #define PG8_SCHED __builtin_amdgcn_sched_barrier(0)
; template <class Epi, class Sched, bool ALIGN_EPI, bool LAST_FUSED = false, bool PERM = false, bool CARRY = false>
; __device__ __forceinline__ void gemm_phase(LAS unsigned char* lds, const int tid, const int K, const int lda, const int ldb, const Sched& S, const Epi& E) {
;     ...
;             PG8_LDA(At, 1, 1); PG8_STAGE(PG8_SB(1, 0), b3, voffB); PG8_STAGE(PG8_SB(1, 1), b3 + hstepB, voffB); PG8_STAGE(PG8_SA(1, 0), a3, voffA);
;             PG8_WAIT_V(8); PG8_WAIT_L(0); PG8_BAR; PG8_MMA(1, 0, At, B0); PG8_MMA(1, 1, At, B1); PG8_BAR; PG8_SCHED;
;         }
;         if constexpr (ALIGN_EPI) { if (wr == 0) PG8_BAR; }
	s_setprio 0
	s_add_i32 s28, s31, s52
	v_lshl_add_u64 v[148:149], v[148:149], 0, s[68:69]
	s_mov_b32 m0, s28
	ds_read_b128 v[186:189], v161 offset:49152
	ds_read_b128 v[190:193], v161 offset:50176
	ds_read_b128 v[194:197], v161 offset:51200
	ds_read_b128 v[198:201], v161 offset:52224
	ds_read_b128 v[202:205], v161 offset:53248
	ds_read_b128 v[206:209], v161 offset:54272
	ds_read_b128 v[210:213], v161 offset:55296
	ds_read_b128 v[214:217], v161 offset:56320
	global_load_lds_dwordx4 v[148:149], off
	s_add_i32 m0, s28, 0x2000
	s_add_u32 s28, s36, 0x80080
	v_lshl_add_u64 v[148:149], v[152:153], 0, s[68:69]
	s_addc_u32 s29, s37, 0
	s_add_i32 s31, s35, s52
	global_load_lds_dwordx4 v[148:149], off
	v_lshl_add_u64 v[148:149], s[28:29], 0, v[0:1]
	s_mov_b32 m0, s31
	s_nop 0
	global_load_lds_dwordx4 v[148:149], off
	v_lshl_add_u64 v[148:149], s[28:29], 0, v[130:131]
	s_add_i32 m0, s31, 0x2000
	s_nop 0
	global_load_lds_dwordx4 v[148:149], off
	v_lshl_add_u64 v[148:149], v[156:157], 0, s[68:69]
	s_mov_b32 m0, s59
	s_nop 0
	global_load_lds_dwordx4 v[148:149], off
	v_lshl_add_u64 v[148:149], v[218:219], 0, s[68:69]
	s_mov_b32 m0, s60
	s_nop 0
	global_load_lds_dwordx4 v[148:149], off
	s_waitcnt vmcnt(8)
	s_waitcnt lgkmcnt(0)
	s_barrier
	v_mfma_f32_16x16x32_bf16 v[62:65], v[140:143], v[186:189], v[62:65]
	s_setprio 1
	v_mfma_f32_16x16x32_bf16 v[58:61], v[162:165], v[186:189], v[58:61]
	v_mfma_f32_16x16x32_bf16 v[46:49], v[140:143], v[194:197], v[46:49]
	v_mfma_f32_16x16x32_bf16 v[42:45], v[162:165], v[194:197], v[42:45]
	v_mfma_f32_16x16x32_bf16 v[30:33], v[140:143], v[202:205], v[30:33]
	v_mfma_f32_16x16x32_bf16 v[26:29], v[162:165], v[202:205], v[26:29]
	v_mfma_f32_16x16x32_bf16 v[14:17], v[140:143], v[210:213], v[14:17]
	v_mfma_f32_16x16x32_bf16 v[10:13], v[162:165], v[210:213], v[10:13]
	v_mfma_f32_16x16x32_bf16 v[62:65], v[144:147], v[190:193], v[62:65]
	v_mfma_f32_16x16x32_bf16 v[58:61], v[166:169], v[190:193], v[58:61]
	v_mfma_f32_16x16x32_bf16 v[46:49], v[144:147], v[198:201], v[46:49]
	v_mfma_f32_16x16x32_bf16 v[42:45], v[166:169], v[198:201], v[42:45]
	v_mfma_f32_16x16x32_bf16 v[30:33], v[144:147], v[206:209], v[30:33]
	v_mfma_f32_16x16x32_bf16 v[26:29], v[166:169], v[206:209], v[26:29]
	v_mfma_f32_16x16x32_bf16 v[14:17], v[144:147], v[214:217], v[14:17]
	v_mfma_f32_16x16x32_bf16 v[10:13], v[166:169], v[214:217], v[10:13]
	s_setprio 0
	s_setprio 1
	v_mfma_f32_16x16x32_bf16 v[54:57], v[170:173], v[186:189], v[54:57]
	v_mfma_f32_16x16x32_bf16 v[50:53], v[178:181], v[186:189], v[50:53]
	v_mfma_f32_16x16x32_bf16 v[38:41], v[170:173], v[194:197], v[38:41]
	v_mfma_f32_16x16x32_bf16 v[34:37], v[178:181], v[194:197], v[34:37]
	v_mfma_f32_16x16x32_bf16 v[22:25], v[170:173], v[202:205], v[22:25]
	v_mfma_f32_16x16x32_bf16 v[18:21], v[178:181], v[202:205], v[18:21]
	v_mfma_f32_16x16x32_bf16 v[6:9], v[170:173], v[210:213], v[6:9]
	v_mfma_f32_16x16x32_bf16 v[2:5], v[178:181], v[210:213], v[2:5]
	v_mfma_f32_16x16x32_bf16 v[54:57], v[174:177], v[190:193], v[54:57]
	v_mfma_f32_16x16x32_bf16 v[50:53], v[182:185], v[190:193], v[50:53]
	v_mfma_f32_16x16x32_bf16 v[38:41], v[174:177], v[198:201], v[38:41]
	v_mfma_f32_16x16x32_bf16 v[34:37], v[182:185], v[198:201], v[34:37]
	v_mfma_f32_16x16x32_bf16 v[22:25], v[174:177], v[206:209], v[22:25]
	v_mfma_f32_16x16x32_bf16 v[18:21], v[182:185], v[206:209], v[18:21]
	v_mfma_f32_16x16x32_bf16 v[6:9], v[174:177], v[214:217], v[6:9]
	v_mfma_f32_16x16x32_bf16 v[2:5], v[182:185], v[214:217], v[2:5]
	s_barrier
	s_setprio 0
	s_add_i32 s24, s24, 2
	s_add_u32 s4, s4, 0x100
	s_addc_u32 s5, s5, 0
	s_add_u32 s22, s22, 0x100
	s_addc_u32 s23, s23, 0
	s_cmp_gt_u32 s24, 29
	s_cbranch_scc0 .LBB0_512
	s_and_b64 vcc, exec, s[78:79]
	s_cbranch_vccz .LBB0_515
	s_barrier

; #define PG8_STAGE(bufoff, gbase, voff) do { _Pragma("unroll") for (int _i = 0; _i < 2; ++_i) \
;         __builtin_amdgcn_global_load_lds((const unsigned*)((const char*)(gbase) + (voff)[_i]), (LAS unsigned*)(lds + (bufoff) + ldsw + _i * 8192), 16, 0, 0); } while (0)
; #define PG8_LDA(dst, b, h) do { _Pragma("unroll") for (int m = 0; m < 4; ++m) _Pragma("unroll") for (int k = 0; k < 2; ++k) dst[m][k] = *(const LAS bf16x8*)(lds + PG8_SA(b, h) + aoff + m * 2048 + k * 1024); } while (0)
; #define PG8_LDB(dst, b, h) do { _Pragma("unroll") for (int n = 0; n < 2; ++n) _Pragma("unroll") for (int k = 0; k < 2; ++k) dst[n][k] = *(const LAS bf16x8*)(lds + PG8_SB(b, h) + boff + n * 2048 + k * 1024); } while (0)
; #define PG8_MMA(ai, bj, At, Bt) do { __builtin_amdgcn_s_setprio(1); _Pragma("unroll") for (int m = 0; m < 4; ++m) _Pragma("unroll") for (int n = 0; n < 2; ++n) _Pragma("unroll") for (int k = 0; k < 2; ++k) \
;         acc[ai][bj][m][n] = __builtin_amdgcn_mfma_f32_16x16x32_bf16(Bt[n][k], At[m][k], acc[ai][bj][m][n], 0, 0, 0); __builtin_amdgcn_s_setprio(0); } while (0)
; #define PG8_WAIT_V(n) asm volatile("s_waitcnt vmcnt(" #n ")" ::: "memory")
; #define PG8_WAIT_L(n) asm volatile("s_waitcnt lgkmcnt(" #n ")" ::: "memory")
; template <class Epi, class Sched, bool ALIGN_EPI, bool LAST_FUSED = false, bool PERM = false, bool CARRY = false>
; __device__ __forceinline__ void gemm_phase(LAS unsigned char* lds, const int tid, const int K, const int lda, const int ldb, const Sched& S, const Epi& E) {
;     ...
;         for (int t = 0; t < nt; t += 2) {
;             const bool last = (t == nt - 2);
;             const char* a1 = cA + (size_t)(t + 1) * kstep;
;             const char* a2 = last ? nA : cA + (size_t)(t + 2) * kstep; const char* b2 = last ? nB : cB + (size_t)(t + 2) * kstep;
;             const char* a3 = a2 + kstep; const char* b3 = b2 + kstep;
;             PG8_LDB(B0, 0, 0); PG8_LDB(B1, 0, 1); PG8_SCHED; PG8_LDA(At, 0, 0); PG8_STAGE(PG8_SA(1, 1), a1 + hstepA, voffA);
;             PG8_WAIT_V(8); PG8_WAIT_L(0); PG8_BAR; PG8_MMA(0, 0, At, B0); PG8_MMA(0, 1, At, B1); PG8_BAR; PG8_SCHED;
;             PG8_LDA(At, 0, 1); PG8_STAGE(PG8_SB(0, 0), b2, voffB); PG8_STAGE(PG8_SB(0, 1), b2 + hstepB, voffB); PG8_STAGE(PG8_SA(0, 0), a2, voffA);
;             PG8_WAIT_V(8); PG8_WAIT_L(0); PG8_BAR; PG8_MMA(1, 0, At, B0); PG8_MMA(1, 1, At, B1); PG8_BAR; PG8_SCHED;
.LBB0_601:
	s_add_u32 s23, s30, s15
	s_addc_u32 s27, s31, 0
	s_add_u32 s35, s23, 0x100
	s_addc_u32 s42, s27, 0
	s_and_b64 s[28:29], s[40:41], exec
	s_cselect_b32 s47, s17, s42
	s_cselect_b32 s46, s16, s35
	s_add_u32 s15, s36, s15
	s_addc_u32 s28, s37, 0
	s_add_u32 s15, s15, 0x100
	s_addc_u32 s35, s28, 0
	s_add_i32 s75, 0, 0x10000
	s_and_b64 s[28:29], s[40:41], exec
	s_cselect_b32 s49, s19, s35
	s_cselect_b32 s48, s18, s15
	s_add_i32 s41, 0, 0x14000
	s_add_u32 s52, s23, 0x80080
	s_addc_u32 s53, s27, 0
	s_add_i32 s45, s75, s59
	s_add_i32 m0, s60, 0xc000
	s_add_i32 s77, s60, 0xe000
	s_add_i32 s29, s45, 0x2000
	s_add_u32 s50, s48, 0x80000
	v_add_u32_e32 v154, s75, v144
	v_add_u32_e32 v170, s41, v144
	s_addc_u32 s51, s49, 0
	s_add_i32 s44, s41, s59
	ds_read_b128 v[136:139], v154
	ds_read_b128 v[146:149], v154 offset:1024
	ds_read_b128 v[150:153], v154 offset:2048
	ds_read_b128 v[154:157], v154 offset:3072
	ds_read_b128 v[158:161], v170
	ds_read_b128 v[162:165], v170 offset:1024
	ds_read_b128 v[166:169], v170 offset:2048
	ds_read_b128 v[170:173], v170 offset:3072
	s_add_i32 s35, s44, 0x2000
	s_add_i32 s28, 0, 0x18000
	s_add_i32 s27, 0, 0x1c000
	s_add_u32 s42, s46, 0x80000
	s_addc_u32 s43, s47, 0
	s_add_i32 s23, s28, s59
	s_add_i32 s15, s23, 0x2000
	s_add_u32 s40, s48, 0x80080
	s_addc_u32 s41, s49, 0
	s_add_i32 s76, s27, s59
	s_add_i32 s75, s76, 0x2000
	v_lshl_add_u64 v[206:207], s[52:53], 0, v[134:135]
	ds_read_b128 v[174:177], v145
	ds_read_b128 v[178:181], v145 offset:1024
	ds_read_b128 v[182:185], v145 offset:2048
	ds_read_b128 v[186:189], v145 offset:3072
	ds_read_b128 v[190:193], v145 offset:4096
	ds_read_b128 v[194:197], v145 offset:5120
	ds_read_b128 v[198:201], v145 offset:6144
	ds_read_b128 v[202:205], v145 offset:7168
	global_load_lds_dwordx4 v[206:207], off
	v_lshl_add_u64 v[206:207], s[52:53], 0, v[132:133]
	s_mov_b32 m0, s77
	s_nop 0
	global_load_lds_dwordx4 v[206:207], off
	s_waitcnt vmcnt(8)
	s_waitcnt lgkmcnt(0)
	s_barrier
	v_mfma_f32_16x16x32_bf16 v[126:129], v[136:139], v[174:177], v[126:129]
	s_setprio 1
	v_mfma_f32_16x16x32_bf16 v[122:125], v[150:153], v[174:177], v[122:125]
	v_mfma_f32_16x16x32_bf16 v[110:113], v[136:139], v[182:185], v[110:113]
	v_mfma_f32_16x16x32_bf16 v[106:109], v[150:153], v[182:185], v[106:109]
	v_mfma_f32_16x16x32_bf16 v[94:97], v[136:139], v[190:193], v[94:97]
	v_mfma_f32_16x16x32_bf16 v[90:93], v[150:153], v[190:193], v[90:93]
	v_mfma_f32_16x16x32_bf16 v[78:81], v[136:139], v[198:201], v[78:81]
	v_mfma_f32_16x16x32_bf16 v[74:77], v[150:153], v[198:201], v[74:77]
	v_mfma_f32_16x16x32_bf16 v[126:129], v[146:149], v[178:181], v[126:129]
	v_mfma_f32_16x16x32_bf16 v[122:125], v[154:157], v[178:181], v[122:125]
	v_mfma_f32_16x16x32_bf16 v[110:113], v[146:149], v[186:189], v[110:113]
	v_mfma_f32_16x16x32_bf16 v[106:109], v[154:157], v[186:189], v[106:109]
	v_mfma_f32_16x16x32_bf16 v[94:97], v[146:149], v[194:197], v[94:97]
	v_mfma_f32_16x16x32_bf16 v[90:93], v[154:157], v[194:197], v[90:93]
	v_mfma_f32_16x16x32_bf16 v[78:81], v[146:149], v[202:205], v[78:81]
	v_mfma_f32_16x16x32_bf16 v[74:77], v[154:157], v[202:205], v[74:77]
	s_setprio 0
	s_setprio 1
	v_mfma_f32_16x16x32_bf16 v[118:121], v[158:161], v[174:177], v[118:121]
	v_mfma_f32_16x16x32_bf16 v[114:117], v[166:169], v[174:177], v[114:117]
	v_mfma_f32_16x16x32_bf16 v[102:105], v[158:161], v[182:185], v[102:105]
	v_mfma_f32_16x16x32_bf16 v[98:101], v[166:169], v[182:185], v[98:101]
	v_mfma_f32_16x16x32_bf16 v[86:89], v[158:161], v[190:193], v[86:89]
	v_mfma_f32_16x16x32_bf16 v[82:85], v[166:169], v[190:193], v[82:85]
	v_mfma_f32_16x16x32_bf16 v[70:73], v[158:161], v[198:201], v[70:73]
	v_mfma_f32_16x16x32_bf16 v[66:69], v[166:169], v[198:201], v[66:69]
	v_mfma_f32_16x16x32_bf16 v[118:121], v[162:165], v[178:181], v[118:121]
	v_mfma_f32_16x16x32_bf16 v[114:117], v[170:173], v[178:181], v[114:117]
	v_mfma_f32_16x16x32_bf16 v[102:105], v[162:165], v[186:189], v[102:105]
	v_mfma_f32_16x16x32_bf16 v[98:101], v[170:173], v[186:189], v[98:101]
	v_mfma_f32_16x16x32_bf16 v[86:89], v[162:165], v[194:197], v[86:89]
	v_mfma_f32_16x16x32_bf16 v[82:85], v[170:173], v[194:197], v[82:85]
	v_mfma_f32_16x16x32_bf16 v[70:73], v[162:165], v[202:205], v[70:73]
	v_mfma_f32_16x16x32_bf16 v[66:69], v[170:173], v[202:205], v[66:69]
	s_barrier
	s_setprio 0
	s_mov_b32 m0, s45
	v_lshl_add_u64 v[206:207], s[48:49], 0, v[0:1]
	ds_read_b128 v[174:177], v145 offset:16384
	ds_read_b128 v[178:181], v145 offset:17408
	ds_read_b128 v[182:185], v145 offset:18432
	ds_read_b128 v[186:189], v145 offset:19456
	ds_read_b128 v[190:193], v145 offset:20480
	ds_read_b128 v[194:197], v145 offset:21504
	ds_read_b128 v[198:201], v145 offset:22528
	ds_read_b128 v[202:205], v145 offset:23552
	global_load_lds_dwordx4 v[206:207], off
	v_lshl_add_u64 v[208:209], s[48:49], 0, v[130:131]
	s_mov_b32 m0, s29
	v_lshl_add_u64 v[210:211], s[50:51], 0, v[0:1]
	global_load_lds_dwordx4 v[208:209], off
	s_mov_b32 m0, s44
	v_lshl_add_u64 v[212:213], s[46:47], 0, v[132:133]
	global_load_lds_dwordx4 v[210:211], off
	v_lshl_add_u64 v[210:211], s[50:51], 0, v[130:131]
	s_mov_b32 m0, s35
	s_nop 0
	global_load_lds_dwordx4 v[210:211], off
	v_lshl_add_u64 v[210:211], s[46:47], 0, v[134:135]
	s_mov_b32 m0, s60
	s_nop 0
	global_load_lds_dwordx4 v[210:211], off
	s_mov_b32 m0, s61
	s_nop 0
	global_load_lds_dwordx4 v[212:213], off
	s_waitcnt vmcnt(8)
	s_waitcnt lgkmcnt(0)
	s_barrier
; #define PG8_STAGE(bufoff, gbase, voff) do { _Pragma("unroll") for (int _i = 0; _i < 2; ++_i) \
;         __builtin_amdgcn_global_load_lds((const unsigned*)((const char*)(gbase) + (voff)[_i]), (LAS unsigned*)(lds + (bufoff) + ldsw + _i * 8192), 16, 0, 0); } while (0)
; #define PG8_LDA(dst, b, h) do { _Pragma("unroll") for (int m = 0; m < 4; ++m) _Pragma("unroll") for (int k = 0; k < 2; ++k) dst[m][k] = *(const LAS bf16x8*)(lds + PG8_SA(b, h) + aoff + m * 2048 + k * 1024); } while (0)
; #define PG8_LDB(dst, b, h) do { _Pragma("unroll") for (int n = 0; n < 2; ++n) _Pragma("unroll") for (int k = 0; k < 2; ++k) dst[n][k] = *(const LAS bf16x8*)(lds + PG8_SB(b, h) + boff + n * 2048 + k * 1024); } while (0)
; #define PG8_MMA(ai, bj, At, Bt) do { __builtin_amdgcn_s_setprio(1); _Pragma("unroll") for (int m = 0; m < 4; ++m) _Pragma("unroll") for (int n = 0; n < 2; ++n) _Pragma("unroll") for (int k = 0; k < 2; ++k) \
;         acc[ai][bj][m][n] = __builtin_amdgcn_mfma_f32_16x16x32_bf16(Bt[n][k], At[m][k], acc[ai][bj][m][n], 0, 0, 0); __builtin_amdgcn_s_setprio(0); } while (0)
; #define PG8_WAIT_V(n) asm volatile("s_waitcnt vmcnt(" #n ")" ::: "memory")
; #define PG8_WAIT_L(n) asm volatile("s_waitcnt lgkmcnt(" #n ")" ::: "memory")
; #define PG8_BAR __builtin_amdgcn_s_barrier()
; #define PG8_SCHED __builtin_amdgcn_sched_barrier(0)
; template <class Epi, class Sched, bool ALIGN_EPI, bool LAST_FUSED = false, bool PERM = false, bool CARRY = false>
; __device__ __forceinline__ void gemm_phase(LAS unsigned char* lds, const int tid, const int K, const int lda, const int ldb, const Sched& S, const Epi& E) {
;     ...
;             PG8_WAIT_V(8); PG8_WAIT_L(0); PG8_BAR; PG8_MMA(1, 0, At, B0); PG8_MMA(1, 1, At, B1); PG8_BAR; PG8_SCHED;
;             PG8_LDB(B0, 1, 0); PG8_LDB(B1, 1, 1); PG8_SCHED; PG8_LDA(At, 1, 0); PG8_STAGE(PG8_SA(0, 1), a2 + hstepA, voffA);
;             PG8_WAIT_V(8); PG8_WAIT_L(0); PG8_BAR; PG8_MMA(0, 0, At, B0); PG8_MMA(0, 1, At, B1); PG8_BAR; PG8_SCHED;
	v_mfma_f32_16x16x32_bf16 v[62:65], v[136:139], v[174:177], v[62:65]
	s_setprio 1
	v_mfma_f32_16x16x32_bf16 v[58:61], v[150:153], v[174:177], v[58:61]
	v_mfma_f32_16x16x32_bf16 v[46:49], v[136:139], v[182:185], v[46:49]
	v_mfma_f32_16x16x32_bf16 v[42:45], v[150:153], v[182:185], v[42:45]
	v_mfma_f32_16x16x32_bf16 v[30:33], v[136:139], v[190:193], v[30:33]
	v_mfma_f32_16x16x32_bf16 v[26:29], v[150:153], v[190:193], v[26:29]
	v_mfma_f32_16x16x32_bf16 v[14:17], v[136:139], v[198:201], v[14:17]
	v_mfma_f32_16x16x32_bf16 v[10:13], v[150:153], v[198:201], v[10:13]
	v_mfma_f32_16x16x32_bf16 v[62:65], v[146:149], v[178:181], v[62:65]
	v_mfma_f32_16x16x32_bf16 v[58:61], v[154:157], v[178:181], v[58:61]
	v_mfma_f32_16x16x32_bf16 v[46:49], v[146:149], v[186:189], v[46:49]
	v_mfma_f32_16x16x32_bf16 v[42:45], v[154:157], v[186:189], v[42:45]
	v_mfma_f32_16x16x32_bf16 v[30:33], v[146:149], v[194:197], v[30:33]
	v_mfma_f32_16x16x32_bf16 v[26:29], v[154:157], v[194:197], v[26:29]
	v_mfma_f32_16x16x32_bf16 v[14:17], v[146:149], v[202:205], v[14:17]
	v_mfma_f32_16x16x32_bf16 v[10:13], v[154:157], v[202:205], v[10:13]
	s_setprio 0
	s_setprio 1
	v_mfma_f32_16x16x32_bf16 v[54:57], v[158:161], v[174:177], v[54:57]
	v_mfma_f32_16x16x32_bf16 v[50:53], v[166:169], v[174:177], v[50:53]
	v_mfma_f32_16x16x32_bf16 v[38:41], v[158:161], v[182:185], v[38:41]
	v_mfma_f32_16x16x32_bf16 v[34:37], v[166:169], v[182:185], v[34:37]
	v_mfma_f32_16x16x32_bf16 v[22:25], v[158:161], v[190:193], v[22:25]
	v_mfma_f32_16x16x32_bf16 v[18:21], v[166:169], v[190:193], v[18:21]
	v_mfma_f32_16x16x32_bf16 v[6:9], v[158:161], v[198:201], v[6:9]
	v_mfma_f32_16x16x32_bf16 v[2:5], v[166:169], v[198:201], v[2:5]
	v_mfma_f32_16x16x32_bf16 v[54:57], v[162:165], v[178:181], v[54:57]
	v_mfma_f32_16x16x32_bf16 v[50:53], v[170:173], v[178:181], v[50:53]
	v_mfma_f32_16x16x32_bf16 v[38:41], v[162:165], v[186:189], v[38:41]
	v_mfma_f32_16x16x32_bf16 v[34:37], v[170:173], v[186:189], v[34:37]
	v_mfma_f32_16x16x32_bf16 v[22:25], v[162:165], v[194:197], v[22:25]
	v_mfma_f32_16x16x32_bf16 v[18:21], v[170:173], v[194:197], v[18:21]
	v_mfma_f32_16x16x32_bf16 v[6:9], v[162:165], v[202:205], v[6:9]
	v_mfma_f32_16x16x32_bf16 v[2:5], v[170:173], v[202:205], v[2:5]
	s_barrier
	s_setprio 0
	v_add_u32_e32 v154, s28, v144
	v_add_u32_e32 v170, s27, v144
	ds_read_b128 v[136:139], v154
	ds_read_b128 v[146:149], v154 offset:1024
	ds_read_b128 v[150:153], v154 offset:2048
	ds_read_b128 v[154:157], v154 offset:3072
	ds_read_b128 v[158:161], v170
	ds_read_b128 v[162:165], v170 offset:1024
	ds_read_b128 v[166:169], v170 offset:2048
	ds_read_b128 v[170:173], v170 offset:3072
	s_mov_b32 m0, s62
	v_lshl_add_u64 v[214:215], s[42:43], 0, v[134:135]
	ds_read_b128 v[174:177], v145 offset:32768
	ds_read_b128 v[178:181], v145 offset:33792
	ds_read_b128 v[182:185], v145 offset:34816
	ds_read_b128 v[186:189], v145 offset:35840
	ds_read_b128 v[190:193], v145 offset:36864
	ds_read_b128 v[194:197], v145 offset:37888
	ds_read_b128 v[198:201], v145 offset:38912
	ds_read_b128 v[202:205], v145 offset:39936
	global_load_lds_dwordx4 v[214:215], off
	v_lshl_add_u64 v[214:215], s[42:43], 0, v[132:133]
	s_mov_b32 m0, s63
	s_nop 0
	global_load_lds_dwordx4 v[214:215], off
	s_waitcnt vmcnt(8)
	s_waitcnt lgkmcnt(0)
	s_barrier
	v_mfma_f32_16x16x32_bf16 v[126:129], v[136:139], v[174:177], v[126:129]
	s_setprio 1
	v_mfma_f32_16x16x32_bf16 v[122:125], v[150:153], v[174:177], v[122:125]
	v_mfma_f32_16x16x32_bf16 v[110:113], v[136:139], v[182:185], v[110:113]
	v_mfma_f32_16x16x32_bf16 v[106:109], v[150:153], v[182:185], v[106:109]
	v_mfma_f32_16x16x32_bf16 v[94:97], v[136:139], v[190:193], v[94:97]
	v_mfma_f32_16x16x32_bf16 v[90:93], v[150:153], v[190:193], v[90:93]
	v_mfma_f32_16x16x32_bf16 v[78:81], v[136:139], v[198:201], v[78:81]
	v_mfma_f32_16x16x32_bf16 v[74:77], v[150:153], v[198:201], v[74:77]
	v_mfma_f32_16x16x32_bf16 v[126:129], v[146:149], v[178:181], v[126:129]
	v_mfma_f32_16x16x32_bf16 v[122:125], v[154:157], v[178:181], v[122:125]
	v_mfma_f32_16x16x32_bf16 v[110:113], v[146:149], v[186:189], v[110:113]
	v_mfma_f32_16x16x32_bf16 v[106:109], v[154:157], v[186:189], v[106:109]
	v_mfma_f32_16x16x32_bf16 v[94:97], v[146:149], v[194:197], v[94:97]
	v_mfma_f32_16x16x32_bf16 v[90:93], v[154:157], v[194:197], v[90:93]
	v_mfma_f32_16x16x32_bf16 v[78:81], v[146:149], v[202:205], v[78:81]
	v_mfma_f32_16x16x32_bf16 v[74:77], v[154:157], v[202:205], v[74:77]
	s_setprio 0
	s_setprio 1
	v_mfma_f32_16x16x32_bf16 v[118:121], v[158:161], v[174:177], v[118:121]
	v_mfma_f32_16x16x32_bf16 v[114:117], v[166:169], v[174:177], v[114:117]
	v_mfma_f32_16x16x32_bf16 v[102:105], v[158:161], v[182:185], v[102:105]
	v_mfma_f32_16x16x32_bf16 v[98:101], v[166:169], v[182:185], v[98:101]
	v_mfma_f32_16x16x32_bf16 v[86:89], v[158:161], v[190:193], v[86:89]
	v_mfma_f32_16x16x32_bf16 v[82:85], v[166:169], v[190:193], v[82:85]
	v_mfma_f32_16x16x32_bf16 v[70:73], v[158:161], v[198:201], v[70:73]
	v_mfma_f32_16x16x32_bf16 v[66:69], v[166:169], v[198:201], v[66:69]
	v_mfma_f32_16x16x32_bf16 v[118:121], v[162:165], v[178:181], v[118:121]
	v_mfma_f32_16x16x32_bf16 v[114:117], v[170:173], v[178:181], v[114:117]
	v_mfma_f32_16x16x32_bf16 v[102:105], v[162:165], v[186:189], v[102:105]
	v_mfma_f32_16x16x32_bf16 v[98:101], v[170:173], v[186:189], v[98:101]
	v_mfma_f32_16x16x32_bf16 v[86:89], v[162:165], v[194:197], v[86:89]
	v_mfma_f32_16x16x32_bf16 v[82:85], v[170:173], v[194:197], v[82:85]
	v_mfma_f32_16x16x32_bf16 v[70:73], v[162:165], v[202:205], v[70:73]
	v_mfma_f32_16x16x32_bf16 v[66:69], v[170:173], v[202:205], v[66:69]
	s_barrier
; #define PG8_STAGE(bufoff, gbase, voff) do { _Pragma("unroll") for (int _i = 0; _i < 2; ++_i) \
;         __builtin_amdgcn_global_load_lds((const unsigned*)((const char*)(gbase) + (voff)[_i]), (LAS unsigned*)(lds + (bufoff) + ldsw + _i * 8192), 16, 0, 0); } while (0)
; #define PG8_LDA(dst, b, h) do { _Pragma("unroll") for (int m = 0; m < 4; ++m) _Pragma("unroll") for (int k = 0; k < 2; ++k) dst[m][k] = *(const LAS bf16x8*)(lds + PG8_SA(b, h) + aoff + m * 2048 + k * 1024); } while (0)
; #define PG8_MMA(ai, bj, At, Bt) do { __builtin_amdgcn_s_setprio(1); _Pragma("unroll") for (int m = 0; m < 4; ++m) _Pragma("unroll") for (int n = 0; n < 2; ++n) _Pragma("unroll") for (int k = 0; k < 2; ++k) \
;         acc[ai][bj][m][n] = __builtin_amdgcn_mfma_f32_16x16x32_bf16(Bt[n][k], At[m][k], acc[ai][bj][m][n], 0, 0, 0); __builtin_amdgcn_s_setprio(0); } while (0)
; #define PG8_WAIT_V(n) asm volatile("s_waitcnt vmcnt(" #n ")" ::: "memory")
; #define PG8_WAIT_L(n) asm volatile("s_waitcnt lgkmcnt(" #n ")" ::: "memory")
; #define PG8_BAR __builtin_amdgcn_s_barrier()
; #define PG8_SCHED __builtin_amdgcn_sched_barrier(0)
; template <class Epi, class Sched, bool ALIGN_EPI, bool LAST_FUSED = false, bool PERM = false, bool CARRY = false>
; __device__ __forceinline__ void gemm_phase(LAS unsigned char* lds, const int tid, const int K, const int lda, const int ldb, const Sched& S, const Epi& E) {
;     ...
;             PG8_LDA(At, 1, 1); PG8_STAGE(PG8_SB(1, 0), b3, voffB); PG8_STAGE(PG8_SB(1, 1), b3 + hstepB, voffB); PG8_STAGE(PG8_SA(1, 0), a3, voffA);
;             PG8_WAIT_V(8); PG8_WAIT_L(0); PG8_BAR; PG8_MMA(1, 0, At, B0); PG8_MMA(1, 1, At, B1); PG8_BAR; PG8_SCHED;
;         }
;         if constexpr (ALIGN_EPI) { if (wr == 0) PG8_BAR; }
	s_setprio 0
	s_mov_b32 m0, s23
	v_lshl_add_u64 v[206:207], v[206:207], 0, s[68:69]
	ds_read_b128 v[174:177], v145 offset:49152
	ds_read_b128 v[178:181], v145 offset:50176
	ds_read_b128 v[182:185], v145 offset:51200
	ds_read_b128 v[186:189], v145 offset:52224
	ds_read_b128 v[190:193], v145 offset:53248
	ds_read_b128 v[194:197], v145 offset:54272
	ds_read_b128 v[198:201], v145 offset:55296
	ds_read_b128 v[202:205], v145 offset:56320
	global_load_lds_dwordx4 v[206:207], off
	v_lshl_add_u64 v[206:207], v[208:209], 0, s[68:69]
	s_mov_b32 m0, s15
	s_nop 0
	global_load_lds_dwordx4 v[206:207], off
	v_lshl_add_u64 v[206:207], s[40:41], 0, v[0:1]
	s_mov_b32 m0, s76
	s_nop 0
	global_load_lds_dwordx4 v[206:207], off
	v_lshl_add_u64 v[206:207], s[40:41], 0, v[130:131]
	s_mov_b32 m0, s75
	s_nop 0
	global_load_lds_dwordx4 v[206:207], off
	v_lshl_add_u64 v[206:207], v[210:211], 0, s[68:69]
	s_mov_b32 m0, s66
	s_nop 0
	global_load_lds_dwordx4 v[206:207], off
	v_lshl_add_u64 v[206:207], v[212:213], 0, s[68:69]
	s_mov_b32 m0, s67
	s_nop 0
	global_load_lds_dwordx4 v[206:207], off
	s_waitcnt vmcnt(8)
	s_waitcnt lgkmcnt(0)
	s_barrier
	v_mfma_f32_16x16x32_bf16 v[62:65], v[136:139], v[174:177], v[62:65]
	s_setprio 1
	v_mfma_f32_16x16x32_bf16 v[58:61], v[150:153], v[174:177], v[58:61]
	v_mfma_f32_16x16x32_bf16 v[46:49], v[136:139], v[182:185], v[46:49]
	v_mfma_f32_16x16x32_bf16 v[42:45], v[150:153], v[182:185], v[42:45]
	v_mfma_f32_16x16x32_bf16 v[30:33], v[136:139], v[190:193], v[30:33]
	v_mfma_f32_16x16x32_bf16 v[26:29], v[150:153], v[190:193], v[26:29]
	v_mfma_f32_16x16x32_bf16 v[14:17], v[136:139], v[198:201], v[14:17]
	v_mfma_f32_16x16x32_bf16 v[10:13], v[150:153], v[198:201], v[10:13]
	v_mfma_f32_16x16x32_bf16 v[62:65], v[146:149], v[178:181], v[62:65]
	v_mfma_f32_16x16x32_bf16 v[58:61], v[154:157], v[178:181], v[58:61]
	v_mfma_f32_16x16x32_bf16 v[46:49], v[146:149], v[186:189], v[46:49]
	v_mfma_f32_16x16x32_bf16 v[42:45], v[154:157], v[186:189], v[42:45]
	v_mfma_f32_16x16x32_bf16 v[30:33], v[146:149], v[194:197], v[30:33]
	v_mfma_f32_16x16x32_bf16 v[26:29], v[154:157], v[194:197], v[26:29]
	v_mfma_f32_16x16x32_bf16 v[14:17], v[146:149], v[202:205], v[14:17]
	v_mfma_f32_16x16x32_bf16 v[10:13], v[154:157], v[202:205], v[10:13]
	s_setprio 0
	s_setprio 1
	v_mfma_f32_16x16x32_bf16 v[54:57], v[158:161], v[174:177], v[54:57]
	v_mfma_f32_16x16x32_bf16 v[50:53], v[166:169], v[174:177], v[50:53]
	v_mfma_f32_16x16x32_bf16 v[38:41], v[158:161], v[182:185], v[38:41]
	v_mfma_f32_16x16x32_bf16 v[34:37], v[166:169], v[182:185], v[34:37]
	v_mfma_f32_16x16x32_bf16 v[22:25], v[158:161], v[190:193], v[22:25]
	v_mfma_f32_16x16x32_bf16 v[18:21], v[166:169], v[190:193], v[18:21]
	v_mfma_f32_16x16x32_bf16 v[6:9], v[158:161], v[198:201], v[6:9]
	v_mfma_f32_16x16x32_bf16 v[2:5], v[166:169], v[198:201], v[2:5]
	v_mfma_f32_16x16x32_bf16 v[54:57], v[162:165], v[178:181], v[54:57]
	v_mfma_f32_16x16x32_bf16 v[50:53], v[170:173], v[178:181], v[50:53]
	v_mfma_f32_16x16x32_bf16 v[38:41], v[162:165], v[186:189], v[38:41]
	v_mfma_f32_16x16x32_bf16 v[34:37], v[170:173], v[186:189], v[34:37]
	v_mfma_f32_16x16x32_bf16 v[22:25], v[162:165], v[194:197], v[22:25]
	v_mfma_f32_16x16x32_bf16 v[18:21], v[170:173], v[194:197], v[18:21]
	v_mfma_f32_16x16x32_bf16 v[6:9], v[162:165], v[202:205], v[6:9]
	v_mfma_f32_16x16x32_bf16 v[2:5], v[170:173], v[202:205], v[2:5]
	s_barrier
	s_setprio 0
	s_movk_i32 s15, 0x100
	s_andn2_b64 vcc, exec, s[38:39]
	s_mov_b64 s[40:41], -1
	s_mov_b64 s[38:39], 0
	s_cbranch_vccz .LBB0_601
	s_and_b64 vcc, exec, s[12:13]
	s_cbranch_vccz .LBB0_604
	s_barrier

; #define PG8_STAGE(bufoff, gbase, voff) do { _Pragma("unroll") for (int _i = 0; _i < 2; ++_i) \
;         __builtin_amdgcn_global_load_lds((const unsigned*)((const char*)(gbase) + (voff)[_i]), (LAS unsigned*)(lds + (bufoff) + ldsw + _i * 8192), 16, 0, 0); } while (0)
; #define PG8_LDA(dst, b, h) do { _Pragma("unroll") for (int m = 0; m < 4; ++m) _Pragma("unroll") for (int k = 0; k < 2; ++k) dst[m][k] = *(const LAS bf16x8*)(lds + PG8_SA(b, h) + aoff + m * 2048 + k * 1024); } while (0)
; #define PG8_LDB(dst, b, h) do { _Pragma("unroll") for (int n = 0; n < 2; ++n) _Pragma("unroll") for (int k = 0; k < 2; ++k) dst[n][k] = *(const LAS bf16x8*)(lds + PG8_SB(b, h) + boff + n * 2048 + k * 1024); } while (0)
; #define PG8_MMA(ai, bj, At, Bt) do { __builtin_amdgcn_s_setprio(1); _Pragma("unroll") for (int m = 0; m < 4; ++m) _Pragma("unroll") for (int n = 0; n < 2; ++n) _Pragma("unroll") for (int k = 0; k < 2; ++k) \
;         acc[ai][bj][m][n] = __builtin_amdgcn_mfma_f32_16x16x32_bf16(Bt[n][k], At[m][k], acc[ai][bj][m][n], 0, 0, 0); __builtin_amdgcn_s_setprio(0); } while (0)
; #define PG8_WAIT_V(n) asm volatile("s_waitcnt vmcnt(" #n ")" ::: "memory")
; #define PG8_WAIT_L(n) asm volatile("s_waitcnt lgkmcnt(" #n ")" ::: "memory")
; template <class Epi, class Sched, bool ALIGN_EPI, bool LAST_FUSED = false, bool PERM = false, bool CARRY = false>
; __device__ __forceinline__ void gemm_phase(LAS unsigned char* lds, const int tid, const int K, const int lda, const int ldb, const Sched& S, const Epi& E) {
;     ...
;         for (int t = 0; t < nt; t += 2) {
;             const bool last = (t == nt - 2);
;             const char* a1 = cA + (size_t)(t + 1) * kstep;
;             const char* a2 = last ? nA : cA + (size_t)(t + 2) * kstep; const char* b2 = last ? nB : cB + (size_t)(t + 2) * kstep;
;             const char* a3 = a2 + kstep; const char* b3 = b2 + kstep;
;             PG8_LDB(B0, 0, 0); PG8_LDB(B1, 0, 1); PG8_SCHED; PG8_LDA(At, 0, 0); PG8_STAGE(PG8_SA(1, 1), a1 + hstepA, voffA);
;             PG8_WAIT_V(8); PG8_WAIT_L(0); PG8_BAR; PG8_MMA(0, 0, At, B0); PG8_MMA(0, 1, At, B1); PG8_BAR; PG8_SCHED;
;             PG8_LDA(At, 0, 1); PG8_STAGE(PG8_SB(0, 0), b2, voffB); PG8_STAGE(PG8_SB(0, 1), b2 + hstepB, voffB); PG8_STAGE(PG8_SA(0, 0), a2, voffA);
;             PG8_WAIT_V(8); PG8_WAIT_L(0); PG8_BAR; PG8_MMA(1, 0, At, B0); PG8_MMA(1, 1, At, B1); PG8_BAR; PG8_SCHED;
.LBB0_622:
	s_add_u32 s48, s30, s24
	s_addc_u32 s49, s31, 0
	s_add_u32 s42, s48, 0x100
	s_addc_u32 s43, s49, 0
	s_and_b64 s[40:41], s[38:39], exec
	s_cselect_b32 s43, s15, s43
	s_cselect_b32 s42, s14, s42
	s_add_u32 s24, s26, s24
	s_addc_u32 s40, s27, 0
	s_add_u32 s24, s24, 0x100
	s_addc_u32 s40, s40, 0
	s_add_i32 s62, 0, 0x10000
	s_and_b64 s[38:39], s[38:39], exec
	s_cselect_b32 s47, s17, s40
	s_cselect_b32 s46, s16, s24
	s_add_i32 s39, 0, 0x14000
	s_add_u32 s64, s48, 0x30080
	s_addc_u32 s65, s49, 0
	s_add_i32 s67, s62, s29
	s_add_i32 m0, s45, 0xc000
	s_add_i32 s66, s45, 0xe000
	s_add_i32 s70, s67, 0x2000
	s_add_u32 s48, s46, 0x10000
	v_add_u32_e32 v152, s62, v140
	v_add_u32_e32 v168, s39, v140
	s_addc_u32 s49, s47, 0
	s_add_i32 s71, s39, s29
	ds_read_b128 v[136:139], v152
	ds_read_b128 v[144:147], v152 offset:1024
	ds_read_b128 v[148:151], v152 offset:2048
	ds_read_b128 v[152:155], v152 offset:3072
	ds_read_b128 v[156:159], v168
	ds_read_b128 v[160:163], v168 offset:1024
	ds_read_b128 v[164:167], v168 offset:2048
	ds_read_b128 v[168:171], v168 offset:3072
	s_add_i32 s74, s71, 0x2000
	s_add_i32 s75, 0, 0x18000
	s_add_i32 s76, 0, 0x1c000
	s_add_u32 s40, s42, 0x30000
	s_addc_u32 s41, s43, 0
	s_add_i32 s61, s75, s29
	s_add_i32 s24, s61, 0x2000
	s_add_u32 s38, s46, 0x10080
	s_addc_u32 s39, s47, 0
	s_add_i32 s63, s76, s29
	s_add_i32 s62, s63, 0x2000
	v_lshl_add_u64 v[204:205], s[64:65], 0, v[130:131]
	ds_read_b128 v[172:175], v143
	ds_read_b128 v[176:179], v143 offset:1024
	ds_read_b128 v[180:183], v143 offset:2048
	ds_read_b128 v[184:187], v143 offset:3072
	ds_read_b128 v[188:191], v143 offset:4096
	ds_read_b128 v[192:195], v143 offset:5120
	ds_read_b128 v[196:199], v143 offset:6144
	ds_read_b128 v[200:203], v143 offset:7168
	global_load_lds_dwordx4 v[204:205], off
	v_lshl_add_u64 v[204:205], s[64:65], 0, v[132:133]
	s_mov_b32 m0, s66
	s_nop 0
	global_load_lds_dwordx4 v[204:205], off
	s_waitcnt vmcnt(8)
	s_waitcnt lgkmcnt(0)
	s_barrier
	v_mfma_f32_16x16x32_bf16 v[126:129], v[136:139], v[172:175], v[126:129]
	s_setprio 1
	v_mfma_f32_16x16x32_bf16 v[122:125], v[148:151], v[172:175], v[122:125]
	v_mfma_f32_16x16x32_bf16 v[118:121], v[136:139], v[180:183], v[118:121]
	v_mfma_f32_16x16x32_bf16 v[114:117], v[148:151], v[180:183], v[114:117]
	v_mfma_f32_16x16x32_bf16 v[110:113], v[136:139], v[188:191], v[110:113]
	v_mfma_f32_16x16x32_bf16 v[106:109], v[148:151], v[188:191], v[106:109]
	v_mfma_f32_16x16x32_bf16 v[102:105], v[136:139], v[196:199], v[102:105]
	v_mfma_f32_16x16x32_bf16 v[98:101], v[148:151], v[196:199], v[98:101]
	v_mfma_f32_16x16x32_bf16 v[126:129], v[144:147], v[176:179], v[126:129]
	v_mfma_f32_16x16x32_bf16 v[122:125], v[152:155], v[176:179], v[122:125]
	v_mfma_f32_16x16x32_bf16 v[118:121], v[144:147], v[184:187], v[118:121]
	v_mfma_f32_16x16x32_bf16 v[114:117], v[152:155], v[184:187], v[114:117]
	v_mfma_f32_16x16x32_bf16 v[110:113], v[144:147], v[192:195], v[110:113]
	v_mfma_f32_16x16x32_bf16 v[106:109], v[152:155], v[192:195], v[106:109]
	v_mfma_f32_16x16x32_bf16 v[102:105], v[144:147], v[200:203], v[102:105]
	v_mfma_f32_16x16x32_bf16 v[98:101], v[152:155], v[200:203], v[98:101]
	s_setprio 0
	s_setprio 1
	v_mfma_f32_16x16x32_bf16 v[94:97], v[156:159], v[172:175], v[94:97]
	v_mfma_f32_16x16x32_bf16 v[90:93], v[164:167], v[172:175], v[90:93]
	v_mfma_f32_16x16x32_bf16 v[86:89], v[156:159], v[180:183], v[86:89]
	v_mfma_f32_16x16x32_bf16 v[82:85], v[164:167], v[180:183], v[82:85]
	v_mfma_f32_16x16x32_bf16 v[78:81], v[156:159], v[188:191], v[78:81]
	v_mfma_f32_16x16x32_bf16 v[74:77], v[164:167], v[188:191], v[74:77]
	v_mfma_f32_16x16x32_bf16 v[70:73], v[156:159], v[196:199], v[70:73]
	v_mfma_f32_16x16x32_bf16 v[66:69], v[164:167], v[196:199], v[66:69]
	v_mfma_f32_16x16x32_bf16 v[94:97], v[160:163], v[176:179], v[94:97]
	v_mfma_f32_16x16x32_bf16 v[90:93], v[168:171], v[176:179], v[90:93]
	v_mfma_f32_16x16x32_bf16 v[86:89], v[160:163], v[184:187], v[86:89]
	v_mfma_f32_16x16x32_bf16 v[82:85], v[168:171], v[184:187], v[82:85]
	v_mfma_f32_16x16x32_bf16 v[78:81], v[160:163], v[192:195], v[78:81]
	v_mfma_f32_16x16x32_bf16 v[74:77], v[168:171], v[192:195], v[74:77]
	v_mfma_f32_16x16x32_bf16 v[70:73], v[160:163], v[200:203], v[70:73]
	v_mfma_f32_16x16x32_bf16 v[66:69], v[168:171], v[200:203], v[66:69]
	s_barrier
	s_setprio 0
	s_mov_b32 m0, s67
	v_lshl_add_u64 v[204:205], s[46:47], 0, v[0:1]
	ds_read_b128 v[172:175], v143 offset:16384
	ds_read_b128 v[176:179], v143 offset:17408
	ds_read_b128 v[180:183], v143 offset:18432
	ds_read_b128 v[184:187], v143 offset:19456
	ds_read_b128 v[188:191], v143 offset:20480
	ds_read_b128 v[192:195], v143 offset:21504
	ds_read_b128 v[196:199], v143 offset:22528
	ds_read_b128 v[200:203], v143 offset:23552
	global_load_lds_dwordx4 v[204:205], off
	v_lshl_add_u64 v[206:207], s[46:47], 0, v[134:135]
	s_mov_b32 m0, s70
	v_lshl_add_u64 v[208:209], s[48:49], 0, v[0:1]
	global_load_lds_dwordx4 v[206:207], off
	s_mov_b32 m0, s71
	v_lshl_add_u64 v[210:211], s[42:43], 0, v[132:133]
	global_load_lds_dwordx4 v[208:209], off
	v_lshl_add_u64 v[208:209], s[48:49], 0, v[134:135]
	s_mov_b32 m0, s74
	s_nop 0
	global_load_lds_dwordx4 v[208:209], off
	v_lshl_add_u64 v[208:209], s[42:43], 0, v[130:131]
	s_mov_b32 m0, s45
	s_nop 0
	global_load_lds_dwordx4 v[208:209], off
	s_mov_b32 m0, s50
	s_nop 0
	global_load_lds_dwordx4 v[210:211], off
	s_waitcnt vmcnt(8)
	s_waitcnt lgkmcnt(0)
	s_barrier
; #define PG8_STAGE(bufoff, gbase, voff) do { _Pragma("unroll") for (int _i = 0; _i < 2; ++_i) \
;         __builtin_amdgcn_global_load_lds((const unsigned*)((const char*)(gbase) + (voff)[_i]), (LAS unsigned*)(lds + (bufoff) + ldsw + _i * 8192), 16, 0, 0); } while (0)
; #define PG8_LDA(dst, b, h) do { _Pragma("unroll") for (int m = 0; m < 4; ++m) _Pragma("unroll") for (int k = 0; k < 2; ++k) dst[m][k] = *(const LAS bf16x8*)(lds + PG8_SA(b, h) + aoff + m * 2048 + k * 1024); } while (0)
; #define PG8_LDB(dst, b, h) do { _Pragma("unroll") for (int n = 0; n < 2; ++n) _Pragma("unroll") for (int k = 0; k < 2; ++k) dst[n][k] = *(const LAS bf16x8*)(lds + PG8_SB(b, h) + boff + n * 2048 + k * 1024); } while (0)
; #define PG8_MMA(ai, bj, At, Bt) do { __builtin_amdgcn_s_setprio(1); _Pragma("unroll") for (int m = 0; m < 4; ++m) _Pragma("unroll") for (int n = 0; n < 2; ++n) _Pragma("unroll") for (int k = 0; k < 2; ++k) \
;         acc[ai][bj][m][n] = __builtin_amdgcn_mfma_f32_16x16x32_bf16(Bt[n][k], At[m][k], acc[ai][bj][m][n], 0, 0, 0); __builtin_amdgcn_s_setprio(0); } while (0)
; #define PG8_WAIT_V(n) asm volatile("s_waitcnt vmcnt(" #n ")" ::: "memory")
; #define PG8_WAIT_L(n) asm volatile("s_waitcnt lgkmcnt(" #n ")" ::: "memory")
; #define PG8_BAR __builtin_amdgcn_s_barrier()
; #define PG8_SCHED __builtin_amdgcn_sched_barrier(0)
; template <class Epi, class Sched, bool ALIGN_EPI, bool LAST_FUSED = false, bool PERM = false, bool CARRY = false>
; __device__ __forceinline__ void gemm_phase(LAS unsigned char* lds, const int tid, const int K, const int lda, const int ldb, const Sched& S, const Epi& E) {
;     ...
;             PG8_WAIT_V(8); PG8_WAIT_L(0); PG8_BAR; PG8_MMA(1, 0, At, B0); PG8_MMA(1, 1, At, B1); PG8_BAR; PG8_SCHED;
;             PG8_LDB(B0, 1, 0); PG8_LDB(B1, 1, 1); PG8_SCHED; PG8_LDA(At, 1, 0); PG8_STAGE(PG8_SA(0, 1), a2 + hstepA, voffA);
;             PG8_WAIT_V(8); PG8_WAIT_L(0); PG8_BAR; PG8_MMA(0, 0, At, B0); PG8_MMA(0, 1, At, B1); PG8_BAR; PG8_SCHED;
	v_mfma_f32_16x16x32_bf16 v[62:65], v[136:139], v[172:175], v[62:65]
	s_setprio 1
	v_mfma_f32_16x16x32_bf16 v[58:61], v[148:151], v[172:175], v[58:61]
	v_mfma_f32_16x16x32_bf16 v[54:57], v[136:139], v[180:183], v[54:57]
	v_mfma_f32_16x16x32_bf16 v[50:53], v[148:151], v[180:183], v[50:53]
	v_mfma_f32_16x16x32_bf16 v[46:49], v[136:139], v[188:191], v[46:49]
	v_mfma_f32_16x16x32_bf16 v[42:45], v[148:151], v[188:191], v[42:45]
	v_mfma_f32_16x16x32_bf16 v[38:41], v[136:139], v[196:199], v[38:41]
	v_mfma_f32_16x16x32_bf16 v[34:37], v[148:151], v[196:199], v[34:37]
	v_mfma_f32_16x16x32_bf16 v[62:65], v[144:147], v[176:179], v[62:65]
	v_mfma_f32_16x16x32_bf16 v[58:61], v[152:155], v[176:179], v[58:61]
	v_mfma_f32_16x16x32_bf16 v[54:57], v[144:147], v[184:187], v[54:57]
	v_mfma_f32_16x16x32_bf16 v[50:53], v[152:155], v[184:187], v[50:53]
	v_mfma_f32_16x16x32_bf16 v[46:49], v[144:147], v[192:195], v[46:49]
	v_mfma_f32_16x16x32_bf16 v[42:45], v[152:155], v[192:195], v[42:45]
	v_mfma_f32_16x16x32_bf16 v[38:41], v[144:147], v[200:203], v[38:41]
	v_mfma_f32_16x16x32_bf16 v[34:37], v[152:155], v[200:203], v[34:37]
	s_setprio 0
	s_setprio 1
	v_mfma_f32_16x16x32_bf16 v[30:33], v[156:159], v[172:175], v[30:33]
	v_mfma_f32_16x16x32_bf16 v[26:29], v[164:167], v[172:175], v[26:29]
	v_mfma_f32_16x16x32_bf16 v[22:25], v[156:159], v[180:183], v[22:25]
	v_mfma_f32_16x16x32_bf16 v[18:21], v[164:167], v[180:183], v[18:21]
	v_mfma_f32_16x16x32_bf16 v[14:17], v[156:159], v[188:191], v[14:17]
	v_mfma_f32_16x16x32_bf16 v[10:13], v[164:167], v[188:191], v[10:13]
	v_mfma_f32_16x16x32_bf16 v[6:9], v[156:159], v[196:199], v[6:9]
	v_mfma_f32_16x16x32_bf16 v[2:5], v[164:167], v[196:199], v[2:5]
	v_mfma_f32_16x16x32_bf16 v[30:33], v[160:163], v[176:179], v[30:33]
	v_mfma_f32_16x16x32_bf16 v[26:29], v[168:171], v[176:179], v[26:29]
	v_mfma_f32_16x16x32_bf16 v[22:25], v[160:163], v[184:187], v[22:25]
	v_mfma_f32_16x16x32_bf16 v[18:21], v[168:171], v[184:187], v[18:21]
	v_mfma_f32_16x16x32_bf16 v[14:17], v[160:163], v[192:195], v[14:17]
	v_mfma_f32_16x16x32_bf16 v[10:13], v[168:171], v[192:195], v[10:13]
	v_mfma_f32_16x16x32_bf16 v[6:9], v[160:163], v[200:203], v[6:9]
	v_mfma_f32_16x16x32_bf16 v[2:5], v[168:171], v[200:203], v[2:5]
	s_barrier
	s_setprio 0
	v_add_u32_e32 v152, s75, v140
	v_add_u32_e32 v168, s76, v140
	ds_read_b128 v[136:139], v152
	ds_read_b128 v[144:147], v152 offset:1024
	ds_read_b128 v[148:151], v152 offset:2048
	ds_read_b128 v[152:155], v152 offset:3072
	ds_read_b128 v[156:159], v168
	ds_read_b128 v[160:163], v168 offset:1024
	ds_read_b128 v[164:167], v168 offset:2048
	ds_read_b128 v[168:171], v168 offset:3072
	s_mov_b32 m0, s51
	v_lshl_add_u64 v[212:213], s[40:41], 0, v[130:131]
	ds_read_b128 v[172:175], v143 offset:32768
	ds_read_b128 v[176:179], v143 offset:33792
	ds_read_b128 v[180:183], v143 offset:34816
	ds_read_b128 v[184:187], v143 offset:35840
	ds_read_b128 v[188:191], v143 offset:36864
	ds_read_b128 v[192:195], v143 offset:37888
	ds_read_b128 v[196:199], v143 offset:38912
	ds_read_b128 v[200:203], v143 offset:39936
	global_load_lds_dwordx4 v[212:213], off
	v_lshl_add_u64 v[212:213], s[40:41], 0, v[132:133]
	s_mov_b32 m0, s52
	s_nop 0
	global_load_lds_dwordx4 v[212:213], off
	s_waitcnt vmcnt(8)
	s_waitcnt lgkmcnt(0)
	s_barrier
	v_mfma_f32_16x16x32_bf16 v[126:129], v[136:139], v[172:175], v[126:129]
	s_setprio 1
	v_mfma_f32_16x16x32_bf16 v[122:125], v[148:151], v[172:175], v[122:125]
	v_mfma_f32_16x16x32_bf16 v[118:121], v[136:139], v[180:183], v[118:121]
	v_mfma_f32_16x16x32_bf16 v[114:117], v[148:151], v[180:183], v[114:117]
	v_mfma_f32_16x16x32_bf16 v[110:113], v[136:139], v[188:191], v[110:113]
	v_mfma_f32_16x16x32_bf16 v[106:109], v[148:151], v[188:191], v[106:109]
	v_mfma_f32_16x16x32_bf16 v[102:105], v[136:139], v[196:199], v[102:105]
	v_mfma_f32_16x16x32_bf16 v[98:101], v[148:151], v[196:199], v[98:101]
	v_mfma_f32_16x16x32_bf16 v[126:129], v[144:147], v[176:179], v[126:129]
	v_mfma_f32_16x16x32_bf16 v[122:125], v[152:155], v[176:179], v[122:125]
	v_mfma_f32_16x16x32_bf16 v[118:121], v[144:147], v[184:187], v[118:121]
	v_mfma_f32_16x16x32_bf16 v[114:117], v[152:155], v[184:187], v[114:117]
	v_mfma_f32_16x16x32_bf16 v[110:113], v[144:147], v[192:195], v[110:113]
	v_mfma_f32_16x16x32_bf16 v[106:109], v[152:155], v[192:195], v[106:109]
	v_mfma_f32_16x16x32_bf16 v[102:105], v[144:147], v[200:203], v[102:105]
	v_mfma_f32_16x16x32_bf16 v[98:101], v[152:155], v[200:203], v[98:101]
	s_setprio 0
	s_setprio 1
	v_mfma_f32_16x16x32_bf16 v[94:97], v[156:159], v[172:175], v[94:97]
	v_mfma_f32_16x16x32_bf16 v[90:93], v[164:167], v[172:175], v[90:93]
	v_mfma_f32_16x16x32_bf16 v[86:89], v[156:159], v[180:183], v[86:89]
	v_mfma_f32_16x16x32_bf16 v[82:85], v[164:167], v[180:183], v[82:85]
	v_mfma_f32_16x16x32_bf16 v[78:81], v[156:159], v[188:191], v[78:81]
	v_mfma_f32_16x16x32_bf16 v[74:77], v[164:167], v[188:191], v[74:77]
	v_mfma_f32_16x16x32_bf16 v[70:73], v[156:159], v[196:199], v[70:73]
	v_mfma_f32_16x16x32_bf16 v[66:69], v[164:167], v[196:199], v[66:69]
	v_mfma_f32_16x16x32_bf16 v[94:97], v[160:163], v[176:179], v[94:97]
	v_mfma_f32_16x16x32_bf16 v[90:93], v[168:171], v[176:179], v[90:93]
	v_mfma_f32_16x16x32_bf16 v[86:89], v[160:163], v[184:187], v[86:89]
	v_mfma_f32_16x16x32_bf16 v[82:85], v[168:171], v[184:187], v[82:85]
	v_mfma_f32_16x16x32_bf16 v[78:81], v[160:163], v[192:195], v[78:81]
	v_mfma_f32_16x16x32_bf16 v[74:77], v[168:171], v[192:195], v[74:77]
	v_mfma_f32_16x16x32_bf16 v[70:73], v[160:163], v[200:203], v[70:73]
	v_mfma_f32_16x16x32_bf16 v[66:69], v[168:171], v[200:203], v[66:69]
	s_barrier
; #define PG8_STAGE(bufoff, gbase, voff) do { _Pragma("unroll") for (int _i = 0; _i < 2; ++_i) \
;         __builtin_amdgcn_global_load_lds((const unsigned*)((const char*)(gbase) + (voff)[_i]), (LAS unsigned*)(lds + (bufoff) + ldsw + _i * 8192), 16, 0, 0); } while (0)
; #define PG8_LDA(dst, b, h) do { _Pragma("unroll") for (int m = 0; m < 4; ++m) _Pragma("unroll") for (int k = 0; k < 2; ++k) dst[m][k] = *(const LAS bf16x8*)(lds + PG8_SA(b, h) + aoff + m * 2048 + k * 1024); } while (0)
; #define PG8_MMA(ai, bj, At, Bt) do { __builtin_amdgcn_s_setprio(1); _Pragma("unroll") for (int m = 0; m < 4; ++m) _Pragma("unroll") for (int n = 0; n < 2; ++n) _Pragma("unroll") for (int k = 0; k < 2; ++k) \
;         acc[ai][bj][m][n] = __builtin_amdgcn_mfma_f32_16x16x32_bf16(Bt[n][k], At[m][k], acc[ai][bj][m][n], 0, 0, 0); __builtin_amdgcn_s_setprio(0); } while (0)
; #define PG8_WAIT_V(n) asm volatile("s_waitcnt vmcnt(" #n ")" ::: "memory")
; #define PG8_WAIT_L(n) asm volatile("s_waitcnt lgkmcnt(" #n ")" ::: "memory")
; #define PG8_BAR __builtin_amdgcn_s_barrier()
; #define PG8_SCHED __builtin_amdgcn_sched_barrier(0)
; template <class Epi, class Sched, bool ALIGN_EPI, bool LAST_FUSED = false, bool PERM = false, bool CARRY = false>
; __device__ __forceinline__ void gemm_phase(LAS unsigned char* lds, const int tid, const int K, const int lda, const int ldb, const Sched& S, const Epi& E) {
;     ...
;             PG8_LDA(At, 1, 1); PG8_STAGE(PG8_SB(1, 0), b3, voffB); PG8_STAGE(PG8_SB(1, 1), b3 + hstepB, voffB); PG8_STAGE(PG8_SA(1, 0), a3, voffA);
;             PG8_WAIT_V(8); PG8_WAIT_L(0); PG8_BAR; PG8_MMA(1, 0, At, B0); PG8_MMA(1, 1, At, B1); PG8_BAR; PG8_SCHED;
;         }
;         if constexpr (ALIGN_EPI) { if (wr == 0) PG8_BAR; }
	s_setprio 0
	s_mov_b32 m0, s61
	v_lshl_add_u64 v[204:205], v[204:205], 0, s[68:69]
	ds_read_b128 v[172:175], v143 offset:49152
	ds_read_b128 v[176:179], v143 offset:50176
	ds_read_b128 v[180:183], v143 offset:51200
	ds_read_b128 v[184:187], v143 offset:52224
	ds_read_b128 v[188:191], v143 offset:53248
	ds_read_b128 v[192:195], v143 offset:54272
	ds_read_b128 v[196:199], v143 offset:55296
	ds_read_b128 v[200:203], v143 offset:56320
	global_load_lds_dwordx4 v[204:205], off
	v_lshl_add_u64 v[204:205], v[206:207], 0, s[68:69]
	s_mov_b32 m0, s24
	s_nop 0
	global_load_lds_dwordx4 v[204:205], off
	v_lshl_add_u64 v[204:205], s[38:39], 0, v[0:1]
	s_mov_b32 m0, s63
	s_nop 0
	global_load_lds_dwordx4 v[204:205], off
	v_lshl_add_u64 v[204:205], s[38:39], 0, v[134:135]
	s_mov_b32 m0, s62
	s_nop 0
	global_load_lds_dwordx4 v[204:205], off
	v_lshl_add_u64 v[204:205], v[208:209], 0, s[68:69]
	s_mov_b32 m0, s55
	s_nop 0
	global_load_lds_dwordx4 v[204:205], off
	v_lshl_add_u64 v[204:205], v[210:211], 0, s[68:69]
	s_mov_b32 m0, s56
	s_nop 0
	global_load_lds_dwordx4 v[204:205], off
	s_waitcnt vmcnt(8)
	s_waitcnt lgkmcnt(0)
	s_barrier
	v_mfma_f32_16x16x32_bf16 v[62:65], v[136:139], v[172:175], v[62:65]
	s_setprio 1
	v_mfma_f32_16x16x32_bf16 v[58:61], v[148:151], v[172:175], v[58:61]
	v_mfma_f32_16x16x32_bf16 v[54:57], v[136:139], v[180:183], v[54:57]
	v_mfma_f32_16x16x32_bf16 v[50:53], v[148:151], v[180:183], v[50:53]
	v_mfma_f32_16x16x32_bf16 v[46:49], v[136:139], v[188:191], v[46:49]
	v_mfma_f32_16x16x32_bf16 v[42:45], v[148:151], v[188:191], v[42:45]
	v_mfma_f32_16x16x32_bf16 v[38:41], v[136:139], v[196:199], v[38:41]
	v_mfma_f32_16x16x32_bf16 v[34:37], v[148:151], v[196:199], v[34:37]
	v_mfma_f32_16x16x32_bf16 v[62:65], v[144:147], v[176:179], v[62:65]
	v_mfma_f32_16x16x32_bf16 v[58:61], v[152:155], v[176:179], v[58:61]
	v_mfma_f32_16x16x32_bf16 v[54:57], v[144:147], v[184:187], v[54:57]
	v_mfma_f32_16x16x32_bf16 v[50:53], v[152:155], v[184:187], v[50:53]
	v_mfma_f32_16x16x32_bf16 v[46:49], v[144:147], v[192:195], v[46:49]
	v_mfma_f32_16x16x32_bf16 v[42:45], v[152:155], v[192:195], v[42:45]
	v_mfma_f32_16x16x32_bf16 v[38:41], v[144:147], v[200:203], v[38:41]
	v_mfma_f32_16x16x32_bf16 v[34:37], v[152:155], v[200:203], v[34:37]
	s_setprio 0
	s_setprio 1
	v_mfma_f32_16x16x32_bf16 v[30:33], v[156:159], v[172:175], v[30:33]
	v_mfma_f32_16x16x32_bf16 v[26:29], v[164:167], v[172:175], v[26:29]
	v_mfma_f32_16x16x32_bf16 v[22:25], v[156:159], v[180:183], v[22:25]
	v_mfma_f32_16x16x32_bf16 v[18:21], v[164:167], v[180:183], v[18:21]
	v_mfma_f32_16x16x32_bf16 v[14:17], v[156:159], v[188:191], v[14:17]
	v_mfma_f32_16x16x32_bf16 v[10:13], v[164:167], v[188:191], v[10:13]
	v_mfma_f32_16x16x32_bf16 v[6:9], v[156:159], v[196:199], v[6:9]
	v_mfma_f32_16x16x32_bf16 v[2:5], v[164:167], v[196:199], v[2:5]
	v_mfma_f32_16x16x32_bf16 v[30:33], v[160:163], v[176:179], v[30:33]
	v_mfma_f32_16x16x32_bf16 v[26:29], v[168:171], v[176:179], v[26:29]
	v_mfma_f32_16x16x32_bf16 v[22:25], v[160:163], v[184:187], v[22:25]
	v_mfma_f32_16x16x32_bf16 v[18:21], v[168:171], v[184:187], v[18:21]
	v_mfma_f32_16x16x32_bf16 v[14:17], v[160:163], v[192:195], v[14:17]
	v_mfma_f32_16x16x32_bf16 v[10:13], v[168:171], v[192:195], v[10:13]
	v_mfma_f32_16x16x32_bf16 v[6:9], v[160:163], v[200:203], v[6:9]
	v_mfma_f32_16x16x32_bf16 v[2:5], v[168:171], v[200:203], v[2:5]
	s_barrier
	s_setprio 0
	s_movk_i32 s24, 0x100
	s_andn2_b64 vcc, exec, s[36:37]
	s_mov_b64 s[38:39], -1
	s_mov_b64 s[36:37], 0
	s_cbranch_vccz .LBB0_622
	s_and_b64 vcc, exec, s[10:11]
	s_cbranch_vccz .LBB0_625
	s_barrier

; #define PG8_STAGE(bufoff, gbase, voff) do { _Pragma("unroll") for (int _i = 0; _i < 2; ++_i) \
;         __builtin_amdgcn_global_load_lds((const unsigned*)((const char*)(gbase) + (voff)[_i]), (LAS unsigned*)(lds + (bufoff) + ldsw + _i * 8192), 16, 0, 0); } while (0)
; #define PG8_LDA(dst, b, h) do { _Pragma("unroll") for (int m = 0; m < 4; ++m) _Pragma("unroll") for (int k = 0; k < 2; ++k) dst[m][k] = *(const LAS bf16x8*)(lds + PG8_SA(b, h) + aoff + m * 2048 + k * 1024); } while (0)
; #define PG8_LDB(dst, b, h) do { _Pragma("unroll") for (int n = 0; n < 2; ++n) _Pragma("unroll") for (int k = 0; k < 2; ++k) dst[n][k] = *(const LAS bf16x8*)(lds + PG8_SB(b, h) + boff + n * 2048 + k * 1024); } while (0)
; #define PG8_MMA(ai, bj, At, Bt) do { __builtin_amdgcn_s_setprio(1); _Pragma("unroll") for (int m = 0; m < 4; ++m) _Pragma("unroll") for (int n = 0; n < 2; ++n) _Pragma("unroll") for (int k = 0; k < 2; ++k) \
;         acc[ai][bj][m][n] = __builtin_amdgcn_mfma_f32_16x16x32_bf16(Bt[n][k], At[m][k], acc[ai][bj][m][n], 0, 0, 0); __builtin_amdgcn_s_setprio(0); } while (0)
; #define PG8_WAIT_V(n) asm volatile("s_waitcnt vmcnt(" #n ")" ::: "memory")
; #define PG8_WAIT_L(n) asm volatile("s_waitcnt lgkmcnt(" #n ")" ::: "memory")
; template <class Epi, class Sched, bool ALIGN_EPI, bool LAST_FUSED = false, bool PERM = false, bool CARRY = false>
; __device__ __forceinline__ void gemm_phase(LAS unsigned char* lds, const int tid, const int K, const int lda, const int ldb, const Sched& S, const Epi& E) {
;     ...
;         for (int t = 0; t < nt; t += 2) {
;             const bool last = (t == nt - 2);
;             const char* a1 = cA + (size_t)(t + 1) * kstep;
;             const char* a2 = last ? nA : cA + (size_t)(t + 2) * kstep; const char* b2 = last ? nB : cB + (size_t)(t + 2) * kstep;
;             const char* a3 = a2 + kstep; const char* b3 = b2 + kstep;
;             PG8_LDB(B0, 0, 0); PG8_LDB(B1, 0, 1); PG8_SCHED; PG8_LDA(At, 0, 0); PG8_STAGE(PG8_SA(1, 1), a1 + hstepA, voffA);
;             PG8_WAIT_V(8); PG8_WAIT_L(0); PG8_BAR; PG8_MMA(0, 0, At, B0); PG8_MMA(0, 1, At, B1); PG8_BAR; PG8_SCHED;
;             PG8_LDA(At, 0, 1); PG8_STAGE(PG8_SB(0, 0), b2, voffB); PG8_STAGE(PG8_SB(0, 1), b2 + hstepB, voffB); PG8_STAGE(PG8_SA(0, 0), a2, voffA);
;             PG8_WAIT_V(8); PG8_WAIT_L(0); PG8_BAR; PG8_MMA(1, 0, At, B0); PG8_MMA(1, 1, At, B1); PG8_BAR; PG8_SCHED;
.LBB0_705:
	s_add_u32 s30, s26, 0x100
	s_addc_u32 s31, s27, 0
	s_add_i32 s54, 0, 0x10000
	s_cmp_eq_u32 s53, 8
	s_cselect_b32 s39, s15, s31
	s_cselect_b32 s38, s14, s30
	v_add_u32_e32 v140, s54, v144
	s_cselect_b32 s37, s17, s52
	s_cselect_b32 s36, s16, s13
	s_add_i32 s55, 0, 0x14000
	ds_read_b128 v[146:149], v140
	ds_read_b128 v[150:153], v140 offset:1024
	ds_read_b128 v[154:157], v140 offset:2048
	ds_read_b128 v[158:161], v140 offset:3072
	v_add_u32_e32 v140, s55, v144
	ds_read_b128 v[162:165], v140
	ds_read_b128 v[166:169], v140 offset:1024
	ds_read_b128 v[170:173], v140 offset:2048
	ds_read_b128 v[174:177], v140 offset:3072
	v_lshl_add_u64 v[140:141], s[26:27], 0, v[136:137]
	s_add_i32 m0, s19, 0xc000
	ds_read_b128 v[178:181], v145
	ds_read_b128 v[182:185], v145 offset:1024
	ds_read_b128 v[186:189], v145 offset:2048
	ds_read_b128 v[190:193], v145 offset:3072
	ds_read_b128 v[194:197], v145 offset:4096
	ds_read_b128 v[198:201], v145 offset:5120
	ds_read_b128 v[202:205], v145 offset:6144
	ds_read_b128 v[206:209], v145 offset:7168
	global_load_lds_dwordx4 v[140:141], off
	v_lshl_add_u64 v[140:141], s[26:27], 0, v[138:139]
	s_add_i32 m0, s19, 0xe000
	s_nop 0
	global_load_lds_dwordx4 v[140:141], off
	s_waitcnt vmcnt(8)
	s_waitcnt lgkmcnt(0)
	s_barrier
	v_mfma_f32_16x16x32_bf16 v[126:129], v[146:149], v[178:181], v[126:129]
	s_setprio 1
	v_mfma_f32_16x16x32_bf16 v[122:125], v[154:157], v[178:181], v[122:125]
	v_mfma_f32_16x16x32_bf16 v[118:121], v[146:149], v[186:189], v[118:121]
	v_mfma_f32_16x16x32_bf16 v[110:113], v[154:157], v[186:189], v[110:113]
	v_mfma_f32_16x16x32_bf16 v[102:105], v[146:149], v[194:197], v[102:105]
	v_mfma_f32_16x16x32_bf16 v[94:97], v[154:157], v[194:197], v[94:97]
	v_mfma_f32_16x16x32_bf16 v[86:89], v[146:149], v[202:205], v[86:89]
	v_mfma_f32_16x16x32_bf16 v[78:81], v[154:157], v[202:205], v[78:81]
	v_mfma_f32_16x16x32_bf16 v[126:129], v[150:153], v[182:185], v[126:129]
	v_mfma_f32_16x16x32_bf16 v[122:125], v[158:161], v[182:185], v[122:125]
	v_mfma_f32_16x16x32_bf16 v[118:121], v[150:153], v[190:193], v[118:121]
	v_mfma_f32_16x16x32_bf16 v[110:113], v[158:161], v[190:193], v[110:113]
	v_mfma_f32_16x16x32_bf16 v[102:105], v[150:153], v[198:201], v[102:105]
	v_mfma_f32_16x16x32_bf16 v[94:97], v[158:161], v[198:201], v[94:97]
	v_mfma_f32_16x16x32_bf16 v[86:89], v[150:153], v[206:209], v[86:89]
	v_mfma_f32_16x16x32_bf16 v[78:81], v[158:161], v[206:209], v[78:81]
	s_setprio 0
	s_setprio 1
	v_mfma_f32_16x16x32_bf16 v[114:117], v[162:165], v[178:181], v[114:117]
	v_mfma_f32_16x16x32_bf16 v[106:109], v[170:173], v[178:181], v[106:109]
	v_mfma_f32_16x16x32_bf16 v[98:101], v[162:165], v[186:189], v[98:101]
	v_mfma_f32_16x16x32_bf16 v[90:93], v[170:173], v[186:189], v[90:93]
	v_mfma_f32_16x16x32_bf16 v[82:85], v[162:165], v[194:197], v[82:85]
	v_mfma_f32_16x16x32_bf16 v[74:77], v[170:173], v[194:197], v[74:77]
	v_mfma_f32_16x16x32_bf16 v[70:73], v[162:165], v[202:205], v[70:73]
	v_mfma_f32_16x16x32_bf16 v[66:69], v[170:173], v[202:205], v[66:69]
	v_mfma_f32_16x16x32_bf16 v[114:117], v[166:169], v[182:185], v[114:117]
	v_mfma_f32_16x16x32_bf16 v[106:109], v[174:177], v[182:185], v[106:109]
	v_mfma_f32_16x16x32_bf16 v[98:101], v[166:169], v[190:193], v[98:101]
	v_mfma_f32_16x16x32_bf16 v[90:93], v[174:177], v[190:193], v[90:93]
	v_mfma_f32_16x16x32_bf16 v[82:85], v[166:169], v[198:201], v[82:85]
	v_mfma_f32_16x16x32_bf16 v[74:77], v[174:177], v[198:201], v[74:77]
	v_mfma_f32_16x16x32_bf16 v[70:73], v[166:169], v[206:209], v[70:73]
	v_mfma_f32_16x16x32_bf16 v[66:69], v[174:177], v[206:209], v[66:69]
	s_barrier
	s_setprio 0
	s_add_i32 s26, s54, s40
	v_lshl_add_u64 v[140:141], s[36:37], 0, v[0:1]
	s_mov_b32 m0, s26
	ds_read_b128 v[178:181], v145 offset:16384
	ds_read_b128 v[182:185], v145 offset:17408
	ds_read_b128 v[186:189], v145 offset:18432
	ds_read_b128 v[190:193], v145 offset:19456
	ds_read_b128 v[194:197], v145 offset:20480
	ds_read_b128 v[198:201], v145 offset:21504
	ds_read_b128 v[202:205], v145 offset:22528
	ds_read_b128 v[206:209], v145 offset:23552
	global_load_lds_dwordx4 v[140:141], off
	s_add_i32 m0, s26, 0x2000
	s_add_u32 s26, s36, 0x30000
	v_lshl_add_u64 v[210:211], s[36:37], 0, v[130:131]
	s_addc_u32 s27, s37, 0
	s_add_i32 s54, s55, s40
	global_load_lds_dwordx4 v[210:211], off
	v_lshl_add_u64 v[212:213], s[26:27], 0, v[0:1]
	s_mov_b32 m0, s54
	v_lshl_add_u64 v[214:215], s[38:39], 0, v[132:133]
	global_load_lds_dwordx4 v[212:213], off
	v_lshl_add_u64 v[212:213], s[26:27], 0, v[130:131]
	s_add_i32 m0, s54, 0x2000
	s_nop 0
	global_load_lds_dwordx4 v[212:213], off
	v_lshl_add_u64 v[212:213], s[38:39], 0, v[134:135]
	s_mov_b32 m0, s19
	s_nop 0
	global_load_lds_dwordx4 v[212:213], off
	s_mov_b32 m0, s42
	s_nop 0
	global_load_lds_dwordx4 v[214:215], off
	s_waitcnt vmcnt(8)
	s_waitcnt lgkmcnt(0)
	s_barrier
; #define PG8_STAGE(bufoff, gbase, voff) do { _Pragma("unroll") for (int _i = 0; _i < 2; ++_i) \
;         __builtin_amdgcn_global_load_lds((const unsigned*)((const char*)(gbase) + (voff)[_i]), (LAS unsigned*)(lds + (bufoff) + ldsw + _i * 8192), 16, 0, 0); } while (0)
; #define PG8_LDA(dst, b, h) do { _Pragma("unroll") for (int m = 0; m < 4; ++m) _Pragma("unroll") for (int k = 0; k < 2; ++k) dst[m][k] = *(const LAS bf16x8*)(lds + PG8_SA(b, h) + aoff + m * 2048 + k * 1024); } while (0)
; #define PG8_LDB(dst, b, h) do { _Pragma("unroll") for (int n = 0; n < 2; ++n) _Pragma("unroll") for (int k = 0; k < 2; ++k) dst[n][k] = *(const LAS bf16x8*)(lds + PG8_SB(b, h) + boff + n * 2048 + k * 1024); } while (0)
; #define PG8_MMA(ai, bj, At, Bt) do { __builtin_amdgcn_s_setprio(1); _Pragma("unroll") for (int m = 0; m < 4; ++m) _Pragma("unroll") for (int n = 0; n < 2; ++n) _Pragma("unroll") for (int k = 0; k < 2; ++k) \
;         acc[ai][bj][m][n] = __builtin_amdgcn_mfma_f32_16x16x32_bf16(Bt[n][k], At[m][k], acc[ai][bj][m][n], 0, 0, 0); __builtin_amdgcn_s_setprio(0); } while (0)
; #define PG8_WAIT_V(n) asm volatile("s_waitcnt vmcnt(" #n ")" ::: "memory")
; #define PG8_WAIT_L(n) asm volatile("s_waitcnt lgkmcnt(" #n ")" ::: "memory")
; #define PG8_BAR __builtin_amdgcn_s_barrier()
; #define PG8_SCHED __builtin_amdgcn_sched_barrier(0)
; template <class Epi, class Sched, bool ALIGN_EPI, bool LAST_FUSED = false, bool PERM = false, bool CARRY = false>
; __device__ __forceinline__ void gemm_phase(LAS unsigned char* lds, const int tid, const int K, const int lda, const int ldb, const Sched& S, const Epi& E) {
;     ...
;             PG8_WAIT_V(8); PG8_WAIT_L(0); PG8_BAR; PG8_MMA(1, 0, At, B0); PG8_MMA(1, 1, At, B1); PG8_BAR; PG8_SCHED;
;             PG8_LDB(B0, 1, 0); PG8_LDB(B1, 1, 1); PG8_SCHED; PG8_LDA(At, 1, 0); PG8_STAGE(PG8_SA(0, 1), a2 + hstepA, voffA);
;             PG8_WAIT_V(8); PG8_WAIT_L(0); PG8_BAR; PG8_MMA(0, 0, At, B0); PG8_MMA(0, 1, At, B1); PG8_BAR; PG8_SCHED;
	v_mfma_f32_16x16x32_bf16 v[62:65], v[146:149], v[178:181], v[62:65]
	s_setprio 1
	v_mfma_f32_16x16x32_bf16 v[58:61], v[154:157], v[178:181], v[58:61]
	v_mfma_f32_16x16x32_bf16 v[54:57], v[146:149], v[186:189], v[54:57]
	v_mfma_f32_16x16x32_bf16 v[46:49], v[154:157], v[186:189], v[46:49]
	v_mfma_f32_16x16x32_bf16 v[38:41], v[146:149], v[194:197], v[38:41]
	v_mfma_f32_16x16x32_bf16 v[30:33], v[154:157], v[194:197], v[30:33]
	v_mfma_f32_16x16x32_bf16 v[22:25], v[146:149], v[202:205], v[22:25]
	v_mfma_f32_16x16x32_bf16 v[14:17], v[154:157], v[202:205], v[14:17]
	v_mfma_f32_16x16x32_bf16 v[62:65], v[150:153], v[182:185], v[62:65]
	v_mfma_f32_16x16x32_bf16 v[58:61], v[158:161], v[182:185], v[58:61]
	v_mfma_f32_16x16x32_bf16 v[54:57], v[150:153], v[190:193], v[54:57]
	v_mfma_f32_16x16x32_bf16 v[46:49], v[158:161], v[190:193], v[46:49]
	v_mfma_f32_16x16x32_bf16 v[38:41], v[150:153], v[198:201], v[38:41]
	v_mfma_f32_16x16x32_bf16 v[30:33], v[158:161], v[198:201], v[30:33]
	v_mfma_f32_16x16x32_bf16 v[22:25], v[150:153], v[206:209], v[22:25]
	v_mfma_f32_16x16x32_bf16 v[14:17], v[158:161], v[206:209], v[14:17]
	s_setprio 0
	s_setprio 1
	v_mfma_f32_16x16x32_bf16 v[50:53], v[162:165], v[178:181], v[50:53]
	v_mfma_f32_16x16x32_bf16 v[42:45], v[170:173], v[178:181], v[42:45]
	v_mfma_f32_16x16x32_bf16 v[34:37], v[162:165], v[186:189], v[34:37]
	v_mfma_f32_16x16x32_bf16 v[26:29], v[170:173], v[186:189], v[26:29]
	v_mfma_f32_16x16x32_bf16 v[18:21], v[162:165], v[194:197], v[18:21]
	v_mfma_f32_16x16x32_bf16 v[10:13], v[170:173], v[194:197], v[10:13]
	v_mfma_f32_16x16x32_bf16 v[6:9], v[162:165], v[202:205], v[6:9]
	v_mfma_f32_16x16x32_bf16 v[2:5], v[170:173], v[202:205], v[2:5]
	v_mfma_f32_16x16x32_bf16 v[50:53], v[166:169], v[182:185], v[50:53]
	v_mfma_f32_16x16x32_bf16 v[42:45], v[174:177], v[182:185], v[42:45]
	v_mfma_f32_16x16x32_bf16 v[34:37], v[166:169], v[190:193], v[34:37]
	v_mfma_f32_16x16x32_bf16 v[26:29], v[174:177], v[190:193], v[26:29]
	v_mfma_f32_16x16x32_bf16 v[18:21], v[166:169], v[198:201], v[18:21]
	v_mfma_f32_16x16x32_bf16 v[10:13], v[174:177], v[198:201], v[10:13]
	v_mfma_f32_16x16x32_bf16 v[6:9], v[166:169], v[206:209], v[6:9]
	v_mfma_f32_16x16x32_bf16 v[2:5], v[174:177], v[206:209], v[2:5]
	s_barrier
	s_setprio 0
	s_add_i32 s54, 0, 0x18000
	s_add_i32 s55, 0, 0x1c000
	v_add_u32_e32 v158, s54, v144
	v_add_u32_e32 v174, s55, v144
	ds_read_b128 v[146:149], v158
	ds_read_b128 v[150:153], v158 offset:1024
	ds_read_b128 v[154:157], v158 offset:2048
	ds_read_b128 v[158:161], v158 offset:3072
	ds_read_b128 v[162:165], v174
	ds_read_b128 v[166:169], v174 offset:1024
	ds_read_b128 v[170:173], v174 offset:2048
	ds_read_b128 v[174:177], v174 offset:3072
	s_add_u32 s26, s38, 0x180000
	s_addc_u32 s27, s39, 0
	s_mov_b32 m0, s43
	v_lshl_add_u64 v[216:217], s[26:27], 0, v[134:135]
	ds_read_b128 v[178:181], v145 offset:32768
	ds_read_b128 v[182:185], v145 offset:33792
	ds_read_b128 v[186:189], v145 offset:34816
	ds_read_b128 v[190:193], v145 offset:35840
	ds_read_b128 v[194:197], v145 offset:36864
	ds_read_b128 v[198:201], v145 offset:37888
	ds_read_b128 v[202:205], v145 offset:38912
	ds_read_b128 v[206:209], v145 offset:39936
	global_load_lds_dwordx4 v[216:217], off
	v_lshl_add_u64 v[216:217], s[26:27], 0, v[132:133]
	s_mov_b32 m0, s44
	s_nop 0
	global_load_lds_dwordx4 v[216:217], off
	s_waitcnt vmcnt(8)
	s_waitcnt lgkmcnt(0)
	s_barrier
	v_mfma_f32_16x16x32_bf16 v[126:129], v[146:149], v[178:181], v[126:129]
	s_setprio 1
	v_mfma_f32_16x16x32_bf16 v[122:125], v[154:157], v[178:181], v[122:125]
	v_mfma_f32_16x16x32_bf16 v[118:121], v[146:149], v[186:189], v[118:121]
	v_mfma_f32_16x16x32_bf16 v[110:113], v[154:157], v[186:189], v[110:113]
	v_mfma_f32_16x16x32_bf16 v[102:105], v[146:149], v[194:197], v[102:105]
	v_mfma_f32_16x16x32_bf16 v[94:97], v[154:157], v[194:197], v[94:97]
	v_mfma_f32_16x16x32_bf16 v[86:89], v[146:149], v[202:205], v[86:89]
	v_mfma_f32_16x16x32_bf16 v[78:81], v[154:157], v[202:205], v[78:81]
	v_mfma_f32_16x16x32_bf16 v[126:129], v[150:153], v[182:185], v[126:129]
	v_mfma_f32_16x16x32_bf16 v[122:125], v[158:161], v[182:185], v[122:125]
	v_mfma_f32_16x16x32_bf16 v[118:121], v[150:153], v[190:193], v[118:121]
	v_mfma_f32_16x16x32_bf16 v[110:113], v[158:161], v[190:193], v[110:113]
	v_mfma_f32_16x16x32_bf16 v[102:105], v[150:153], v[198:201], v[102:105]
	v_mfma_f32_16x16x32_bf16 v[94:97], v[158:161], v[198:201], v[94:97]
	v_mfma_f32_16x16x32_bf16 v[86:89], v[150:153], v[206:209], v[86:89]
	v_mfma_f32_16x16x32_bf16 v[78:81], v[158:161], v[206:209], v[78:81]
	s_setprio 0
	s_setprio 1
	v_mfma_f32_16x16x32_bf16 v[114:117], v[162:165], v[178:181], v[114:117]
	v_mfma_f32_16x16x32_bf16 v[106:109], v[170:173], v[178:181], v[106:109]
	v_mfma_f32_16x16x32_bf16 v[98:101], v[162:165], v[186:189], v[98:101]
	v_mfma_f32_16x16x32_bf16 v[90:93], v[170:173], v[186:189], v[90:93]
	v_mfma_f32_16x16x32_bf16 v[82:85], v[162:165], v[194:197], v[82:85]
	v_mfma_f32_16x16x32_bf16 v[74:77], v[170:173], v[194:197], v[74:77]
	v_mfma_f32_16x16x32_bf16 v[70:73], v[162:165], v[202:205], v[70:73]
	v_mfma_f32_16x16x32_bf16 v[66:69], v[170:173], v[202:205], v[66:69]
	v_mfma_f32_16x16x32_bf16 v[114:117], v[166:169], v[182:185], v[114:117]
	v_mfma_f32_16x16x32_bf16 v[106:109], v[174:177], v[182:185], v[106:109]
	v_mfma_f32_16x16x32_bf16 v[98:101], v[166:169], v[190:193], v[98:101]
	v_mfma_f32_16x16x32_bf16 v[90:93], v[174:177], v[190:193], v[90:93]
	v_mfma_f32_16x16x32_bf16 v[82:85], v[166:169], v[198:201], v[82:85]
	v_mfma_f32_16x16x32_bf16 v[74:77], v[174:177], v[198:201], v[74:77]
	v_mfma_f32_16x16x32_bf16 v[70:73], v[166:169], v[206:209], v[70:73]
	v_mfma_f32_16x16x32_bf16 v[66:69], v[174:177], v[206:209], v[66:69]
	s_barrier
; #define PG8_STAGE(bufoff, gbase, voff) do { _Pragma("unroll") for (int _i = 0; _i < 2; ++_i) \
;         __builtin_amdgcn_global_load_lds((const unsigned*)((const char*)(gbase) + (voff)[_i]), (LAS unsigned*)(lds + (bufoff) + ldsw + _i * 8192), 16, 0, 0); } while (0)
; #define PG8_LDA(dst, b, h) do { _Pragma("unroll") for (int m = 0; m < 4; ++m) _Pragma("unroll") for (int k = 0; k < 2; ++k) dst[m][k] = *(const LAS bf16x8*)(lds + PG8_SA(b, h) + aoff + m * 2048 + k * 1024); } while (0)
; #define PG8_MMA(ai, bj, At, Bt) do { __builtin_amdgcn_s_setprio(1); _Pragma("unroll") for (int m = 0; m < 4; ++m) _Pragma("unroll") for (int n = 0; n < 2; ++n) _Pragma("unroll") for (int k = 0; k < 2; ++k) \
;         acc[ai][bj][m][n] = __builtin_amdgcn_mfma_f32_16x16x32_bf16(Bt[n][k], At[m][k], acc[ai][bj][m][n], 0, 0, 0); __builtin_amdgcn_s_setprio(0); } while (0)
; #define PG8_WAIT_V(n) asm volatile("s_waitcnt vmcnt(" #n ")" ::: "memory")
; #define PG8_WAIT_L(n) asm volatile("s_waitcnt lgkmcnt(" #n ")" ::: "memory")
; #define PG8_BAR __builtin_amdgcn_s_barrier()
; #define PG8_SCHED __builtin_amdgcn_sched_barrier(0)
; template <class Epi, class Sched, bool ALIGN_EPI, bool LAST_FUSED = false, bool PERM = false, bool CARRY = false>
; __device__ __forceinline__ void gemm_phase(LAS unsigned char* lds, const int tid, const int K, const int lda, const int ldb, const Sched& S, const Epi& E) {
;     ...
;             PG8_LDA(At, 1, 1); PG8_STAGE(PG8_SB(1, 0), b3, voffB); PG8_STAGE(PG8_SB(1, 1), b3 + hstepB, voffB); PG8_STAGE(PG8_SA(1, 0), a3, voffA);
;             PG8_WAIT_V(8); PG8_WAIT_L(0); PG8_BAR; PG8_MMA(1, 0, At, B0); PG8_MMA(1, 1, At, B1); PG8_BAR; PG8_SCHED;
;         }
;         if constexpr (ALIGN_EPI) { if (wr == 0) PG8_BAR; }
	s_setprio 0
	s_add_i32 s26, s54, s40
	v_lshl_add_u64 v[140:141], v[140:141], 0, s[68:69]
	s_mov_b32 m0, s26
	ds_read_b128 v[178:181], v145 offset:49152
	ds_read_b128 v[182:185], v145 offset:50176
	ds_read_b128 v[186:189], v145 offset:51200
	ds_read_b128 v[190:193], v145 offset:52224
	ds_read_b128 v[194:197], v145 offset:53248
	ds_read_b128 v[198:201], v145 offset:54272
	ds_read_b128 v[202:205], v145 offset:55296
	ds_read_b128 v[206:209], v145 offset:56320
	global_load_lds_dwordx4 v[140:141], off
	s_add_i32 m0, s26, 0x2000
	s_add_u32 s26, s36, 0x30080
	v_lshl_add_u64 v[140:141], v[210:211], 0, s[68:69]
	s_addc_u32 s27, s37, 0
	s_add_i32 s36, s55, s40
	global_load_lds_dwordx4 v[140:141], off
	v_lshl_add_u64 v[140:141], s[26:27], 0, v[0:1]
	s_mov_b32 m0, s36
	s_nop 0
	global_load_lds_dwordx4 v[140:141], off
	v_lshl_add_u64 v[140:141], s[26:27], 0, v[130:131]
	s_add_i32 m0, s36, 0x2000
	s_nop 0
	global_load_lds_dwordx4 v[140:141], off
	v_lshl_add_u64 v[140:141], v[212:213], 0, s[68:69]
	s_mov_b32 m0, s46
	s_nop 0
	global_load_lds_dwordx4 v[140:141], off
	v_lshl_add_u64 v[140:141], v[214:215], 0, s[68:69]
	s_mov_b32 m0, s47
	s_nop 0
	global_load_lds_dwordx4 v[140:141], off
	s_waitcnt vmcnt(8)
	s_waitcnt lgkmcnt(0)
	s_barrier
	v_mfma_f32_16x16x32_bf16 v[62:65], v[146:149], v[178:181], v[62:65]
	s_setprio 1
	v_mfma_f32_16x16x32_bf16 v[58:61], v[154:157], v[178:181], v[58:61]
	v_mfma_f32_16x16x32_bf16 v[54:57], v[146:149], v[186:189], v[54:57]
	v_mfma_f32_16x16x32_bf16 v[46:49], v[154:157], v[186:189], v[46:49]
	v_mfma_f32_16x16x32_bf16 v[38:41], v[146:149], v[194:197], v[38:41]
	v_mfma_f32_16x16x32_bf16 v[30:33], v[154:157], v[194:197], v[30:33]
	v_mfma_f32_16x16x32_bf16 v[22:25], v[146:149], v[202:205], v[22:25]
	v_mfma_f32_16x16x32_bf16 v[14:17], v[154:157], v[202:205], v[14:17]
	v_mfma_f32_16x16x32_bf16 v[62:65], v[150:153], v[182:185], v[62:65]
	v_mfma_f32_16x16x32_bf16 v[58:61], v[158:161], v[182:185], v[58:61]
	v_mfma_f32_16x16x32_bf16 v[54:57], v[150:153], v[190:193], v[54:57]
	v_mfma_f32_16x16x32_bf16 v[46:49], v[158:161], v[190:193], v[46:49]
	v_mfma_f32_16x16x32_bf16 v[38:41], v[150:153], v[198:201], v[38:41]
	v_mfma_f32_16x16x32_bf16 v[30:33], v[158:161], v[198:201], v[30:33]
	v_mfma_f32_16x16x32_bf16 v[22:25], v[150:153], v[206:209], v[22:25]
	v_mfma_f32_16x16x32_bf16 v[14:17], v[158:161], v[206:209], v[14:17]
	s_setprio 0
	s_setprio 1
	v_mfma_f32_16x16x32_bf16 v[50:53], v[162:165], v[178:181], v[50:53]
	v_mfma_f32_16x16x32_bf16 v[42:45], v[170:173], v[178:181], v[42:45]
	v_mfma_f32_16x16x32_bf16 v[34:37], v[162:165], v[186:189], v[34:37]
	v_mfma_f32_16x16x32_bf16 v[26:29], v[170:173], v[186:189], v[26:29]
	v_mfma_f32_16x16x32_bf16 v[18:21], v[162:165], v[194:197], v[18:21]
	v_mfma_f32_16x16x32_bf16 v[10:13], v[170:173], v[194:197], v[10:13]
	v_mfma_f32_16x16x32_bf16 v[6:9], v[162:165], v[202:205], v[6:9]
	v_mfma_f32_16x16x32_bf16 v[2:5], v[170:173], v[202:205], v[2:5]
	v_mfma_f32_16x16x32_bf16 v[50:53], v[166:169], v[182:185], v[50:53]
	v_mfma_f32_16x16x32_bf16 v[42:45], v[174:177], v[182:185], v[42:45]
	v_mfma_f32_16x16x32_bf16 v[34:37], v[166:169], v[190:193], v[34:37]
	v_mfma_f32_16x16x32_bf16 v[26:29], v[174:177], v[190:193], v[26:29]
	v_mfma_f32_16x16x32_bf16 v[18:21], v[166:169], v[198:201], v[18:21]
	v_mfma_f32_16x16x32_bf16 v[10:13], v[174:177], v[198:201], v[10:13]
	v_mfma_f32_16x16x32_bf16 v[6:9], v[166:169], v[206:209], v[6:9]
	v_mfma_f32_16x16x32_bf16 v[2:5], v[174:177], v[206:209], v[2:5]
	s_barrier
	s_setprio 0
	s_add_i32 s53, s53, 2
	s_add_u32 s13, s13, 0x100
	s_addc_u32 s52, s52, 0
	s_cmp_gt_u32 s53, 9
	s_mov_b64 s[26:27], s[30:31]
	s_cbranch_scc0 .LBB0_705
	s_and_b64 vcc, exec, s[10:11]
	s_cbranch_vccz .LBB0_708
	s_barrier

; #define PG8_STAGE(bufoff, gbase, voff) do { _Pragma("unroll") for (int _i = 0; _i < 2; ++_i) \
;         __builtin_amdgcn_global_load_lds((const unsigned*)((const char*)(gbase) + (voff)[_i]), (LAS unsigned*)(lds + (bufoff) + ldsw + _i * 8192), 16, 0, 0); } while (0)
; #define PG8_LDA(dst, b, h) do { _Pragma("unroll") for (int m = 0; m < 4; ++m) _Pragma("unroll") for (int k = 0; k < 2; ++k) dst[m][k] = *(const LAS bf16x8*)(lds + PG8_SA(b, h) + aoff + m * 2048 + k * 1024); } while (0)
; #define PG8_LDB(dst, b, h) do { _Pragma("unroll") for (int n = 0; n < 2; ++n) _Pragma("unroll") for (int k = 0; k < 2; ++k) dst[n][k] = *(const LAS bf16x8*)(lds + PG8_SB(b, h) + boff + n * 2048 + k * 1024); } while (0)
; #define PG8_MMA(ai, bj, At, Bt) do { __builtin_amdgcn_s_setprio(1); _Pragma("unroll") for (int m = 0; m < 4; ++m) _Pragma("unroll") for (int n = 0; n < 2; ++n) _Pragma("unroll") for (int k = 0; k < 2; ++k) \
;         acc[ai][bj][m][n] = __builtin_amdgcn_mfma_f32_16x16x32_bf16(Bt[n][k], At[m][k], acc[ai][bj][m][n], 0, 0, 0); __builtin_amdgcn_s_setprio(0); } while (0)
; #define PG8_WAIT_V(n) asm volatile("s_waitcnt vmcnt(" #n ")" ::: "memory")
; #define PG8_WAIT_L(n) asm volatile("s_waitcnt lgkmcnt(" #n ")" ::: "memory")
; template <class Epi, class Sched, bool ALIGN_EPI, bool LAST_FUSED = false, bool PERM = false, bool CARRY = false>
; __device__ __forceinline__ void gemm_phase(LAS unsigned char* lds, const int tid, const int K, const int lda, const int ldb, const Sched& S, const Epi& E) {
;     ...
;         for (int t = 0; t < nt; t += 2) {
;             const bool last = (t == nt - 2);
;             const char* a1 = cA + (size_t)(t + 1) * kstep;
;             const char* a2 = last ? nA : cA + (size_t)(t + 2) * kstep; const char* b2 = last ? nB : cB + (size_t)(t + 2) * kstep;
;             const char* a3 = a2 + kstep; const char* b3 = b2 + kstep;
;             PG8_LDB(B0, 0, 0); PG8_LDB(B1, 0, 1); PG8_SCHED; PG8_LDA(At, 0, 0); PG8_STAGE(PG8_SA(1, 1), a1 + hstepA, voffA);
;             PG8_WAIT_V(8); PG8_WAIT_L(0); PG8_BAR; PG8_MMA(0, 0, At, B0); PG8_MMA(0, 1, At, B1); PG8_BAR; PG8_SCHED;
;             PG8_LDA(At, 0, 1); PG8_STAGE(PG8_SB(0, 0), b2, voffB); PG8_STAGE(PG8_SB(0, 1), b2 + hstepB, voffB); PG8_STAGE(PG8_SA(0, 0), a2, voffA);
;             PG8_WAIT_V(8); PG8_WAIT_L(0); PG8_BAR; PG8_MMA(1, 0, At, B0); PG8_MMA(1, 1, At, B1); PG8_BAR; PG8_SCHED;
.LBB0_838:
	s_add_u32 s6, s4, 0xfff80080
	s_addc_u32 s7, s5, -1
	s_add_i32 s29, 0, 0x10000
	s_cmp_eq_u32 s28, 28
	s_cselect_b32 s37, s43, s7
	s_cselect_b32 s36, s42, s6
	v_add_u32_e32 v140, s29, v146
	s_cselect_b32 s7, s71, s23
	s_cselect_b32 s6, s70, s22
	s_add_i32 s31, 0, 0x14000
	ds_read_b128 v[136:139], v140
	ds_read_b128 v[148:151], v140 offset:1024
	ds_read_b128 v[152:155], v140 offset:2048
	ds_read_b128 v[156:159], v140 offset:3072
	v_add_u32_e32 v140, s31, v146
	ds_read_b128 v[160:163], v140
	ds_read_b128 v[164:167], v140 offset:1024
	ds_read_b128 v[168:171], v140 offset:2048
	ds_read_b128 v[172:175], v140 offset:3072
	v_lshl_add_u64 v[140:141], s[4:5], 0, v[132:133]
	s_add_i32 m0, s50, 0xc000
	ds_read_b128 v[176:179], v147
	ds_read_b128 v[180:183], v147 offset:1024
	ds_read_b128 v[184:187], v147 offset:2048
	ds_read_b128 v[188:191], v147 offset:3072
	ds_read_b128 v[192:195], v147 offset:4096
	ds_read_b128 v[196:199], v147 offset:5120
	ds_read_b128 v[200:203], v147 offset:6144
	ds_read_b128 v[204:207], v147 offset:7168
	global_load_lds_dwordx4 v[140:141], off
	v_lshl_add_u64 v[140:141], s[4:5], 0, v[134:135]
	s_add_i32 m0, s50, 0xe000
	s_nop 0
	global_load_lds_dwordx4 v[140:141], off
	s_waitcnt vmcnt(8)
	s_waitcnt lgkmcnt(0)
	s_barrier
	v_mfma_f32_16x16x32_bf16 v[126:129], v[136:139], v[176:179], v[126:129]
	s_setprio 1
	v_mfma_f32_16x16x32_bf16 v[122:125], v[152:155], v[176:179], v[122:125]
	v_mfma_f32_16x16x32_bf16 v[110:113], v[136:139], v[184:187], v[110:113]
	v_mfma_f32_16x16x32_bf16 v[106:109], v[152:155], v[184:187], v[106:109]
	v_mfma_f32_16x16x32_bf16 v[94:97], v[136:139], v[192:195], v[94:97]
	v_mfma_f32_16x16x32_bf16 v[90:93], v[152:155], v[192:195], v[90:93]
	v_mfma_f32_16x16x32_bf16 v[78:81], v[136:139], v[200:203], v[78:81]
	v_mfma_f32_16x16x32_bf16 v[74:77], v[152:155], v[200:203], v[74:77]
	v_mfma_f32_16x16x32_bf16 v[126:129], v[148:151], v[180:183], v[126:129]
	v_mfma_f32_16x16x32_bf16 v[122:125], v[156:159], v[180:183], v[122:125]
	v_mfma_f32_16x16x32_bf16 v[110:113], v[148:151], v[188:191], v[110:113]
	v_mfma_f32_16x16x32_bf16 v[106:109], v[156:159], v[188:191], v[106:109]
	v_mfma_f32_16x16x32_bf16 v[94:97], v[148:151], v[196:199], v[94:97]
	v_mfma_f32_16x16x32_bf16 v[90:93], v[156:159], v[196:199], v[90:93]
	v_mfma_f32_16x16x32_bf16 v[78:81], v[148:151], v[204:207], v[78:81]
	v_mfma_f32_16x16x32_bf16 v[74:77], v[156:159], v[204:207], v[74:77]
	s_setprio 0
	s_setprio 1
	v_mfma_f32_16x16x32_bf16 v[118:121], v[160:163], v[176:179], v[118:121]
	v_mfma_f32_16x16x32_bf16 v[114:117], v[168:171], v[176:179], v[114:117]
	v_mfma_f32_16x16x32_bf16 v[102:105], v[160:163], v[184:187], v[102:105]
	v_mfma_f32_16x16x32_bf16 v[98:101], v[168:171], v[184:187], v[98:101]
	v_mfma_f32_16x16x32_bf16 v[86:89], v[160:163], v[192:195], v[86:89]
	v_mfma_f32_16x16x32_bf16 v[82:85], v[168:171], v[192:195], v[82:85]
	v_mfma_f32_16x16x32_bf16 v[70:73], v[160:163], v[200:203], v[70:73]
	v_mfma_f32_16x16x32_bf16 v[66:69], v[168:171], v[200:203], v[66:69]
	v_mfma_f32_16x16x32_bf16 v[118:121], v[164:167], v[180:183], v[118:121]
	v_mfma_f32_16x16x32_bf16 v[114:117], v[172:175], v[180:183], v[114:117]
	v_mfma_f32_16x16x32_bf16 v[102:105], v[164:167], v[188:191], v[102:105]
	v_mfma_f32_16x16x32_bf16 v[98:101], v[172:175], v[188:191], v[98:101]
	v_mfma_f32_16x16x32_bf16 v[86:89], v[164:167], v[196:199], v[86:89]
	v_mfma_f32_16x16x32_bf16 v[82:85], v[172:175], v[196:199], v[82:85]
	v_mfma_f32_16x16x32_bf16 v[70:73], v[164:167], v[204:207], v[70:73]
	v_mfma_f32_16x16x32_bf16 v[66:69], v[172:175], v[204:207], v[66:69]
	s_barrier
	s_setprio 0
	s_add_i32 s29, s29, s49
	v_lshl_add_u64 v[140:141], s[6:7], 0, v[0:1]
	s_mov_b32 m0, s29
	ds_read_b128 v[176:179], v147 offset:16384
	ds_read_b128 v[180:183], v147 offset:17408
	ds_read_b128 v[184:187], v147 offset:18432
	ds_read_b128 v[188:191], v147 offset:19456
	ds_read_b128 v[192:195], v147 offset:20480
	ds_read_b128 v[196:199], v147 offset:21504
	ds_read_b128 v[200:203], v147 offset:22528
	ds_read_b128 v[204:207], v147 offset:23552
	global_load_lds_dwordx4 v[140:141], off
	s_add_i32 m0, s29, 0x2000
	s_add_u32 s44, s6, 0x80000
	v_lshl_add_u64 v[208:209], s[6:7], 0, v[130:131]
	s_addc_u32 s45, s7, 0
	s_add_i32 s29, s31, s49
	global_load_lds_dwordx4 v[208:209], off
	v_lshl_add_u64 v[210:211], s[44:45], 0, v[0:1]
	s_mov_b32 m0, s29
	v_lshl_add_u64 v[212:213], s[36:37], 0, v[130:131]
	global_load_lds_dwordx4 v[210:211], off
	v_lshl_add_u64 v[210:211], s[44:45], 0, v[130:131]
	s_add_i32 m0, s29, 0x2000
	s_nop 0
	global_load_lds_dwordx4 v[210:211], off
	v_lshl_add_u64 v[210:211], s[36:37], 0, v[0:1]
	s_mov_b32 m0, s50
	s_nop 0
	global_load_lds_dwordx4 v[210:211], off
	s_mov_b32 m0, s51
	s_nop 0
	global_load_lds_dwordx4 v[212:213], off
	s_waitcnt vmcnt(8)
	s_waitcnt lgkmcnt(0)
	s_barrier
; #define PG8_STAGE(bufoff, gbase, voff) do { _Pragma("unroll") for (int _i = 0; _i < 2; ++_i) \
;         __builtin_amdgcn_global_load_lds((const unsigned*)((const char*)(gbase) + (voff)[_i]), (LAS unsigned*)(lds + (bufoff) + ldsw + _i * 8192), 16, 0, 0); } while (0)
; #define PG8_LDA(dst, b, h) do { _Pragma("unroll") for (int m = 0; m < 4; ++m) _Pragma("unroll") for (int k = 0; k < 2; ++k) dst[m][k] = *(const LAS bf16x8*)(lds + PG8_SA(b, h) + aoff + m * 2048 + k * 1024); } while (0)
; #define PG8_LDB(dst, b, h) do { _Pragma("unroll") for (int n = 0; n < 2; ++n) _Pragma("unroll") for (int k = 0; k < 2; ++k) dst[n][k] = *(const LAS bf16x8*)(lds + PG8_SB(b, h) + boff + n * 2048 + k * 1024); } while (0)
; #define PG8_MMA(ai, bj, At, Bt) do { __builtin_amdgcn_s_setprio(1); _Pragma("unroll") for (int m = 0; m < 4; ++m) _Pragma("unroll") for (int n = 0; n < 2; ++n) _Pragma("unroll") for (int k = 0; k < 2; ++k) \
;         acc[ai][bj][m][n] = __builtin_amdgcn_mfma_f32_16x16x32_bf16(Bt[n][k], At[m][k], acc[ai][bj][m][n], 0, 0, 0); __builtin_amdgcn_s_setprio(0); } while (0)
; #define PG8_WAIT_V(n) asm volatile("s_waitcnt vmcnt(" #n ")" ::: "memory")
; #define PG8_WAIT_L(n) asm volatile("s_waitcnt lgkmcnt(" #n ")" ::: "memory")
; #define PG8_BAR __builtin_amdgcn_s_barrier()
; #define PG8_SCHED __builtin_amdgcn_sched_barrier(0)
; template <class Epi, class Sched, bool ALIGN_EPI, bool LAST_FUSED = false, bool PERM = false, bool CARRY = false>
; __device__ __forceinline__ void gemm_phase(LAS unsigned char* lds, const int tid, const int K, const int lda, const int ldb, const Sched& S, const Epi& E) {
;     ...
;             PG8_WAIT_V(8); PG8_WAIT_L(0); PG8_BAR; PG8_MMA(1, 0, At, B0); PG8_MMA(1, 1, At, B1); PG8_BAR; PG8_SCHED;
;             PG8_LDB(B0, 1, 0); PG8_LDB(B1, 1, 1); PG8_SCHED; PG8_LDA(At, 1, 0); PG8_STAGE(PG8_SA(0, 1), a2 + hstepA, voffA);
;             PG8_WAIT_V(8); PG8_WAIT_L(0); PG8_BAR; PG8_MMA(0, 0, At, B0); PG8_MMA(0, 1, At, B1); PG8_BAR; PG8_SCHED;
	v_mfma_f32_16x16x32_bf16 v[62:65], v[136:139], v[176:179], v[62:65]
	s_setprio 1
	v_mfma_f32_16x16x32_bf16 v[58:61], v[152:155], v[176:179], v[58:61]
	v_mfma_f32_16x16x32_bf16 v[46:49], v[136:139], v[184:187], v[46:49]
	v_mfma_f32_16x16x32_bf16 v[42:45], v[152:155], v[184:187], v[42:45]
	v_mfma_f32_16x16x32_bf16 v[30:33], v[136:139], v[192:195], v[30:33]
	v_mfma_f32_16x16x32_bf16 v[26:29], v[152:155], v[192:195], v[26:29]
	v_mfma_f32_16x16x32_bf16 v[14:17], v[136:139], v[200:203], v[14:17]
	v_mfma_f32_16x16x32_bf16 v[10:13], v[152:155], v[200:203], v[10:13]
	v_mfma_f32_16x16x32_bf16 v[62:65], v[148:151], v[180:183], v[62:65]
	v_mfma_f32_16x16x32_bf16 v[58:61], v[156:159], v[180:183], v[58:61]
	v_mfma_f32_16x16x32_bf16 v[46:49], v[148:151], v[188:191], v[46:49]
	v_mfma_f32_16x16x32_bf16 v[42:45], v[156:159], v[188:191], v[42:45]
	v_mfma_f32_16x16x32_bf16 v[30:33], v[148:151], v[196:199], v[30:33]
	v_mfma_f32_16x16x32_bf16 v[26:29], v[156:159], v[196:199], v[26:29]
	v_mfma_f32_16x16x32_bf16 v[14:17], v[148:151], v[204:207], v[14:17]
	v_mfma_f32_16x16x32_bf16 v[10:13], v[156:159], v[204:207], v[10:13]
	s_setprio 0
	s_setprio 1
	v_mfma_f32_16x16x32_bf16 v[54:57], v[160:163], v[176:179], v[54:57]
	v_mfma_f32_16x16x32_bf16 v[50:53], v[168:171], v[176:179], v[50:53]
	v_mfma_f32_16x16x32_bf16 v[38:41], v[160:163], v[184:187], v[38:41]
	v_mfma_f32_16x16x32_bf16 v[34:37], v[168:171], v[184:187], v[34:37]
	v_mfma_f32_16x16x32_bf16 v[22:25], v[160:163], v[192:195], v[22:25]
	v_mfma_f32_16x16x32_bf16 v[18:21], v[168:171], v[192:195], v[18:21]
	v_mfma_f32_16x16x32_bf16 v[6:9], v[160:163], v[200:203], v[6:9]
	v_mfma_f32_16x16x32_bf16 v[2:5], v[168:171], v[200:203], v[2:5]
	v_mfma_f32_16x16x32_bf16 v[54:57], v[164:167], v[180:183], v[54:57]
	v_mfma_f32_16x16x32_bf16 v[50:53], v[172:175], v[180:183], v[50:53]
	v_mfma_f32_16x16x32_bf16 v[38:41], v[164:167], v[188:191], v[38:41]
	v_mfma_f32_16x16x32_bf16 v[34:37], v[172:175], v[188:191], v[34:37]
	v_mfma_f32_16x16x32_bf16 v[22:25], v[164:167], v[196:199], v[22:25]
	v_mfma_f32_16x16x32_bf16 v[18:21], v[172:175], v[196:199], v[18:21]
	v_mfma_f32_16x16x32_bf16 v[6:9], v[164:167], v[204:207], v[6:9]
	v_mfma_f32_16x16x32_bf16 v[2:5], v[172:175], v[204:207], v[2:5]
	s_barrier
	s_setprio 0
	s_add_i32 s29, 0, 0x18000
	s_add_i32 s31, 0, 0x1c000
	v_add_u32_e32 v156, s29, v146
	v_add_u32_e32 v172, s31, v146
	ds_read_b128 v[136:139], v156
	ds_read_b128 v[148:151], v156 offset:1024
	ds_read_b128 v[152:155], v156 offset:2048
	ds_read_b128 v[156:159], v156 offset:3072
	ds_read_b128 v[160:163], v172
	ds_read_b128 v[164:167], v172 offset:1024
	ds_read_b128 v[168:171], v172 offset:2048
	ds_read_b128 v[172:175], v172 offset:3072
	s_add_u32 s36, s36, 0x80000
	s_addc_u32 s37, s37, 0
	s_mov_b32 m0, s52
	v_lshl_add_u64 v[214:215], s[36:37], 0, v[0:1]
	ds_read_b128 v[176:179], v147 offset:32768
	ds_read_b128 v[180:183], v147 offset:33792
	ds_read_b128 v[184:187], v147 offset:34816
	ds_read_b128 v[188:191], v147 offset:35840
	ds_read_b128 v[192:195], v147 offset:36864
	ds_read_b128 v[196:199], v147 offset:37888
	ds_read_b128 v[200:203], v147 offset:38912
	ds_read_b128 v[204:207], v147 offset:39936
	global_load_lds_dwordx4 v[214:215], off
	v_lshl_add_u64 v[214:215], s[36:37], 0, v[130:131]
	s_mov_b32 m0, s53
	s_nop 0
	global_load_lds_dwordx4 v[214:215], off
	s_waitcnt vmcnt(8)
	s_waitcnt lgkmcnt(0)
	s_barrier
	v_mfma_f32_16x16x32_bf16 v[126:129], v[136:139], v[176:179], v[126:129]
	s_setprio 1
	v_mfma_f32_16x16x32_bf16 v[122:125], v[152:155], v[176:179], v[122:125]
	v_mfma_f32_16x16x32_bf16 v[110:113], v[136:139], v[184:187], v[110:113]
	v_mfma_f32_16x16x32_bf16 v[106:109], v[152:155], v[184:187], v[106:109]
	v_mfma_f32_16x16x32_bf16 v[94:97], v[136:139], v[192:195], v[94:97]
	v_mfma_f32_16x16x32_bf16 v[90:93], v[152:155], v[192:195], v[90:93]
	v_mfma_f32_16x16x32_bf16 v[78:81], v[136:139], v[200:203], v[78:81]
	v_mfma_f32_16x16x32_bf16 v[74:77], v[152:155], v[200:203], v[74:77]
	v_mfma_f32_16x16x32_bf16 v[126:129], v[148:151], v[180:183], v[126:129]
	v_mfma_f32_16x16x32_bf16 v[122:125], v[156:159], v[180:183], v[122:125]
	v_mfma_f32_16x16x32_bf16 v[110:113], v[148:151], v[188:191], v[110:113]
	v_mfma_f32_16x16x32_bf16 v[106:109], v[156:159], v[188:191], v[106:109]
	v_mfma_f32_16x16x32_bf16 v[94:97], v[148:151], v[196:199], v[94:97]
	v_mfma_f32_16x16x32_bf16 v[90:93], v[156:159], v[196:199], v[90:93]
	v_mfma_f32_16x16x32_bf16 v[78:81], v[148:151], v[204:207], v[78:81]
	v_mfma_f32_16x16x32_bf16 v[74:77], v[156:159], v[204:207], v[74:77]
	s_setprio 0
	s_setprio 1
	v_mfma_f32_16x16x32_bf16 v[118:121], v[160:163], v[176:179], v[118:121]
	v_mfma_f32_16x16x32_bf16 v[114:117], v[168:171], v[176:179], v[114:117]
	v_mfma_f32_16x16x32_bf16 v[102:105], v[160:163], v[184:187], v[102:105]
	v_mfma_f32_16x16x32_bf16 v[98:101], v[168:171], v[184:187], v[98:101]
	v_mfma_f32_16x16x32_bf16 v[86:89], v[160:163], v[192:195], v[86:89]
	v_mfma_f32_16x16x32_bf16 v[82:85], v[168:171], v[192:195], v[82:85]
	v_mfma_f32_16x16x32_bf16 v[70:73], v[160:163], v[200:203], v[70:73]
	v_mfma_f32_16x16x32_bf16 v[66:69], v[168:171], v[200:203], v[66:69]
	v_mfma_f32_16x16x32_bf16 v[118:121], v[164:167], v[180:183], v[118:121]
	v_mfma_f32_16x16x32_bf16 v[114:117], v[172:175], v[180:183], v[114:117]
	v_mfma_f32_16x16x32_bf16 v[102:105], v[164:167], v[188:191], v[102:105]
	v_mfma_f32_16x16x32_bf16 v[98:101], v[172:175], v[188:191], v[98:101]
	v_mfma_f32_16x16x32_bf16 v[86:89], v[164:167], v[196:199], v[86:89]
	v_mfma_f32_16x16x32_bf16 v[82:85], v[172:175], v[196:199], v[82:85]
	v_mfma_f32_16x16x32_bf16 v[70:73], v[164:167], v[204:207], v[70:73]
	v_mfma_f32_16x16x32_bf16 v[66:69], v[172:175], v[204:207], v[66:69]
	s_barrier
; #define PG8_STAGE(bufoff, gbase, voff) do { _Pragma("unroll") for (int _i = 0; _i < 2; ++_i) \
;         __builtin_amdgcn_global_load_lds((const unsigned*)((const char*)(gbase) + (voff)[_i]), (LAS unsigned*)(lds + (bufoff) + ldsw + _i * 8192), 16, 0, 0); } while (0)
; #define PG8_LDA(dst, b, h) do { _Pragma("unroll") for (int m = 0; m < 4; ++m) _Pragma("unroll") for (int k = 0; k < 2; ++k) dst[m][k] = *(const LAS bf16x8*)(lds + PG8_SA(b, h) + aoff + m * 2048 + k * 1024); } while (0)
; #define PG8_MMA(ai, bj, At, Bt) do { __builtin_amdgcn_s_setprio(1); _Pragma("unroll") for (int m = 0; m < 4; ++m) _Pragma("unroll") for (int n = 0; n < 2; ++n) _Pragma("unroll") for (int k = 0; k < 2; ++k) \
;         acc[ai][bj][m][n] = __builtin_amdgcn_mfma_f32_16x16x32_bf16(Bt[n][k], At[m][k], acc[ai][bj][m][n], 0, 0, 0); __builtin_amdgcn_s_setprio(0); } while (0)
; #define PG8_WAIT_V(n) asm volatile("s_waitcnt vmcnt(" #n ")" ::: "memory")
; #define PG8_WAIT_L(n) asm volatile("s_waitcnt lgkmcnt(" #n ")" ::: "memory")
; #define PG8_BAR __builtin_amdgcn_s_barrier()
; #define PG8_SCHED __builtin_amdgcn_sched_barrier(0)
; template <class Epi, class Sched, bool ALIGN_EPI, bool LAST_FUSED = false, bool PERM = false, bool CARRY = false>
; __device__ __forceinline__ void gemm_phase(LAS unsigned char* lds, const int tid, const int K, const int lda, const int ldb, const Sched& S, const Epi& E) {
;     ...
;             PG8_LDA(At, 1, 1); PG8_STAGE(PG8_SB(1, 0), b3, voffB); PG8_STAGE(PG8_SB(1, 1), b3 + hstepB, voffB); PG8_STAGE(PG8_SA(1, 0), a3, voffA);
;             PG8_WAIT_V(8); PG8_WAIT_L(0); PG8_BAR; PG8_MMA(1, 0, At, B0); PG8_MMA(1, 1, At, B1); PG8_BAR; PG8_SCHED;
;         }
;         if constexpr (ALIGN_EPI) { if (wr == 0) PG8_BAR; }
	s_setprio 0
	s_add_i32 s29, s29, s49
	v_lshl_add_u64 v[140:141], v[140:141], 0, s[68:69]
	s_mov_b32 m0, s29
	ds_read_b128 v[176:179], v147 offset:49152
	ds_read_b128 v[180:183], v147 offset:50176
	ds_read_b128 v[184:187], v147 offset:51200
	ds_read_b128 v[188:191], v147 offset:52224
	ds_read_b128 v[192:195], v147 offset:53248
	ds_read_b128 v[196:199], v147 offset:54272
	ds_read_b128 v[200:203], v147 offset:55296
	ds_read_b128 v[204:207], v147 offset:56320
	global_load_lds_dwordx4 v[140:141], off
	s_add_i32 m0, s29, 0x2000
	s_add_u32 s6, s6, 0x80080
	v_lshl_add_u64 v[140:141], v[208:209], 0, s[68:69]
	s_addc_u32 s7, s7, 0
	s_add_i32 s29, s31, s49
	global_load_lds_dwordx4 v[140:141], off
	v_lshl_add_u64 v[140:141], s[6:7], 0, v[0:1]
	s_mov_b32 m0, s29
	s_nop 0
	global_load_lds_dwordx4 v[140:141], off
	v_lshl_add_u64 v[140:141], s[6:7], 0, v[130:131]
	s_add_i32 m0, s29, 0x2000
	s_nop 0
	global_load_lds_dwordx4 v[140:141], off
	v_lshl_add_u64 v[140:141], v[210:211], 0, s[68:69]
	s_mov_b32 m0, s55
	s_nop 0
	global_load_lds_dwordx4 v[140:141], off
	v_lshl_add_u64 v[140:141], v[212:213], 0, s[68:69]
	s_mov_b32 m0, s56
	s_nop 0
	global_load_lds_dwordx4 v[140:141], off
	s_waitcnt vmcnt(8)
	s_waitcnt lgkmcnt(0)
	s_barrier
	v_mfma_f32_16x16x32_bf16 v[62:65], v[136:139], v[176:179], v[62:65]
	s_setprio 1
	v_mfma_f32_16x16x32_bf16 v[58:61], v[152:155], v[176:179], v[58:61]
	v_mfma_f32_16x16x32_bf16 v[46:49], v[136:139], v[184:187], v[46:49]
	v_mfma_f32_16x16x32_bf16 v[42:45], v[152:155], v[184:187], v[42:45]
	v_mfma_f32_16x16x32_bf16 v[30:33], v[136:139], v[192:195], v[30:33]
	v_mfma_f32_16x16x32_bf16 v[26:29], v[152:155], v[192:195], v[26:29]
	v_mfma_f32_16x16x32_bf16 v[14:17], v[136:139], v[200:203], v[14:17]
	v_mfma_f32_16x16x32_bf16 v[10:13], v[152:155], v[200:203], v[10:13]
	v_mfma_f32_16x16x32_bf16 v[62:65], v[148:151], v[180:183], v[62:65]
	v_mfma_f32_16x16x32_bf16 v[58:61], v[156:159], v[180:183], v[58:61]
	v_mfma_f32_16x16x32_bf16 v[46:49], v[148:151], v[188:191], v[46:49]
	v_mfma_f32_16x16x32_bf16 v[42:45], v[156:159], v[188:191], v[42:45]
	v_mfma_f32_16x16x32_bf16 v[30:33], v[148:151], v[196:199], v[30:33]
	v_mfma_f32_16x16x32_bf16 v[26:29], v[156:159], v[196:199], v[26:29]
	v_mfma_f32_16x16x32_bf16 v[14:17], v[148:151], v[204:207], v[14:17]
	v_mfma_f32_16x16x32_bf16 v[10:13], v[156:159], v[204:207], v[10:13]
	s_setprio 0
	s_setprio 1
	v_mfma_f32_16x16x32_bf16 v[54:57], v[160:163], v[176:179], v[54:57]
	v_mfma_f32_16x16x32_bf16 v[50:53], v[168:171], v[176:179], v[50:53]
	v_mfma_f32_16x16x32_bf16 v[38:41], v[160:163], v[184:187], v[38:41]
	v_mfma_f32_16x16x32_bf16 v[34:37], v[168:171], v[184:187], v[34:37]
	v_mfma_f32_16x16x32_bf16 v[22:25], v[160:163], v[192:195], v[22:25]
	v_mfma_f32_16x16x32_bf16 v[18:21], v[168:171], v[192:195], v[18:21]
	v_mfma_f32_16x16x32_bf16 v[6:9], v[160:163], v[200:203], v[6:9]
	v_mfma_f32_16x16x32_bf16 v[2:5], v[168:171], v[200:203], v[2:5]
	v_mfma_f32_16x16x32_bf16 v[54:57], v[164:167], v[180:183], v[54:57]
	v_mfma_f32_16x16x32_bf16 v[50:53], v[172:175], v[180:183], v[50:53]
	v_mfma_f32_16x16x32_bf16 v[38:41], v[164:167], v[188:191], v[38:41]
	v_mfma_f32_16x16x32_bf16 v[34:37], v[172:175], v[188:191], v[34:37]
	v_mfma_f32_16x16x32_bf16 v[22:25], v[164:167], v[196:199], v[22:25]
	v_mfma_f32_16x16x32_bf16 v[18:21], v[172:175], v[196:199], v[18:21]
	v_mfma_f32_16x16x32_bf16 v[6:9], v[164:167], v[204:207], v[6:9]
	v_mfma_f32_16x16x32_bf16 v[2:5], v[172:175], v[204:207], v[2:5]
	s_barrier
	s_setprio 0
	s_add_i32 s28, s28, 2
	s_add_u32 s4, s4, 0x100
	s_addc_u32 s5, s5, 0
	s_add_u32 s22, s22, 0x100
	s_addc_u32 s23, s23, 0
	s_cmp_gt_u32 s28, 29
	s_cbranch_scc0 .LBB0_838
	s_and_b64 vcc, exec, s[26:27]
	s_cbranch_vccz .LBB0_841
	s_barrier

; #define PG8_STAGE(bufoff, gbase, voff) do { _Pragma("unroll") for (int _i = 0; _i < 2; ++_i) \
;         __builtin_amdgcn_global_load_lds((const unsigned*)((const char*)(gbase) + (voff)[_i]), (LAS unsigned*)(lds + (bufoff) + ldsw + _i * 8192), 16, 0, 0); } while (0)
; #define PG8_LDA(dst, b, h) do { _Pragma("unroll") for (int m = 0; m < 4; ++m) _Pragma("unroll") for (int k = 0; k < 2; ++k) dst[m][k] = *(const LAS bf16x8*)(lds + PG8_SA(b, h) + aoff + m * 2048 + k * 1024); } while (0)
; #define PG8_LDB(dst, b, h) do { _Pragma("unroll") for (int n = 0; n < 2; ++n) _Pragma("unroll") for (int k = 0; k < 2; ++k) dst[n][k] = *(const LAS bf16x8*)(lds + PG8_SB(b, h) + boff + n * 2048 + k * 1024); } while (0)
; #define PG8_MMA(ai, bj, At, Bt) do { __builtin_amdgcn_s_setprio(1); _Pragma("unroll") for (int m = 0; m < 4; ++m) _Pragma("unroll") for (int n = 0; n < 2; ++n) _Pragma("unroll") for (int k = 0; k < 2; ++k) \
;         acc[ai][bj][m][n] = __builtin_amdgcn_mfma_f32_16x16x32_bf16(Bt[n][k], At[m][k], acc[ai][bj][m][n], 0, 0, 0); __builtin_amdgcn_s_setprio(0); } while (0)
; #define PG8_WAIT_V(n) asm volatile("s_waitcnt vmcnt(" #n ")" ::: "memory")
; #define PG8_WAIT_L(n) asm volatile("s_waitcnt lgkmcnt(" #n ")" ::: "memory")
; template <class Epi, class Sched, bool ALIGN_EPI, bool LAST_FUSED = false, bool PERM = false, bool CARRY = false>
; __device__ __forceinline__ void gemm_phase(LAS unsigned char* lds, const int tid, const int K, const int lda, const int ldb, const Sched& S, const Epi& E) {
;     ...
;         for (int t = 0; t < nt; t += 2) {
;             const bool last = (t == nt - 2);
;             const char* a1 = cA + (size_t)(t + 1) * kstep;
;             const char* a2 = last ? nA : cA + (size_t)(t + 2) * kstep; const char* b2 = last ? nB : cB + (size_t)(t + 2) * kstep;
;             const char* a3 = a2 + kstep; const char* b3 = b2 + kstep;
;             PG8_LDB(B0, 0, 0); PG8_LDB(B1, 0, 1); PG8_SCHED; PG8_LDA(At, 0, 0); PG8_STAGE(PG8_SA(1, 1), a1 + hstepA, voffA);
;             PG8_WAIT_V(8); PG8_WAIT_L(0); PG8_BAR; PG8_MMA(0, 0, At, B0); PG8_MMA(0, 1, At, B1); PG8_BAR; PG8_SCHED;
;             PG8_LDA(At, 0, 1); PG8_STAGE(PG8_SB(0, 0), b2, voffB); PG8_STAGE(PG8_SB(0, 1), b2 + hstepB, voffB); PG8_STAGE(PG8_SA(0, 0), a2, voffA);
;             PG8_WAIT_V(8); PG8_WAIT_L(0); PG8_BAR; PG8_MMA(1, 0, At, B0); PG8_MMA(1, 1, At, B1); PG8_BAR; PG8_SCHED;
.LBB0_1077:
	s_add_u32 s23, s26, 0xfff80080
	s_addc_u32 s28, s27, -1
	s_add_i32 s29, 0, 0x10000
	s_cmp_eq_u32 s15, 28
	s_cselect_b32 s37, s17, s28
	s_cselect_b32 s36, s16, s23
	s_cselect_b32 s31, s19, s13
	s_cselect_b32 s30, s18, s5
	s_add_i32 s23, 0, 0x14000
	v_add_u32_e32 v152, s29, v142
	v_add_u32_e32 v168, s23, v142
	ds_read_b128 v[136:139], v152
	ds_read_b128 v[144:147], v152 offset:1024
	ds_read_b128 v[148:151], v152 offset:2048
	ds_read_b128 v[152:155], v152 offset:3072
	ds_read_b128 v[156:159], v168
	ds_read_b128 v[160:163], v168 offset:1024
	ds_read_b128 v[164:167], v168 offset:2048
	ds_read_b128 v[168:171], v168 offset:3072
	v_lshl_add_u64 v[204:205], s[26:27], 0, v[132:133]
	s_add_i32 m0, s46, 0xc000
	ds_read_b128 v[172:175], v143
	ds_read_b128 v[176:179], v143 offset:1024
	ds_read_b128 v[180:183], v143 offset:2048
	ds_read_b128 v[184:187], v143 offset:3072
	ds_read_b128 v[188:191], v143 offset:4096
	ds_read_b128 v[192:195], v143 offset:5120
	ds_read_b128 v[196:199], v143 offset:6144
	ds_read_b128 v[200:203], v143 offset:7168
	global_load_lds_dwordx4 v[204:205], off
	v_lshl_add_u64 v[204:205], s[26:27], 0, v[134:135]
	s_add_i32 m0, s46, 0xe000
	s_nop 0
	global_load_lds_dwordx4 v[204:205], off
	s_waitcnt vmcnt(8)
	s_waitcnt lgkmcnt(0)
	s_barrier
	v_mfma_f32_16x16x32_bf16 v[126:129], v[136:139], v[172:175], v[126:129]
	s_setprio 1
	v_mfma_f32_16x16x32_bf16 v[122:125], v[148:151], v[172:175], v[122:125]
	v_mfma_f32_16x16x32_bf16 v[110:113], v[136:139], v[180:183], v[110:113]
	v_mfma_f32_16x16x32_bf16 v[106:109], v[148:151], v[180:183], v[106:109]
	v_mfma_f32_16x16x32_bf16 v[94:97], v[136:139], v[188:191], v[94:97]
	v_mfma_f32_16x16x32_bf16 v[90:93], v[148:151], v[188:191], v[90:93]
	v_mfma_f32_16x16x32_bf16 v[78:81], v[136:139], v[196:199], v[78:81]
	v_mfma_f32_16x16x32_bf16 v[74:77], v[148:151], v[196:199], v[74:77]
	v_mfma_f32_16x16x32_bf16 v[126:129], v[144:147], v[176:179], v[126:129]
	v_mfma_f32_16x16x32_bf16 v[122:125], v[152:155], v[176:179], v[122:125]
	v_mfma_f32_16x16x32_bf16 v[110:113], v[144:147], v[184:187], v[110:113]
	v_mfma_f32_16x16x32_bf16 v[106:109], v[152:155], v[184:187], v[106:109]
	v_mfma_f32_16x16x32_bf16 v[94:97], v[144:147], v[192:195], v[94:97]
	v_mfma_f32_16x16x32_bf16 v[90:93], v[152:155], v[192:195], v[90:93]
	v_mfma_f32_16x16x32_bf16 v[78:81], v[144:147], v[200:203], v[78:81]
	v_mfma_f32_16x16x32_bf16 v[74:77], v[152:155], v[200:203], v[74:77]
	s_setprio 0
	s_setprio 1
	v_mfma_f32_16x16x32_bf16 v[118:121], v[156:159], v[172:175], v[118:121]
	v_mfma_f32_16x16x32_bf16 v[114:117], v[164:167], v[172:175], v[114:117]
	v_mfma_f32_16x16x32_bf16 v[102:105], v[156:159], v[180:183], v[102:105]
	v_mfma_f32_16x16x32_bf16 v[98:101], v[164:167], v[180:183], v[98:101]
	v_mfma_f32_16x16x32_bf16 v[86:89], v[156:159], v[188:191], v[86:89]
	v_mfma_f32_16x16x32_bf16 v[82:85], v[164:167], v[188:191], v[82:85]
	v_mfma_f32_16x16x32_bf16 v[70:73], v[156:159], v[196:199], v[70:73]
	v_mfma_f32_16x16x32_bf16 v[66:69], v[164:167], v[196:199], v[66:69]
	v_mfma_f32_16x16x32_bf16 v[118:121], v[160:163], v[176:179], v[118:121]
	v_mfma_f32_16x16x32_bf16 v[114:117], v[168:171], v[176:179], v[114:117]
	v_mfma_f32_16x16x32_bf16 v[102:105], v[160:163], v[184:187], v[102:105]
	v_mfma_f32_16x16x32_bf16 v[98:101], v[168:171], v[184:187], v[98:101]
	v_mfma_f32_16x16x32_bf16 v[86:89], v[160:163], v[192:195], v[86:89]
	v_mfma_f32_16x16x32_bf16 v[82:85], v[168:171], v[192:195], v[82:85]
	v_mfma_f32_16x16x32_bf16 v[70:73], v[160:163], v[200:203], v[70:73]
	v_mfma_f32_16x16x32_bf16 v[66:69], v[168:171], v[200:203], v[66:69]
	s_barrier
	s_setprio 0
	s_add_i32 s28, s29, s43
	v_lshl_add_u64 v[204:205], s[30:31], 0, v[0:1]
	s_mov_b32 m0, s28
	ds_read_b128 v[172:175], v143 offset:16384
	ds_read_b128 v[176:179], v143 offset:17408
	ds_read_b128 v[180:183], v143 offset:18432
	ds_read_b128 v[184:187], v143 offset:19456
	ds_read_b128 v[188:191], v143 offset:20480
	ds_read_b128 v[192:195], v143 offset:21504
	ds_read_b128 v[196:199], v143 offset:22528
	ds_read_b128 v[200:203], v143 offset:23552
	global_load_lds_dwordx4 v[204:205], off
	s_add_i32 m0, s28, 0x2000
	s_add_u32 s28, s30, 0x80000
	v_lshl_add_u64 v[206:207], s[30:31], 0, v[130:131]
	s_addc_u32 s29, s31, 0
	s_add_i32 s23, s23, s43
	global_load_lds_dwordx4 v[206:207], off
	v_lshl_add_u64 v[208:209], s[28:29], 0, v[0:1]
	s_mov_b32 m0, s23
	v_lshl_add_u64 v[210:211], s[36:37], 0, v[130:131]
	global_load_lds_dwordx4 v[208:209], off
	v_lshl_add_u64 v[208:209], s[28:29], 0, v[130:131]
	s_add_i32 m0, s23, 0x2000
	s_nop 0
	global_load_lds_dwordx4 v[208:209], off
	v_lshl_add_u64 v[208:209], s[36:37], 0, v[0:1]
	s_mov_b32 m0, s46
	s_nop 0
	global_load_lds_dwordx4 v[208:209], off
	s_mov_b32 m0, s47
	s_nop 0
	global_load_lds_dwordx4 v[210:211], off
	s_waitcnt vmcnt(8)
	s_waitcnt lgkmcnt(0)
	s_barrier
; #define PG8_STAGE(bufoff, gbase, voff) do { _Pragma("unroll") for (int _i = 0; _i < 2; ++_i) \
;         __builtin_amdgcn_global_load_lds((const unsigned*)((const char*)(gbase) + (voff)[_i]), (LAS unsigned*)(lds + (bufoff) + ldsw + _i * 8192), 16, 0, 0); } while (0)
; #define PG8_LDA(dst, b, h) do { _Pragma("unroll") for (int m = 0; m < 4; ++m) _Pragma("unroll") for (int k = 0; k < 2; ++k) dst[m][k] = *(const LAS bf16x8*)(lds + PG8_SA(b, h) + aoff + m * 2048 + k * 1024); } while (0)
; #define PG8_LDB(dst, b, h) do { _Pragma("unroll") for (int n = 0; n < 2; ++n) _Pragma("unroll") for (int k = 0; k < 2; ++k) dst[n][k] = *(const LAS bf16x8*)(lds + PG8_SB(b, h) + boff + n * 2048 + k * 1024); } while (0)
; #define PG8_MMA(ai, bj, At, Bt) do { __builtin_amdgcn_s_setprio(1); _Pragma("unroll") for (int m = 0; m < 4; ++m) _Pragma("unroll") for (int n = 0; n < 2; ++n) _Pragma("unroll") for (int k = 0; k < 2; ++k) \
;         acc[ai][bj][m][n] = __builtin_amdgcn_mfma_f32_16x16x32_bf16(Bt[n][k], At[m][k], acc[ai][bj][m][n], 0, 0, 0); __builtin_amdgcn_s_setprio(0); } while (0)
; #define PG8_WAIT_V(n) asm volatile("s_waitcnt vmcnt(" #n ")" ::: "memory")
; #define PG8_WAIT_L(n) asm volatile("s_waitcnt lgkmcnt(" #n ")" ::: "memory")
; #define PG8_BAR __builtin_amdgcn_s_barrier()
; #define PG8_SCHED __builtin_amdgcn_sched_barrier(0)
; template <class Epi, class Sched, bool ALIGN_EPI, bool LAST_FUSED = false, bool PERM = false, bool CARRY = false>
; __device__ __forceinline__ void gemm_phase(LAS unsigned char* lds, const int tid, const int K, const int lda, const int ldb, const Sched& S, const Epi& E) {
;     ...
;             PG8_WAIT_V(8); PG8_WAIT_L(0); PG8_BAR; PG8_MMA(1, 0, At, B0); PG8_MMA(1, 1, At, B1); PG8_BAR; PG8_SCHED;
;             PG8_LDB(B0, 1, 0); PG8_LDB(B1, 1, 1); PG8_SCHED; PG8_LDA(At, 1, 0); PG8_STAGE(PG8_SA(0, 1), a2 + hstepA, voffA);
;             PG8_WAIT_V(8); PG8_WAIT_L(0); PG8_BAR; PG8_MMA(0, 0, At, B0); PG8_MMA(0, 1, At, B1); PG8_BAR; PG8_SCHED;
	v_mfma_f32_16x16x32_bf16 v[62:65], v[136:139], v[172:175], v[62:65]
	s_setprio 1
	v_mfma_f32_16x16x32_bf16 v[58:61], v[148:151], v[172:175], v[58:61]
	v_mfma_f32_16x16x32_bf16 v[46:49], v[136:139], v[180:183], v[46:49]
	v_mfma_f32_16x16x32_bf16 v[42:45], v[148:151], v[180:183], v[42:45]
	v_mfma_f32_16x16x32_bf16 v[30:33], v[136:139], v[188:191], v[30:33]
	v_mfma_f32_16x16x32_bf16 v[26:29], v[148:151], v[188:191], v[26:29]
	v_mfma_f32_16x16x32_bf16 v[14:17], v[136:139], v[196:199], v[14:17]
	v_mfma_f32_16x16x32_bf16 v[10:13], v[148:151], v[196:199], v[10:13]
	v_mfma_f32_16x16x32_bf16 v[62:65], v[144:147], v[176:179], v[62:65]
	v_mfma_f32_16x16x32_bf16 v[58:61], v[152:155], v[176:179], v[58:61]
	v_mfma_f32_16x16x32_bf16 v[46:49], v[144:147], v[184:187], v[46:49]
	v_mfma_f32_16x16x32_bf16 v[42:45], v[152:155], v[184:187], v[42:45]
	v_mfma_f32_16x16x32_bf16 v[30:33], v[144:147], v[192:195], v[30:33]
	v_mfma_f32_16x16x32_bf16 v[26:29], v[152:155], v[192:195], v[26:29]
	v_mfma_f32_16x16x32_bf16 v[14:17], v[144:147], v[200:203], v[14:17]
	v_mfma_f32_16x16x32_bf16 v[10:13], v[152:155], v[200:203], v[10:13]
	s_setprio 0
	s_setprio 1
	v_mfma_f32_16x16x32_bf16 v[54:57], v[156:159], v[172:175], v[54:57]
	v_mfma_f32_16x16x32_bf16 v[50:53], v[164:167], v[172:175], v[50:53]
	v_mfma_f32_16x16x32_bf16 v[38:41], v[156:159], v[180:183], v[38:41]
	v_mfma_f32_16x16x32_bf16 v[34:37], v[164:167], v[180:183], v[34:37]
	v_mfma_f32_16x16x32_bf16 v[22:25], v[156:159], v[188:191], v[22:25]
	v_mfma_f32_16x16x32_bf16 v[18:21], v[164:167], v[188:191], v[18:21]
	v_mfma_f32_16x16x32_bf16 v[6:9], v[156:159], v[196:199], v[6:9]
	v_mfma_f32_16x16x32_bf16 v[2:5], v[164:167], v[196:199], v[2:5]
	v_mfma_f32_16x16x32_bf16 v[54:57], v[160:163], v[176:179], v[54:57]
	v_mfma_f32_16x16x32_bf16 v[50:53], v[168:171], v[176:179], v[50:53]
	v_mfma_f32_16x16x32_bf16 v[38:41], v[160:163], v[184:187], v[38:41]
	v_mfma_f32_16x16x32_bf16 v[34:37], v[168:171], v[184:187], v[34:37]
	v_mfma_f32_16x16x32_bf16 v[22:25], v[160:163], v[192:195], v[22:25]
	v_mfma_f32_16x16x32_bf16 v[18:21], v[168:171], v[192:195], v[18:21]
	v_mfma_f32_16x16x32_bf16 v[6:9], v[160:163], v[200:203], v[6:9]
	v_mfma_f32_16x16x32_bf16 v[2:5], v[168:171], v[200:203], v[2:5]
	s_barrier
	s_setprio 0
	s_add_i32 s23, 0, 0x18000
	s_add_i32 s35, 0, 0x1c000
	v_add_u32_e32 v152, s23, v142
	v_add_u32_e32 v168, s35, v142
	ds_read_b128 v[136:139], v152
	ds_read_b128 v[144:147], v152 offset:1024
	ds_read_b128 v[148:151], v152 offset:2048
	ds_read_b128 v[152:155], v152 offset:3072
	ds_read_b128 v[156:159], v168
	ds_read_b128 v[160:163], v168 offset:1024
	ds_read_b128 v[164:167], v168 offset:2048
	ds_read_b128 v[168:171], v168 offset:3072
	s_add_u32 s28, s36, 0x80000
	s_addc_u32 s29, s37, 0
	s_mov_b32 m0, s48
	v_lshl_add_u64 v[212:213], s[28:29], 0, v[0:1]
	ds_read_b128 v[172:175], v143 offset:32768
	ds_read_b128 v[176:179], v143 offset:33792
	ds_read_b128 v[180:183], v143 offset:34816
	ds_read_b128 v[184:187], v143 offset:35840
	ds_read_b128 v[188:191], v143 offset:36864
	ds_read_b128 v[192:195], v143 offset:37888
	ds_read_b128 v[196:199], v143 offset:38912
	ds_read_b128 v[200:203], v143 offset:39936
	global_load_lds_dwordx4 v[212:213], off
	v_lshl_add_u64 v[212:213], s[28:29], 0, v[130:131]
	s_mov_b32 m0, s49
	s_nop 0
	global_load_lds_dwordx4 v[212:213], off
	s_waitcnt vmcnt(8)
	s_waitcnt lgkmcnt(0)
	s_barrier
	v_mfma_f32_16x16x32_bf16 v[126:129], v[136:139], v[172:175], v[126:129]
	s_setprio 1
	v_mfma_f32_16x16x32_bf16 v[122:125], v[148:151], v[172:175], v[122:125]
	v_mfma_f32_16x16x32_bf16 v[110:113], v[136:139], v[180:183], v[110:113]
	v_mfma_f32_16x16x32_bf16 v[106:109], v[148:151], v[180:183], v[106:109]
	v_mfma_f32_16x16x32_bf16 v[94:97], v[136:139], v[188:191], v[94:97]
	v_mfma_f32_16x16x32_bf16 v[90:93], v[148:151], v[188:191], v[90:93]
	v_mfma_f32_16x16x32_bf16 v[78:81], v[136:139], v[196:199], v[78:81]
	v_mfma_f32_16x16x32_bf16 v[74:77], v[148:151], v[196:199], v[74:77]
	v_mfma_f32_16x16x32_bf16 v[126:129], v[144:147], v[176:179], v[126:129]
	v_mfma_f32_16x16x32_bf16 v[122:125], v[152:155], v[176:179], v[122:125]
	v_mfma_f32_16x16x32_bf16 v[110:113], v[144:147], v[184:187], v[110:113]
	v_mfma_f32_16x16x32_bf16 v[106:109], v[152:155], v[184:187], v[106:109]
	v_mfma_f32_16x16x32_bf16 v[94:97], v[144:147], v[192:195], v[94:97]
	v_mfma_f32_16x16x32_bf16 v[90:93], v[152:155], v[192:195], v[90:93]
	v_mfma_f32_16x16x32_bf16 v[78:81], v[144:147], v[200:203], v[78:81]
	v_mfma_f32_16x16x32_bf16 v[74:77], v[152:155], v[200:203], v[74:77]
	s_setprio 0
	s_setprio 1
	v_mfma_f32_16x16x32_bf16 v[118:121], v[156:159], v[172:175], v[118:121]
	v_mfma_f32_16x16x32_bf16 v[114:117], v[164:167], v[172:175], v[114:117]
	v_mfma_f32_16x16x32_bf16 v[102:105], v[156:159], v[180:183], v[102:105]
	v_mfma_f32_16x16x32_bf16 v[98:101], v[164:167], v[180:183], v[98:101]
	v_mfma_f32_16x16x32_bf16 v[86:89], v[156:159], v[188:191], v[86:89]
	v_mfma_f32_16x16x32_bf16 v[82:85], v[164:167], v[188:191], v[82:85]
	v_mfma_f32_16x16x32_bf16 v[70:73], v[156:159], v[196:199], v[70:73]
	v_mfma_f32_16x16x32_bf16 v[66:69], v[164:167], v[196:199], v[66:69]
	v_mfma_f32_16x16x32_bf16 v[118:121], v[160:163], v[176:179], v[118:121]
	v_mfma_f32_16x16x32_bf16 v[114:117], v[168:171], v[176:179], v[114:117]
	v_mfma_f32_16x16x32_bf16 v[102:105], v[160:163], v[184:187], v[102:105]
	v_mfma_f32_16x16x32_bf16 v[98:101], v[168:171], v[184:187], v[98:101]
	v_mfma_f32_16x16x32_bf16 v[86:89], v[160:163], v[192:195], v[86:89]
	v_mfma_f32_16x16x32_bf16 v[82:85], v[168:171], v[192:195], v[82:85]
	v_mfma_f32_16x16x32_bf16 v[70:73], v[160:163], v[200:203], v[70:73]
	v_mfma_f32_16x16x32_bf16 v[66:69], v[168:171], v[200:203], v[66:69]
	s_barrier
; #define PG8_STAGE(bufoff, gbase, voff) do { _Pragma("unroll") for (int _i = 0; _i < 2; ++_i) \
;         __builtin_amdgcn_global_load_lds((const unsigned*)((const char*)(gbase) + (voff)[_i]), (LAS unsigned*)(lds + (bufoff) + ldsw + _i * 8192), 16, 0, 0); } while (0)
; #define PG8_LDA(dst, b, h) do { _Pragma("unroll") for (int m = 0; m < 4; ++m) _Pragma("unroll") for (int k = 0; k < 2; ++k) dst[m][k] = *(const LAS bf16x8*)(lds + PG8_SA(b, h) + aoff + m * 2048 + k * 1024); } while (0)
; #define PG8_WAIT_V(n) asm volatile("s_waitcnt vmcnt(" #n ")" ::: "memory")
; #define PG8_WAIT_L(n) asm volatile("s_waitcnt lgkmcnt(" #n ")" ::: "memory")
; template <class Epi, class Sched, bool ALIGN_EPI, bool LAST_FUSED = false, bool PERM = false, bool CARRY = false>
; __device__ __forceinline__ void gemm_phase(LAS unsigned char* lds, const int tid, const int K, const int lda, const int ldb, const Sched& S, const Epi& E) {
;     ...
;         for (int t = 0; t < nt; t += 2) {
;             const bool last = (t == nt - 2);
;             const char* a1 = cA + (size_t)(t + 1) * kstep;
;             const char* a2 = last ? nA : cA + (size_t)(t + 2) * kstep; const char* b2 = last ? nB : cB + (size_t)(t + 2) * kstep;
;             const char* a3 = a2 + kstep; const char* b3 = b2 + kstep;
;             PG8_LDB(B0, 0, 0); PG8_LDB(B1, 0, 1); PG8_SCHED; PG8_LDA(At, 0, 0); PG8_STAGE(PG8_SA(1, 1), a1 + hstepA, voffA);
;             PG8_WAIT_V(8); PG8_WAIT_L(0); PG8_BAR; PG8_MMA(0, 0, At, B0); PG8_MMA(0, 1, At, B1); PG8_BAR; PG8_SCHED;
;             PG8_LDA(At, 0, 1); PG8_STAGE(PG8_SB(0, 0), b2, voffB); PG8_STAGE(PG8_SB(0, 1), b2 + hstepB, voffB); PG8_STAGE(PG8_SA(0, 0), a2, voffA);
;             PG8_WAIT_V(8); PG8_WAIT_L(0); PG8_BAR; PG8_MMA(1, 0, At, B0); PG8_MMA(1, 1, At, B1); PG8_BAR; PG8_SCHED;
;             PG8_LDB(B0, 1, 0); PG8_LDB(B1, 1, 1); PG8_SCHED; PG8_LDA(At, 1, 0); PG8_STAGE(PG8_SA(0, 1), a2 + hstepA, voffA);
;             PG8_WAIT_V(8); PG8_WAIT_L(0); PG8_BAR; PG8_MMA(0, 0, At, B0); PG8_MMA(0, 1, At, B1); PG8_BAR; PG8_SCHED;
;             PG8_LDA(At, 1, 1); PG8_STAGE(PG8_SB(1, 0), b3, voffB); PG8_STAGE(PG8_SB(1, 1), b3 + hstepB, voffB); PG8_STAGE(PG8_SA(1, 0), a3, voffA);
;             PG8_WAIT_V(8); PG8_WAIT_L(0); PG8_BAR; PG8_MMA(1, 0, At, B0); PG8_MMA(1, 1, At, B1); PG8_BAR; PG8_SCHED;
;         }
;         if constexpr (ALIGN_EPI) { if (wr == 0) PG8_BAR; }
	s_setprio 0
	s_add_i32 s23, s23, s43
	v_lshl_add_u64 v[204:205], v[204:205], 0, s[68:69]
	s_mov_b32 m0, s23
	ds_read_b128 v[172:175], v143 offset:49152
	ds_read_b128 v[176:179], v143 offset:50176
	ds_read_b128 v[180:183], v143 offset:51200
	ds_read_b128 v[184:187], v143 offset:52224
	ds_read_b128 v[188:191], v143 offset:53248
	ds_read_b128 v[192:195], v143 offset:54272
	ds_read_b128 v[196:199], v143 offset:55296
	ds_read_b128 v[200:203], v143 offset:56320
	global_load_lds_dwordx4 v[204:205], off
	s_add_i32 m0, s23, 0x2000
	s_add_u32 s28, s30, 0x80080
	v_lshl_add_u64 v[204:205], v[206:207], 0, s[68:69]
	s_addc_u32 s29, s31, 0
	s_add_i32 s23, s35, s43
	global_load_lds_dwordx4 v[204:205], off
	v_lshl_add_u64 v[204:205], s[28:29], 0, v[0:1]
	s_mov_b32 m0, s23
	s_nop 0
	global_load_lds_dwordx4 v[204:205], off
	v_lshl_add_u64 v[204:205], s[28:29], 0, v[130:131]
	s_add_i32 m0, s23, 0x2000
	s_nop 0
	global_load_lds_dwordx4 v[204:205], off
	v_lshl_add_u64 v[204:205], v[208:209], 0, s[68:69]
	s_mov_b32 m0, s51
	s_nop 0
	global_load_lds_dwordx4 v[204:205], off
	v_lshl_add_u64 v[204:205], v[210:211], 0, s[68:69]
	s_mov_b32 m0, s52
	s_nop 0
	global_load_lds_dwordx4 v[204:205], off
	s_waitcnt vmcnt(8)
	s_waitcnt lgkmcnt(0)
	s_barrier
	v_mfma_f32_16x16x32_bf16 v[62:65], v[136:139], v[172:175], v[62:65]
	s_setprio 1
	v_mfma_f32_16x16x32_bf16 v[58:61], v[148:151], v[172:175], v[58:61]
	v_mfma_f32_16x16x32_bf16 v[46:49], v[136:139], v[180:183], v[46:49]
	v_mfma_f32_16x16x32_bf16 v[42:45], v[148:151], v[180:183], v[42:45]
	v_mfma_f32_16x16x32_bf16 v[30:33], v[136:139], v[188:191], v[30:33]
	v_mfma_f32_16x16x32_bf16 v[26:29], v[148:151], v[188:191], v[26:29]
	v_mfma_f32_16x16x32_bf16 v[14:17], v[136:139], v[196:199], v[14:17]
	v_mfma_f32_16x16x32_bf16 v[10:13], v[148:151], v[196:199], v[10:13]
	v_mfma_f32_16x16x32_bf16 v[62:65], v[144:147], v[176:179], v[62:65]
	v_mfma_f32_16x16x32_bf16 v[58:61], v[152:155], v[176:179], v[58:61]
	v_mfma_f32_16x16x32_bf16 v[46:49], v[144:147], v[184:187], v[46:49]
	v_mfma_f32_16x16x32_bf16 v[42:45], v[152:155], v[184:187], v[42:45]
	v_mfma_f32_16x16x32_bf16 v[30:33], v[144:147], v[192:195], v[30:33]
	v_mfma_f32_16x16x32_bf16 v[26:29], v[152:155], v[192:195], v[26:29]
	v_mfma_f32_16x16x32_bf16 v[14:17], v[144:147], v[200:203], v[14:17]
	v_mfma_f32_16x16x32_bf16 v[10:13], v[152:155], v[200:203], v[10:13]
	s_setprio 0
	s_setprio 1
	v_mfma_f32_16x16x32_bf16 v[54:57], v[156:159], v[172:175], v[54:57]
	v_mfma_f32_16x16x32_bf16 v[50:53], v[164:167], v[172:175], v[50:53]
	v_mfma_f32_16x16x32_bf16 v[38:41], v[156:159], v[180:183], v[38:41]
	v_mfma_f32_16x16x32_bf16 v[34:37], v[164:167], v[180:183], v[34:37]
	v_mfma_f32_16x16x32_bf16 v[22:25], v[156:159], v[188:191], v[22:25]
	v_mfma_f32_16x16x32_bf16 v[18:21], v[164:167], v[188:191], v[18:21]
	v_mfma_f32_16x16x32_bf16 v[6:9], v[156:159], v[196:199], v[6:9]
	v_mfma_f32_16x16x32_bf16 v[2:5], v[164:167], v[196:199], v[2:5]
	v_mfma_f32_16x16x32_bf16 v[54:57], v[160:163], v[176:179], v[54:57]
	v_mfma_f32_16x16x32_bf16 v[50:53], v[168:171], v[176:179], v[50:53]
	v_mfma_f32_16x16x32_bf16 v[38:41], v[160:163], v[184:187], v[38:41]
	v_mfma_f32_16x16x32_bf16 v[34:37], v[168:171], v[184:187], v[34:37]
	v_mfma_f32_16x16x32_bf16 v[22:25], v[160:163], v[192:195], v[22:25]
	v_mfma_f32_16x16x32_bf16 v[18:21], v[168:171], v[192:195], v[18:21]
	v_mfma_f32_16x16x32_bf16 v[6:9], v[160:163], v[200:203], v[6:9]
	v_mfma_f32_16x16x32_bf16 v[2:5], v[168:171], v[200:203], v[2:5]
	s_barrier
	s_setprio 0
	s_add_i32 s15, s15, 2
	s_add_u32 s26, s26, 0x100
	s_addc_u32 s27, s27, 0
	s_add_u32 s5, s5, 0x100
	s_addc_u32 s13, s13, 0
	s_cmp_gt_u32 s15, 29
	s_cbranch_scc0 .LBB0_1077
	s_and_b64 vcc, exec, s[10:11]
	s_cbranch_vccz .LBB0_1080
	s_barrier

; #define PG8_STAGE(bufoff, gbase, voff) do { _Pragma("unroll") for (int _i = 0; _i < 2; ++_i) \
;         __builtin_amdgcn_global_load_lds((const unsigned*)((const char*)(gbase) + (voff)[_i]), (LAS unsigned*)(lds + (bufoff) + ldsw + _i * 8192), 16, 0, 0); } while (0)
; #define PG8_LDA(dst, b, h) do { _Pragma("unroll") for (int m = 0; m < 4; ++m) _Pragma("unroll") for (int k = 0; k < 2; ++k) dst[m][k] = *(const LAS bf16x8*)(lds + PG8_SA(b, h) + aoff + m * 2048 + k * 1024); } while (0)
; #define PG8_LDB(dst, b, h) do { _Pragma("unroll") for (int n = 0; n < 2; ++n) _Pragma("unroll") for (int k = 0; k < 2; ++k) dst[n][k] = *(const LAS bf16x8*)(lds + PG8_SB(b, h) + boff + n * 2048 + k * 1024); } while (0)
; #define PG8_WAIT_V(n) asm volatile("s_waitcnt vmcnt(" #n ")" ::: "memory")
; #define PG8_WAIT_L(n) asm volatile("s_waitcnt lgkmcnt(" #n ")" ::: "memory")
; #define PG8_BAR __builtin_amdgcn_s_barrier()
; #define PG8_SCHED __builtin_amdgcn_sched_barrier(0)
; template <class Epi, class Sched, bool ALIGN_EPI, bool LAST_FUSED = false, bool PERM = false, bool CARRY = false>
; __device__ __forceinline__ void gemm_phase(LAS unsigned char* lds, const int tid, const int K, const int lda, const int ldb, const Sched& S, const Epi& E) {
;     ...
;         const bool has_next = S.next(KD_IDX(ui + 1), nxt);
;         const char* nA = has_next ? nxt.a : cA; const char* nB = has_next ? nxt.b : cB; const int nt = cur.nt;
; #pragma unroll 1
;         for (int t = 0; t < nt; t += 2) {
;             const bool last = (t == nt - 2);
;             const char* a1 = cA + (size_t)(t + 1) * kstep;
;             const char* a2 = last ? nA : cA + (size_t)(t + 2) * kstep; const char* b2 = last ? nB : cB + (size_t)(t + 2) * kstep;
;             const char* a3 = a2 + kstep; const char* b3 = b2 + kstep;
;             PG8_LDB(B0, 0, 0); PG8_LDB(B1, 0, 1); PG8_SCHED; PG8_LDA(At, 0, 0); PG8_STAGE(PG8_SA(1, 1), a1 + hstepA, voffA);
;             PG8_WAIT_V(8); PG8_WAIT_L(0); PG8_BAR; PG8_MMA(0, 0, At, B0); PG8_MMA(0, 1, At, B1); PG8_BAR; PG8_SCHED;
;             PG8_LDA(At, 0, 1); PG8_STAGE(PG8_SB(0, 0), b2, voffB); PG8_STAGE(PG8_SB(0, 1), b2 + hstepB, voffB); PG8_STAGE(PG8_SA(0, 0), a2, voffA);
;             PG8_WAIT_V(8); PG8_WAIT_L(0); PG8_BAR; PG8_MMA(1, 0, At, B0); PG8_MMA(1, 1, At, B1); PG8_BAR; PG8_SCHED;
.LBB0_1367:
	s_add_u32 s19, s38, s17
	s_addc_u32 s23, s39, 0
	s_add_u32 s35, s19, 0x100
	s_addc_u32 s37, s23, 0
	s_and_b64 s[28:29], s[46:47], exec
	s_cselect_b32 s51, s27, s37
	s_cselect_b32 s50, s26, s35
	s_add_u32 s17, s40, s17
	s_addc_u32 s28, s41, 0
	s_add_u32 s17, s17, 0x100
	s_addc_u32 s35, s28, 0
	s_add_i32 s45, 0, 0x10000
	s_and_b64 s[28:29], s[46:47], exec
	s_cselect_b32 s55, s31, s35
	s_cselect_b32 s54, s30, s17
	s_add_i32 s47, 0, 0x14000
	s_add_u32 s52, s19, 0x80080
	s_addc_u32 s53, s23, 0
	s_add_i32 s44, s45, s61
	s_add_i32 m0, s63, 0xc000
	s_add_i32 s79, s63, 0xe000
	s_add_i32 s29, s44, 0x2000
	s_add_u32 s58, s54, 0x10000
	v_add_u32_e32 v46, s45, v216
	v_add_u32_e32 v164, s47, v216
	s_addc_u32 s59, s55, 0
	s_add_i32 s37, s47, s61
	ds_read_b128 v[26:29], v46
	ds_read_b128 v[34:37], v46 offset:1024
	ds_read_b128 v[38:41], v46 offset:2048
	ds_read_b128 v[46:49], v46 offset:3072
	ds_read_b128 v[54:57], v164
	ds_read_b128 v[58:61], v164 offset:1024
	ds_read_b128 v[160:163], v164 offset:2048
	ds_read_b128 v[164:167], v164 offset:3072
	s_add_i32 s35, s37, 0x2000
	s_add_i32 s28, 0, 0x18000
	s_add_i32 s23, 0, 0x1c000
	s_add_u32 s48, s50, 0x80000
	s_addc_u32 s49, s51, 0
	s_add_i32 s19, s28, s61
	s_add_i32 s17, s19, 0x2000
	s_add_u32 s46, s54, 0x10080
	s_addc_u32 s47, s55, 0
	s_add_i32 s78, s23, s61
	s_add_i32 s45, s78, 0x2000
	v_lshl_add_u64 v[200:201], s[52:53], 0, v[158:159]
	ds_read_b128 v[168:171], v217
	ds_read_b128 v[172:175], v217 offset:1024
	ds_read_b128 v[176:179], v217 offset:2048
	ds_read_b128 v[180:183], v217 offset:3072
	ds_read_b128 v[184:187], v217 offset:4096
	ds_read_b128 v[188:191], v217 offset:5120
	ds_read_b128 v[192:195], v217 offset:6144
	ds_read_b128 v[196:199], v217 offset:7168
	global_load_lds_dwordx4 v[200:201], off
	v_lshl_add_u64 v[200:201], s[52:53], 0, v[156:157]
	s_mov_b32 m0, s79
	s_nop 0
	global_load_lds_dwordx4 v[200:201], off
	s_waitcnt vmcnt(8)
	s_waitcnt lgkmcnt(0)
	s_barrier
	v_mfma_f32_16x16x32_bf16 v[150:153], v[26:29], v[168:171], v[150:153]
	s_setprio 1
	v_mfma_f32_16x16x32_bf16 v[142:145], v[38:41], v[168:171], v[142:145]
	v_mfma_f32_16x16x32_bf16 v[134:137], v[26:29], v[176:179], v[134:137]
	v_mfma_f32_16x16x32_bf16 v[126:129], v[38:41], v[176:179], v[126:129]
	v_mfma_f32_16x16x32_bf16 v[118:121], v[26:29], v[184:187], v[118:121]
	v_mfma_f32_16x16x32_bf16 v[110:113], v[38:41], v[184:187], v[110:113]
	v_mfma_f32_16x16x32_bf16 v[102:105], v[26:29], v[192:195], v[102:105]
	v_mfma_f32_16x16x32_bf16 v[94:97], v[38:41], v[192:195], v[94:97]
	v_mfma_f32_16x16x32_bf16 v[150:153], v[34:37], v[172:175], v[150:153]
	v_mfma_f32_16x16x32_bf16 v[142:145], v[46:49], v[172:175], v[142:145]
	v_mfma_f32_16x16x32_bf16 v[134:137], v[34:37], v[180:183], v[134:137]
	v_mfma_f32_16x16x32_bf16 v[126:129], v[46:49], v[180:183], v[126:129]
	v_mfma_f32_16x16x32_bf16 v[118:121], v[34:37], v[188:191], v[118:121]
	v_mfma_f32_16x16x32_bf16 v[110:113], v[46:49], v[188:191], v[110:113]
	v_mfma_f32_16x16x32_bf16 v[102:105], v[34:37], v[196:199], v[102:105]
	v_mfma_f32_16x16x32_bf16 v[94:97], v[46:49], v[196:199], v[94:97]
	s_setprio 0
	s_setprio 1
	v_mfma_f32_16x16x32_bf16 v[146:149], v[54:57], v[168:171], v[146:149]
	v_mfma_f32_16x16x32_bf16 v[138:141], v[160:163], v[168:171], v[138:141]
	v_mfma_f32_16x16x32_bf16 v[130:133], v[54:57], v[176:179], v[130:133]
	v_mfma_f32_16x16x32_bf16 v[122:125], v[160:163], v[176:179], v[122:125]
	v_mfma_f32_16x16x32_bf16 v[114:117], v[54:57], v[184:187], v[114:117]
	v_mfma_f32_16x16x32_bf16 v[106:109], v[160:163], v[184:187], v[106:109]
	v_mfma_f32_16x16x32_bf16 v[98:101], v[54:57], v[192:195], v[98:101]
	v_mfma_f32_16x16x32_bf16 v[90:93], v[160:163], v[192:195], v[90:93]
	v_mfma_f32_16x16x32_bf16 v[146:149], v[58:61], v[172:175], v[146:149]
	v_mfma_f32_16x16x32_bf16 v[138:141], v[164:167], v[172:175], v[138:141]
	v_mfma_f32_16x16x32_bf16 v[130:133], v[58:61], v[180:183], v[130:133]
	v_mfma_f32_16x16x32_bf16 v[122:125], v[164:167], v[180:183], v[122:125]
	v_mfma_f32_16x16x32_bf16 v[114:117], v[58:61], v[188:191], v[114:117]
	v_mfma_f32_16x16x32_bf16 v[106:109], v[164:167], v[188:191], v[106:109]
	v_mfma_f32_16x16x32_bf16 v[98:101], v[58:61], v[196:199], v[98:101]
	v_mfma_f32_16x16x32_bf16 v[90:93], v[164:167], v[196:199], v[90:93]
	s_barrier
	s_setprio 0
	s_mov_b32 m0, s44
	v_lshl_add_u64 v[204:205], s[54:55], 0, v[0:1]
	ds_read_b128 v[168:171], v217 offset:16384
	ds_read_b128 v[172:175], v217 offset:17408
	ds_read_b128 v[176:179], v217 offset:18432
	ds_read_b128 v[180:183], v217 offset:19456
	ds_read_b128 v[184:187], v217 offset:20480
	ds_read_b128 v[188:191], v217 offset:21504
	ds_read_b128 v[192:195], v217 offset:22528
	ds_read_b128 v[196:199], v217 offset:23552
	global_load_lds_dwordx4 v[204:205], off
	v_lshl_add_u64 v[206:207], s[54:55], 0, v[154:155]
	s_mov_b32 m0, s29
	v_lshl_add_u64 v[200:201], s[58:59], 0, v[0:1]
	global_load_lds_dwordx4 v[206:207], off
	s_mov_b32 m0, s37
	v_lshl_add_u64 v[208:209], s[50:51], 0, v[158:159]
	global_load_lds_dwordx4 v[200:201], off
	v_lshl_add_u64 v[200:201], s[58:59], 0, v[154:155]
	s_mov_b32 m0, s35
	v_lshl_add_u64 v[210:211], s[50:51], 0, v[156:157]
	global_load_lds_dwordx4 v[200:201], off
	s_mov_b32 m0, s63
	s_nop 0
	global_load_lds_dwordx4 v[208:209], off
	s_mov_b32 m0, s64
	s_nop 0
	global_load_lds_dwordx4 v[210:211], off
	s_waitcnt vmcnt(8)
	s_waitcnt lgkmcnt(0)
	s_barrier
; #define PG8_STAGE(bufoff, gbase, voff) do { _Pragma("unroll") for (int _i = 0; _i < 2; ++_i) \
;         __builtin_amdgcn_global_load_lds((const unsigned*)((const char*)(gbase) + (voff)[_i]), (LAS unsigned*)(lds + (bufoff) + ldsw + _i * 8192), 16, 0, 0); } while (0)
; #define PG8_LDA(dst, b, h) do { _Pragma("unroll") for (int m = 0; m < 4; ++m) _Pragma("unroll") for (int k = 0; k < 2; ++k) dst[m][k] = *(const LAS bf16x8*)(lds + PG8_SA(b, h) + aoff + m * 2048 + k * 1024); } while (0)
; #define PG8_LDB(dst, b, h) do { _Pragma("unroll") for (int n = 0; n < 2; ++n) _Pragma("unroll") for (int k = 0; k < 2; ++k) dst[n][k] = *(const LAS bf16x8*)(lds + PG8_SB(b, h) + boff + n * 2048 + k * 1024); } while (0)
; #define PG8_MMA(ai, bj, At, Bt) do { __builtin_amdgcn_s_setprio(1); _Pragma("unroll") for (int m = 0; m < 4; ++m) _Pragma("unroll") for (int n = 0; n < 2; ++n) _Pragma("unroll") for (int k = 0; k < 2; ++k) \
;         acc[ai][bj][m][n] = __builtin_amdgcn_mfma_f32_16x16x32_bf16(Bt[n][k], At[m][k], acc[ai][bj][m][n], 0, 0, 0); __builtin_amdgcn_s_setprio(0); } while (0)
; #define PG8_WAIT_V(n) asm volatile("s_waitcnt vmcnt(" #n ")" ::: "memory")
; #define PG8_WAIT_L(n) asm volatile("s_waitcnt lgkmcnt(" #n ")" ::: "memory")
; #define PG8_BAR __builtin_amdgcn_s_barrier()
; #define PG8_SCHED __builtin_amdgcn_sched_barrier(0)
; template <class Epi, class Sched, bool ALIGN_EPI, bool LAST_FUSED = false, bool PERM = false, bool CARRY = false>
; __device__ __forceinline__ void gemm_phase(LAS unsigned char* lds, const int tid, const int K, const int lda, const int ldb, const Sched& S, const Epi& E) {
;     ...
;             PG8_WAIT_V(8); PG8_WAIT_L(0); PG8_BAR; PG8_MMA(1, 0, At, B0); PG8_MMA(1, 1, At, B1); PG8_BAR; PG8_SCHED;
;             PG8_LDB(B0, 1, 0); PG8_LDB(B1, 1, 1); PG8_SCHED; PG8_LDA(At, 1, 0); PG8_STAGE(PG8_SA(0, 1), a2 + hstepA, voffA);
;             PG8_WAIT_V(8); PG8_WAIT_L(0); PG8_BAR; PG8_MMA(0, 0, At, B0); PG8_MMA(0, 1, At, B1); PG8_BAR; PG8_SCHED;
	v_mfma_f32_16x16x32_bf16 v[86:89], v[26:29], v[168:171], v[86:89]
	s_setprio 1
	v_mfma_f32_16x16x32_bf16 v[78:81], v[38:41], v[168:171], v[78:81]
	v_mfma_f32_16x16x32_bf16 v[70:73], v[26:29], v[176:179], v[70:73]
	v_mfma_f32_16x16x32_bf16 v[62:65], v[38:41], v[176:179], v[62:65]
	v_mfma_f32_16x16x32_bf16 v[42:45], v[26:29], v[184:187], v[42:45]
	v_mfma_f32_16x16x32_bf16 v[22:25], v[38:41], v[184:187], v[22:25]
	v_mfma_f32_16x16x32_bf16 v[14:17], v[26:29], v[192:195], v[14:17]
	v_mfma_f32_16x16x32_bf16 v[6:9], v[38:41], v[192:195], v[6:9]
	v_mfma_f32_16x16x32_bf16 v[86:89], v[34:37], v[172:175], v[86:89]
	v_mfma_f32_16x16x32_bf16 v[78:81], v[46:49], v[172:175], v[78:81]
	v_mfma_f32_16x16x32_bf16 v[70:73], v[34:37], v[180:183], v[70:73]
	v_mfma_f32_16x16x32_bf16 v[62:65], v[46:49], v[180:183], v[62:65]
	v_mfma_f32_16x16x32_bf16 v[42:45], v[34:37], v[188:191], v[42:45]
	v_mfma_f32_16x16x32_bf16 v[22:25], v[46:49], v[188:191], v[22:25]
	v_mfma_f32_16x16x32_bf16 v[14:17], v[34:37], v[196:199], v[14:17]
	v_mfma_f32_16x16x32_bf16 v[6:9], v[46:49], v[196:199], v[6:9]
	s_setprio 0
	s_setprio 1
	v_mfma_f32_16x16x32_bf16 v[30:33], v[54:57], v[184:187], v[30:33]
	v_mfma_f32_16x16x32_bf16 v[18:21], v[160:163], v[184:187], v[18:21]
	v_mfma_f32_16x16x32_bf16 v[10:13], v[54:57], v[192:195], v[10:13]
	v_mfma_f32_16x16x32_bf16 v[2:5], v[160:163], v[192:195], v[2:5]
	v_mfma_f32_16x16x32_bf16 v[26:29], v[54:57], v[168:171], v[82:85]
	v_mfma_f32_16x16x32_bf16 v[34:37], v[160:163], v[168:171], v[74:77]
	v_mfma_f32_16x16x32_bf16 v[38:41], v[54:57], v[176:179], v[66:69]
	v_mfma_f32_16x16x32_bf16 v[46:49], v[160:163], v[176:179], v[50:53]
	v_mfma_f32_16x16x32_bf16 v[30:33], v[58:61], v[188:191], v[30:33]
	v_mfma_f32_16x16x32_bf16 v[18:21], v[164:167], v[188:191], v[18:21]
	v_mfma_f32_16x16x32_bf16 v[10:13], v[58:61], v[196:199], v[10:13]
	v_mfma_f32_16x16x32_bf16 v[2:5], v[164:167], v[196:199], v[2:5]
	v_mfma_f32_16x16x32_bf16 v[26:29], v[58:61], v[172:175], v[26:29]
	v_mfma_f32_16x16x32_bf16 v[34:37], v[164:167], v[172:175], v[34:37]
	v_mfma_f32_16x16x32_bf16 v[38:41], v[58:61], v[180:183], v[38:41]
	v_mfma_f32_16x16x32_bf16 v[46:49], v[164:167], v[180:183], v[46:49]
	s_barrier
	s_setprio 0
	v_add_u32_e32 v66, s28, v216
	v_add_u32_e32 v74, s23, v216
	ds_read_b128 v[50:53], v66
	ds_read_b128 v[54:57], v66 offset:1024
	ds_read_b128 v[58:61], v66 offset:2048
	ds_read_b128 v[66:69], v66 offset:3072
	ds_read_b128 v[160:163], v74
	ds_read_b128 v[164:167], v74 offset:1024
	ds_read_b128 v[168:171], v74 offset:2048
	ds_read_b128 v[172:175], v74 offset:3072
	s_mov_b32 m0, s65
	v_lshl_add_u64 v[200:201], s[48:49], 0, v[158:159]
	ds_read_b128 v[74:77], v217 offset:32768
	ds_read_b128 v[82:85], v217 offset:33792
	ds_read_b128 v[176:179], v217 offset:34816
	ds_read_b128 v[180:183], v217 offset:35840
	ds_read_b128 v[184:187], v217 offset:36864
	ds_read_b128 v[188:191], v217 offset:37888
	ds_read_b128 v[192:195], v217 offset:38912
	ds_read_b128 v[196:199], v217 offset:39936
	global_load_lds_dwordx4 v[200:201], off
	v_lshl_add_u64 v[200:201], s[48:49], 0, v[156:157]
	s_mov_b32 m0, s66
	s_nop 0
	global_load_lds_dwordx4 v[200:201], off
	s_waitcnt vmcnt(8)
	s_waitcnt lgkmcnt(0)
	s_barrier
	v_mfma_f32_16x16x32_bf16 v[150:153], v[50:53], v[74:77], v[150:153]
	s_setprio 1
	v_mfma_f32_16x16x32_bf16 v[142:145], v[58:61], v[74:77], v[142:145]
	v_mfma_f32_16x16x32_bf16 v[134:137], v[50:53], v[176:179], v[134:137]
	v_mfma_f32_16x16x32_bf16 v[126:129], v[58:61], v[176:179], v[126:129]
	v_mfma_f32_16x16x32_bf16 v[118:121], v[50:53], v[184:187], v[118:121]
	v_mfma_f32_16x16x32_bf16 v[110:113], v[58:61], v[184:187], v[110:113]
	v_mfma_f32_16x16x32_bf16 v[102:105], v[50:53], v[192:195], v[102:105]
	v_mfma_f32_16x16x32_bf16 v[94:97], v[58:61], v[192:195], v[94:97]
	v_mfma_f32_16x16x32_bf16 v[150:153], v[54:57], v[82:85], v[150:153]
	v_mfma_f32_16x16x32_bf16 v[142:145], v[66:69], v[82:85], v[142:145]
	v_mfma_f32_16x16x32_bf16 v[134:137], v[54:57], v[180:183], v[134:137]
	v_mfma_f32_16x16x32_bf16 v[126:129], v[66:69], v[180:183], v[126:129]
	v_mfma_f32_16x16x32_bf16 v[118:121], v[54:57], v[188:191], v[118:121]
	v_mfma_f32_16x16x32_bf16 v[110:113], v[66:69], v[188:191], v[110:113]
	v_mfma_f32_16x16x32_bf16 v[102:105], v[54:57], v[196:199], v[102:105]
	v_mfma_f32_16x16x32_bf16 v[94:97], v[66:69], v[196:199], v[94:97]
	s_setprio 0
	s_setprio 1
	v_mfma_f32_16x16x32_bf16 v[146:149], v[160:163], v[74:77], v[146:149]
	v_mfma_f32_16x16x32_bf16 v[74:77], v[168:171], v[74:77], v[138:141]
	v_mfma_f32_16x16x32_bf16 v[138:141], v[172:175], v[82:85], v[74:77]
	v_mfma_f32_16x16x32_bf16 v[74:77], v[160:163], v[176:179], v[130:133]
	v_mfma_f32_16x16x32_bf16 v[130:133], v[164:167], v[180:183], v[74:77]
	v_mfma_f32_16x16x32_bf16 v[74:77], v[168:171], v[176:179], v[122:125]
	v_mfma_f32_16x16x32_bf16 v[122:125], v[172:175], v[180:183], v[74:77]
	v_mfma_f32_16x16x32_bf16 v[74:77], v[160:163], v[184:187], v[114:117]
	v_mfma_f32_16x16x32_bf16 v[114:117], v[164:167], v[188:191], v[74:77]
	v_mfma_f32_16x16x32_bf16 v[74:77], v[168:171], v[184:187], v[106:109]
	v_mfma_f32_16x16x32_bf16 v[106:109], v[172:175], v[188:191], v[74:77]
	v_mfma_f32_16x16x32_bf16 v[74:77], v[160:163], v[192:195], v[98:101]
	v_mfma_f32_16x16x32_bf16 v[98:101], v[164:167], v[196:199], v[74:77]
	v_mfma_f32_16x16x32_bf16 v[74:77], v[168:171], v[192:195], v[90:93]
	v_mfma_f32_16x16x32_bf16 v[146:149], v[164:167], v[82:85], v[146:149]
	v_mfma_f32_16x16x32_bf16 v[90:93], v[172:175], v[196:199], v[74:77]
	s_barrier
; #define PG8_STAGE(bufoff, gbase, voff) do { _Pragma("unroll") for (int _i = 0; _i < 2; ++_i) \
;         __builtin_amdgcn_global_load_lds((const unsigned*)((const char*)(gbase) + (voff)[_i]), (LAS unsigned*)(lds + (bufoff) + ldsw + _i * 8192), 16, 0, 0); } while (0)
; #define PG8_LDA(dst, b, h) do { _Pragma("unroll") for (int m = 0; m < 4; ++m) _Pragma("unroll") for (int k = 0; k < 2; ++k) dst[m][k] = *(const LAS bf16x8*)(lds + PG8_SA(b, h) + aoff + m * 2048 + k * 1024); } while (0)
; #define PG8_MMA(ai, bj, At, Bt) do { __builtin_amdgcn_s_setprio(1); _Pragma("unroll") for (int m = 0; m < 4; ++m) _Pragma("unroll") for (int n = 0; n < 2; ++n) _Pragma("unroll") for (int k = 0; k < 2; ++k) \
;         acc[ai][bj][m][n] = __builtin_amdgcn_mfma_f32_16x16x32_bf16(Bt[n][k], At[m][k], acc[ai][bj][m][n], 0, 0, 0); __builtin_amdgcn_s_setprio(0); } while (0)
; #define PG8_WAIT_V(n) asm volatile("s_waitcnt vmcnt(" #n ")" ::: "memory")
; #define PG8_WAIT_L(n) asm volatile("s_waitcnt lgkmcnt(" #n ")" ::: "memory")
; #define PG8_BAR __builtin_amdgcn_s_barrier()
; #define PG8_SCHED __builtin_amdgcn_sched_barrier(0)
; template <class Epi, class Sched, bool ALIGN_EPI, bool LAST_FUSED = false, bool PERM = false, bool CARRY = false>
; __device__ __forceinline__ void gemm_phase(LAS unsigned char* lds, const int tid, const int K, const int lda, const int ldb, const Sched& S, const Epi& E) {
;     ...
;             PG8_LDA(At, 1, 1); PG8_STAGE(PG8_SB(1, 0), b3, voffB); PG8_STAGE(PG8_SB(1, 1), b3 + hstepB, voffB); PG8_STAGE(PG8_SA(1, 0), a3, voffA);
;             PG8_WAIT_V(8); PG8_WAIT_L(0); PG8_BAR; PG8_MMA(1, 0, At, B0); PG8_MMA(1, 1, At, B1); PG8_BAR; PG8_SCHED;
;         }
;         if constexpr (ALIGN_EPI) { if (wr == 0) PG8_BAR; }
	s_setprio 0
	s_mov_b32 m0, s19
	v_lshl_add_u64 v[82:83], v[204:205], 0, s[68:69]
	s_nop 1
	ds_read_b128 v[74:77], v217 offset:49152
	ds_read_b128 v[176:179], v217 offset:50176
	ds_read_b128 v[180:183], v217 offset:51200
	ds_read_b128 v[184:187], v217 offset:52224
	ds_read_b128 v[188:191], v217 offset:53248
	ds_read_b128 v[192:195], v217 offset:54272
	ds_read_b128 v[196:199], v217 offset:55296
	ds_read_b128 v[200:203], v217 offset:56320
	global_load_lds_dwordx4 v[82:83], off
	v_lshl_add_u64 v[82:83], v[206:207], 0, s[68:69]
	s_mov_b32 m0, s17
	s_nop 0
	global_load_lds_dwordx4 v[82:83], off
	v_lshl_add_u64 v[82:83], s[46:47], 0, v[0:1]
	s_mov_b32 m0, s78
	s_nop 0
	global_load_lds_dwordx4 v[82:83], off
	v_lshl_add_u64 v[82:83], s[46:47], 0, v[154:155]
	s_mov_b32 m0, s45
	s_nop 0
	global_load_lds_dwordx4 v[82:83], off
	v_lshl_add_u64 v[82:83], v[208:209], 0, s[68:69]
	s_mov_b32 m0, s74
	s_nop 0
	global_load_lds_dwordx4 v[82:83], off
	v_lshl_add_u64 v[82:83], v[210:211], 0, s[68:69]
	s_mov_b32 m0, s75
	s_nop 0
	global_load_lds_dwordx4 v[82:83], off
	s_waitcnt vmcnt(8)
	s_waitcnt lgkmcnt(0)
	s_barrier
	v_mfma_f32_16x16x32_bf16 v[82:85], v[50:53], v[74:77], v[86:89]
	s_setprio 1
	v_mfma_f32_16x16x32_bf16 v[78:81], v[58:61], v[74:77], v[78:81]
	v_mfma_f32_16x16x32_bf16 v[70:73], v[50:53], v[180:183], v[70:73]
	v_mfma_f32_16x16x32_bf16 v[62:65], v[58:61], v[180:183], v[62:65]
	v_mfma_f32_16x16x32_bf16 v[42:45], v[50:53], v[188:191], v[42:45]
	v_mfma_f32_16x16x32_bf16 v[22:25], v[58:61], v[188:191], v[22:25]
	v_mfma_f32_16x16x32_bf16 v[14:17], v[50:53], v[196:199], v[14:17]
	v_mfma_f32_16x16x32_bf16 v[6:9], v[58:61], v[196:199], v[6:9]
	v_mfma_f32_16x16x32_bf16 v[86:89], v[54:57], v[176:179], v[82:85]
	v_mfma_f32_16x16x32_bf16 v[78:81], v[66:69], v[176:179], v[78:81]
	v_mfma_f32_16x16x32_bf16 v[70:73], v[54:57], v[184:187], v[70:73]
	v_mfma_f32_16x16x32_bf16 v[62:65], v[66:69], v[184:187], v[62:65]
	v_mfma_f32_16x16x32_bf16 v[42:45], v[54:57], v[192:195], v[42:45]
	v_mfma_f32_16x16x32_bf16 v[22:25], v[66:69], v[192:195], v[22:25]
	v_mfma_f32_16x16x32_bf16 v[14:17], v[54:57], v[200:203], v[14:17]
	v_mfma_f32_16x16x32_bf16 v[6:9], v[66:69], v[200:203], v[6:9]
	s_setprio 0
	s_setprio 1
	v_mfma_f32_16x16x32_bf16 v[26:29], v[160:163], v[74:77], v[26:29]
	v_mfma_f32_16x16x32_bf16 v[82:85], v[164:167], v[176:179], v[26:29]
	v_mfma_f32_16x16x32_bf16 v[26:29], v[168:171], v[74:77], v[34:37]
	v_mfma_f32_16x16x32_bf16 v[74:77], v[172:175], v[176:179], v[26:29]
	v_mfma_f32_16x16x32_bf16 v[26:29], v[160:163], v[180:183], v[38:41]
	v_mfma_f32_16x16x32_bf16 v[66:69], v[164:167], v[184:187], v[26:29]
	v_mfma_f32_16x16x32_bf16 v[26:29], v[168:171], v[180:183], v[46:49]
	v_mfma_f32_16x16x32_bf16 v[50:53], v[172:175], v[184:187], v[26:29]
	v_mfma_f32_16x16x32_bf16 v[26:29], v[160:163], v[188:191], v[30:33]
	v_mfma_f32_16x16x32_bf16 v[18:21], v[168:171], v[188:191], v[18:21]
	v_mfma_f32_16x16x32_bf16 v[10:13], v[160:163], v[196:199], v[10:13]
	v_mfma_f32_16x16x32_bf16 v[2:5], v[168:171], v[196:199], v[2:5]
	v_mfma_f32_16x16x32_bf16 v[30:33], v[164:167], v[192:195], v[26:29]
	v_mfma_f32_16x16x32_bf16 v[18:21], v[172:175], v[192:195], v[18:21]
	v_mfma_f32_16x16x32_bf16 v[10:13], v[164:167], v[200:203], v[10:13]
	v_mfma_f32_16x16x32_bf16 v[2:5], v[172:175], v[200:203], v[2:5]
	s_barrier
	s_setprio 0
	s_movk_i32 s17, 0x100
	s_andn2_b64 vcc, exec, s[42:43]
	s_mov_b64 s[46:47], -1
	s_mov_b64 s[42:43], 0
	s_cbranch_vccz .LBB0_1367
	s_and_b64 vcc, exec, s[14:15]
	s_cbranch_vccz .LBB0_1370
	s_barrier

; #define PG8_STAGE(bufoff, gbase, voff) do { _Pragma("unroll") for (int _i = 0; _i < 2; ++_i) \
;         __builtin_amdgcn_global_load_lds((const unsigned*)((const char*)(gbase) + (voff)[_i]), (LAS unsigned*)(lds + (bufoff) + ldsw + _i * 8192), 16, 0, 0); } while (0)
; #define PG8_LDA(dst, b, h) do { _Pragma("unroll") for (int m = 0; m < 4; ++m) _Pragma("unroll") for (int k = 0; k < 2; ++k) dst[m][k] = *(const LAS bf16x8*)(lds + PG8_SA(b, h) + aoff + m * 2048 + k * 1024); } while (0)
; #define PG8_LDB(dst, b, h) do { _Pragma("unroll") for (int n = 0; n < 2; ++n) _Pragma("unroll") for (int k = 0; k < 2; ++k) dst[n][k] = *(const LAS bf16x8*)(lds + PG8_SB(b, h) + boff + n * 2048 + k * 1024); } while (0)
; #define PG8_WAIT_V(n) asm volatile("s_waitcnt vmcnt(" #n ")" ::: "memory")
; #define PG8_WAIT_L(n) asm volatile("s_waitcnt lgkmcnt(" #n ")" ::: "memory")
; #define PG8_BAR __builtin_amdgcn_s_barrier()
; #define PG8_SCHED __builtin_amdgcn_sched_barrier(0)
; template <class Epi, class Sched, bool ALIGN_EPI, bool LAST_FUSED = false, bool PERM = false, bool CARRY = false>
; __device__ __forceinline__ void gemm_phase(LAS unsigned char* lds, const int tid, const int K, const int lda, const int ldb, const Sched& S, const Epi& E) {
;     ...
;         const bool has_next = S.next(KD_IDX(ui + 1), nxt);
;         const char* nA = has_next ? nxt.a : cA; const char* nB = has_next ? nxt.b : cB; const int nt = cur.nt;
; #pragma unroll 1
;         for (int t = 0; t < nt; t += 2) {
;             const bool last = (t == nt - 2);
;             const char* a1 = cA + (size_t)(t + 1) * kstep;
;             const char* a2 = last ? nA : cA + (size_t)(t + 2) * kstep; const char* b2 = last ? nB : cB + (size_t)(t + 2) * kstep;
;             const char* a3 = a2 + kstep; const char* b3 = b2 + kstep;
;             PG8_LDB(B0, 0, 0); PG8_LDB(B1, 0, 1); PG8_SCHED; PG8_LDA(At, 0, 0); PG8_STAGE(PG8_SA(1, 1), a1 + hstepA, voffA);
;             PG8_WAIT_V(8); PG8_WAIT_L(0); PG8_BAR; PG8_MMA(0, 0, At, B0); PG8_MMA(0, 1, At, B1); PG8_BAR; PG8_SCHED;
;             PG8_LDA(At, 0, 1); PG8_STAGE(PG8_SB(0, 0), b2, voffB); PG8_STAGE(PG8_SB(0, 1), b2 + hstepB, voffB); PG8_STAGE(PG8_SA(0, 0), a2, voffA);
;             PG8_WAIT_V(8); PG8_WAIT_L(0); PG8_BAR; PG8_MMA(1, 0, At, B0); PG8_MMA(1, 1, At, B1); PG8_BAR; PG8_SCHED;
.LBB0_1585:
	s_add_u32 s52, s42, s48
	s_addc_u32 s53, s43, s49
	s_add_u32 s76, s40, s48
	s_addc_u32 s77, s41, s49
	s_add_i32 s96, 0, 0x10000
	s_cmp_eq_u32 s3, s95
	s_cselect_b32 s53, s24, s53
	s_cselect_b32 s52, s55, s52
	s_cselect_b32 s77, s93, s77
	s_cselect_b32 s76, s94, s76
	s_add_i32 vcc_lo, 0, 0x14000
	v_add_u32_e32 v156, s96, v140
	v_add_u32_e32 v172, vcc_lo, v140
	ds_read_b128 v[142:145], v156
	ds_read_b128 v[146:149], v156 offset:1024
	ds_read_b128 v[150:153], v156 offset:2048
	ds_read_b128 v[156:159], v156 offset:3072
	ds_read_b128 v[160:163], v172
	ds_read_b128 v[164:167], v172 offset:1024
	ds_read_b128 v[168:171], v172 offset:2048
	ds_read_b128 v[172:175], v172 offset:3072
	v_lshl_add_u64 v[208:209], s[42:43], 0, v[138:139]
	s_add_i32 m0, s35, 0xc000
	ds_read_b128 v[176:179], v141
	ds_read_b128 v[180:183], v141 offset:1024
	ds_read_b128 v[184:187], v141 offset:2048
	ds_read_b128 v[188:191], v141 offset:3072
	ds_read_b128 v[192:195], v141 offset:4096
	ds_read_b128 v[196:199], v141 offset:5120
	ds_read_b128 v[200:203], v141 offset:6144
	ds_read_b128 v[204:207], v141 offset:7168
	global_load_lds_dwordx4 v[208:209], off
	v_lshl_add_u64 v[208:209], s[42:43], 0, v[128:129]
	s_add_i32 m0, s35, 0xe000
	s_nop 0
	global_load_lds_dwordx4 v[208:209], off
	s_waitcnt vmcnt(8)
	s_waitcnt lgkmcnt(0)
	s_barrier
	v_mfma_f32_16x16x32_bf16 v[62:65], v[142:145], v[176:179], v[62:65]
	s_setprio 1
	v_mfma_f32_16x16x32_bf16 v[42:45], v[150:153], v[176:179], v[42:45]
	v_mfma_f32_16x16x32_bf16 v[18:21], v[142:145], v[184:187], v[18:21]
	v_mfma_f32_16x16x32_bf16 v[14:17], v[150:153], v[184:187], v[14:17]
	v_mfma_f32_16x16x32_bf16 v[38:41], v[142:145], v[192:195], v[38:41]
	v_mfma_f32_16x16x32_bf16 v[30:33], v[150:153], v[192:195], v[30:33]
	v_mfma_f32_16x16x32_bf16 v[58:61], v[142:145], v[200:203], v[58:61]
	v_mfma_f32_16x16x32_bf16 v[54:57], v[150:153], v[200:203], v[54:57]
	v_mfma_f32_16x16x32_bf16 v[62:65], v[146:149], v[180:183], v[62:65]
	v_mfma_f32_16x16x32_bf16 v[42:45], v[156:159], v[180:183], v[42:45]
	v_mfma_f32_16x16x32_bf16 v[18:21], v[146:149], v[188:191], v[18:21]
	v_mfma_f32_16x16x32_bf16 v[14:17], v[156:159], v[188:191], v[14:17]
	v_mfma_f32_16x16x32_bf16 v[38:41], v[146:149], v[196:199], v[38:41]
	v_mfma_f32_16x16x32_bf16 v[30:33], v[156:159], v[196:199], v[30:33]
	v_mfma_f32_16x16x32_bf16 v[58:61], v[146:149], v[204:207], v[58:61]
	v_mfma_f32_16x16x32_bf16 v[54:57], v[156:159], v[204:207], v[54:57]
	s_setprio 0
	s_setprio 1
	v_mfma_f32_16x16x32_bf16 v[34:37], v[160:163], v[176:179], v[34:37]
	v_mfma_f32_16x16x32_bf16 v[2:5], v[168:171], v[176:179], v[2:5]
	v_mfma_f32_16x16x32_bf16 v[10:13], v[160:163], v[184:187], v[10:13]
	v_mfma_f32_16x16x32_bf16 v[6:9], v[168:171], v[184:187], v[6:9]
	v_mfma_f32_16x16x32_bf16 v[26:29], v[160:163], v[192:195], v[26:29]
	v_mfma_f32_16x16x32_bf16 v[22:25], v[168:171], v[192:195], v[22:25]
	v_mfma_f32_16x16x32_bf16 v[50:53], v[160:163], v[200:203], v[50:53]
	v_mfma_f32_16x16x32_bf16 v[46:49], v[168:171], v[200:203], v[46:49]
	v_mfma_f32_16x16x32_bf16 v[34:37], v[164:167], v[180:183], v[34:37]
	v_mfma_f32_16x16x32_bf16 v[2:5], v[172:175], v[180:183], v[2:5]
	v_mfma_f32_16x16x32_bf16 v[10:13], v[164:167], v[188:191], v[10:13]
	v_mfma_f32_16x16x32_bf16 v[6:9], v[172:175], v[188:191], v[6:9]
	v_mfma_f32_16x16x32_bf16 v[26:29], v[164:167], v[196:199], v[26:29]
	v_mfma_f32_16x16x32_bf16 v[22:25], v[172:175], v[196:199], v[22:25]
	v_mfma_f32_16x16x32_bf16 v[50:53], v[164:167], v[204:207], v[50:53]
	v_mfma_f32_16x16x32_bf16 v[46:49], v[172:175], v[204:207], v[46:49]
	s_barrier
	s_setprio 0
	s_add_i32 s96, s96, s87
	v_lshl_add_u64 v[208:209], s[76:77], 0, v[0:1]
	s_mov_b32 m0, s96
	ds_read_b128 v[176:179], v141 offset:16384
	ds_read_b128 v[180:183], v141 offset:17408
	ds_read_b128 v[184:187], v141 offset:18432
	ds_read_b128 v[188:191], v141 offset:19456
	ds_read_b128 v[192:195], v141 offset:20480
	ds_read_b128 v[196:199], v141 offset:21504
	ds_read_b128 v[200:203], v141 offset:22528
	ds_read_b128 v[204:207], v141 offset:23552
	global_load_lds_dwordx4 v[208:209], off
	s_add_i32 m0, s96, 0x2000
	s_add_u32 s96, s76, 0x80000
	v_lshl_add_u64 v[210:211], s[76:77], 0, v[122:123]
	s_addc_u32 s97, s77, 0
	s_add_i32 vcc_lo, vcc_lo, s87
	global_load_lds_dwordx4 v[210:211], off
	v_lshl_add_u64 v[212:213], s[96:97], 0, v[0:1]
	s_mov_b32 m0, vcc_lo
	v_lshl_add_u64 v[214:215], s[52:53], 0, v[122:123]
	global_load_lds_dwordx4 v[212:213], off
	v_lshl_add_u64 v[212:213], s[96:97], 0, v[122:123]
	s_add_i32 m0, vcc_lo, 0x2000
	s_nop 0
	global_load_lds_dwordx4 v[212:213], off
	v_lshl_add_u64 v[212:213], s[52:53], 0, v[0:1]
	s_mov_b32 m0, s35
	s_nop 0
	global_load_lds_dwordx4 v[212:213], off
	s_mov_b32 m0, s28
	s_nop 0
	global_load_lds_dwordx4 v[214:215], off
	s_waitcnt vmcnt(8)
	s_waitcnt lgkmcnt(0)
	s_barrier
; #define PG8_STAGE(bufoff, gbase, voff) do { _Pragma("unroll") for (int _i = 0; _i < 2; ++_i) \
;         __builtin_amdgcn_global_load_lds((const unsigned*)((const char*)(gbase) + (voff)[_i]), (LAS unsigned*)(lds + (bufoff) + ldsw + _i * 8192), 16, 0, 0); } while (0)
; #define PG8_LDA(dst, b, h) do { _Pragma("unroll") for (int m = 0; m < 4; ++m) _Pragma("unroll") for (int k = 0; k < 2; ++k) dst[m][k] = *(const LAS bf16x8*)(lds + PG8_SA(b, h) + aoff + m * 2048 + k * 1024); } while (0)
; #define PG8_LDB(dst, b, h) do { _Pragma("unroll") for (int n = 0; n < 2; ++n) _Pragma("unroll") for (int k = 0; k < 2; ++k) dst[n][k] = *(const LAS bf16x8*)(lds + PG8_SB(b, h) + boff + n * 2048 + k * 1024); } while (0)
; #define PG8_MMA(ai, bj, At, Bt) do { __builtin_amdgcn_s_setprio(1); _Pragma("unroll") for (int m = 0; m < 4; ++m) _Pragma("unroll") for (int n = 0; n < 2; ++n) _Pragma("unroll") for (int k = 0; k < 2; ++k) \
;         acc[ai][bj][m][n] = __builtin_amdgcn_mfma_f32_16x16x32_bf16(Bt[n][k], At[m][k], acc[ai][bj][m][n], 0, 0, 0); __builtin_amdgcn_s_setprio(0); } while (0)
; #define PG8_WAIT_V(n) asm volatile("s_waitcnt vmcnt(" #n ")" ::: "memory")
; #define PG8_WAIT_L(n) asm volatile("s_waitcnt lgkmcnt(" #n ")" ::: "memory")
; #define PG8_BAR __builtin_amdgcn_s_barrier()
; #define PG8_SCHED __builtin_amdgcn_sched_barrier(0)
; template <class Epi, class Sched, bool ALIGN_EPI, bool LAST_FUSED = false, bool PERM = false, bool CARRY = false>
; __device__ __forceinline__ void gemm_phase(LAS unsigned char* lds, const int tid, const int K, const int lda, const int ldb, const Sched& S, const Epi& E) {
;     ...
;             PG8_WAIT_V(8); PG8_WAIT_L(0); PG8_BAR; PG8_MMA(1, 0, At, B0); PG8_MMA(1, 1, At, B1); PG8_BAR; PG8_SCHED;
;             PG8_LDB(B0, 1, 0); PG8_LDB(B1, 1, 1); PG8_SCHED; PG8_LDA(At, 1, 0); PG8_STAGE(PG8_SA(0, 1), a2 + hstepA, voffA);
;             PG8_WAIT_V(8); PG8_WAIT_L(0); PG8_BAR; PG8_MMA(0, 0, At, B0); PG8_MMA(0, 1, At, B1); PG8_BAR; PG8_SCHED;
	v_mfma_f32_16x16x32_bf16 v[78:81], v[142:145], v[176:179], v[78:81]
	s_setprio 1
	v_mfma_f32_16x16x32_bf16 v[74:77], v[150:153], v[176:179], v[74:77]
	v_mfma_f32_16x16x32_bf16 v[98:101], v[142:145], v[184:187], v[98:101]
	v_mfma_f32_16x16x32_bf16 v[94:97], v[150:153], v[184:187], v[94:97]
	v_mfma_f32_16x16x32_bf16 v[118:121], v[142:145], v[192:195], v[118:121]
	v_mfma_f32_16x16x32_bf16 v[114:117], v[150:153], v[192:195], v[114:117]
	v_mfma_f32_16x16x32_bf16 v[134:137], v[142:145], v[200:203], v[134:137]
	v_mfma_f32_16x16x32_bf16 v[130:133], v[150:153], v[200:203], v[130:133]
	v_mfma_f32_16x16x32_bf16 v[78:81], v[146:149], v[180:183], v[78:81]
	v_mfma_f32_16x16x32_bf16 v[74:77], v[156:159], v[180:183], v[74:77]
	v_mfma_f32_16x16x32_bf16 v[98:101], v[146:149], v[188:191], v[98:101]
	v_mfma_f32_16x16x32_bf16 v[94:97], v[156:159], v[188:191], v[94:97]
	v_mfma_f32_16x16x32_bf16 v[118:121], v[146:149], v[196:199], v[118:121]
	v_mfma_f32_16x16x32_bf16 v[114:117], v[156:159], v[196:199], v[114:117]
	v_mfma_f32_16x16x32_bf16 v[134:137], v[146:149], v[204:207], v[134:137]
	v_mfma_f32_16x16x32_bf16 v[130:133], v[156:159], v[204:207], v[130:133]
	s_setprio 0
	s_setprio 1
	v_mfma_f32_16x16x32_bf16 v[70:73], v[160:163], v[176:179], v[70:73]
	v_mfma_f32_16x16x32_bf16 v[66:69], v[168:171], v[176:179], v[66:69]
	v_mfma_f32_16x16x32_bf16 v[90:93], v[160:163], v[184:187], v[90:93]
	v_mfma_f32_16x16x32_bf16 v[86:89], v[168:171], v[184:187], v[86:89]
	v_mfma_f32_16x16x32_bf16 v[110:113], v[160:163], v[192:195], v[110:113]
	v_mfma_f32_16x16x32_bf16 v[106:109], v[168:171], v[192:195], v[106:109]
	v_mfma_f32_16x16x32_bf16 v[102:105], v[160:163], v[200:203], v[102:105]
	v_mfma_f32_16x16x32_bf16 v[82:85], v[168:171], v[200:203], v[82:85]
	v_mfma_f32_16x16x32_bf16 v[70:73], v[164:167], v[180:183], v[70:73]
	v_mfma_f32_16x16x32_bf16 v[66:69], v[172:175], v[180:183], v[66:69]
	v_mfma_f32_16x16x32_bf16 v[90:93], v[164:167], v[188:191], v[90:93]
	v_mfma_f32_16x16x32_bf16 v[86:89], v[172:175], v[188:191], v[86:89]
	v_mfma_f32_16x16x32_bf16 v[110:113], v[164:167], v[196:199], v[110:113]
	v_mfma_f32_16x16x32_bf16 v[106:109], v[172:175], v[196:199], v[106:109]
	v_mfma_f32_16x16x32_bf16 v[102:105], v[164:167], v[204:207], v[102:105]
	v_mfma_f32_16x16x32_bf16 v[82:85], v[172:175], v[204:207], v[82:85]
	s_barrier
	s_setprio 0
	s_add_i32 s96, 0, 0x18000
	s_add_i32 s97, 0, 0x1c000
	v_add_u32_e32 v156, s96, v140
	v_add_u32_e32 v172, s97, v140
	ds_read_b128 v[142:145], v156
	ds_read_b128 v[146:149], v156 offset:1024
	ds_read_b128 v[150:153], v156 offset:2048
	ds_read_b128 v[156:159], v156 offset:3072
	ds_read_b128 v[160:163], v172
	ds_read_b128 v[164:167], v172 offset:1024
	ds_read_b128 v[168:171], v172 offset:2048
	ds_read_b128 v[172:175], v172 offset:3072
	s_add_u32 s52, s52, 0x80000
	s_addc_u32 s53, s53, 0
	s_mov_b32 m0, s29
	v_lshl_add_u64 v[216:217], s[52:53], 0, v[0:1]
	ds_read_b128 v[176:179], v141 offset:32768
	ds_read_b128 v[180:183], v141 offset:33792
	ds_read_b128 v[184:187], v141 offset:34816
	ds_read_b128 v[188:191], v141 offset:35840
	ds_read_b128 v[192:195], v141 offset:36864
	ds_read_b128 v[196:199], v141 offset:37888
	ds_read_b128 v[200:203], v141 offset:38912
	ds_read_b128 v[204:207], v141 offset:39936
	global_load_lds_dwordx4 v[216:217], off
	v_lshl_add_u64 v[216:217], s[52:53], 0, v[122:123]
	s_mov_b32 m0, s14
	s_nop 0
	global_load_lds_dwordx4 v[216:217], off
	s_waitcnt vmcnt(8)
	s_waitcnt lgkmcnt(0)
	s_barrier
	v_mfma_f32_16x16x32_bf16 v[62:65], v[142:145], v[176:179], v[62:65]
	s_setprio 1
	v_mfma_f32_16x16x32_bf16 v[42:45], v[150:153], v[176:179], v[42:45]
	v_mfma_f32_16x16x32_bf16 v[18:21], v[142:145], v[184:187], v[18:21]
	v_mfma_f32_16x16x32_bf16 v[14:17], v[150:153], v[184:187], v[14:17]
	v_mfma_f32_16x16x32_bf16 v[38:41], v[142:145], v[192:195], v[38:41]
	v_mfma_f32_16x16x32_bf16 v[30:33], v[150:153], v[192:195], v[30:33]
	v_mfma_f32_16x16x32_bf16 v[58:61], v[142:145], v[200:203], v[58:61]
	v_mfma_f32_16x16x32_bf16 v[54:57], v[150:153], v[200:203], v[54:57]
	v_mfma_f32_16x16x32_bf16 v[62:65], v[146:149], v[180:183], v[62:65]
	v_mfma_f32_16x16x32_bf16 v[42:45], v[156:159], v[180:183], v[42:45]
	v_mfma_f32_16x16x32_bf16 v[18:21], v[146:149], v[188:191], v[18:21]
	v_mfma_f32_16x16x32_bf16 v[14:17], v[156:159], v[188:191], v[14:17]
	v_mfma_f32_16x16x32_bf16 v[38:41], v[146:149], v[196:199], v[38:41]
	v_mfma_f32_16x16x32_bf16 v[30:33], v[156:159], v[196:199], v[30:33]
	v_mfma_f32_16x16x32_bf16 v[58:61], v[146:149], v[204:207], v[58:61]
	v_mfma_f32_16x16x32_bf16 v[54:57], v[156:159], v[204:207], v[54:57]
	s_setprio 0
	s_setprio 1
	v_mfma_f32_16x16x32_bf16 v[34:37], v[160:163], v[176:179], v[34:37]
	v_mfma_f32_16x16x32_bf16 v[2:5], v[168:171], v[176:179], v[2:5]
	v_mfma_f32_16x16x32_bf16 v[10:13], v[160:163], v[184:187], v[10:13]
	v_mfma_f32_16x16x32_bf16 v[6:9], v[168:171], v[184:187], v[6:9]
	v_mfma_f32_16x16x32_bf16 v[26:29], v[160:163], v[192:195], v[26:29]
	v_mfma_f32_16x16x32_bf16 v[22:25], v[168:171], v[192:195], v[22:25]
	v_mfma_f32_16x16x32_bf16 v[50:53], v[160:163], v[200:203], v[50:53]
	v_mfma_f32_16x16x32_bf16 v[46:49], v[168:171], v[200:203], v[46:49]
	v_mfma_f32_16x16x32_bf16 v[34:37], v[164:167], v[180:183], v[34:37]
	v_mfma_f32_16x16x32_bf16 v[2:5], v[172:175], v[180:183], v[2:5]
	v_mfma_f32_16x16x32_bf16 v[10:13], v[164:167], v[188:191], v[10:13]
	v_mfma_f32_16x16x32_bf16 v[6:9], v[172:175], v[188:191], v[6:9]
	v_mfma_f32_16x16x32_bf16 v[26:29], v[164:167], v[196:199], v[26:29]
	v_mfma_f32_16x16x32_bf16 v[22:25], v[172:175], v[196:199], v[22:25]
	v_mfma_f32_16x16x32_bf16 v[50:53], v[164:167], v[204:207], v[50:53]
	v_mfma_f32_16x16x32_bf16 v[46:49], v[172:175], v[204:207], v[46:49]
	s_barrier
; #define PG8_STAGE(bufoff, gbase, voff) do { _Pragma("unroll") for (int _i = 0; _i < 2; ++_i) \
;         __builtin_amdgcn_global_load_lds((const unsigned*)((const char*)(gbase) + (voff)[_i]), (LAS unsigned*)(lds + (bufoff) + ldsw + _i * 8192), 16, 0, 0); } while (0)
; #define PG8_LDA(dst, b, h) do { _Pragma("unroll") for (int m = 0; m < 4; ++m) _Pragma("unroll") for (int k = 0; k < 2; ++k) dst[m][k] = *(const LAS bf16x8*)(lds + PG8_SA(b, h) + aoff + m * 2048 + k * 1024); } while (0)
; #define PG8_MMA(ai, bj, At, Bt) do { __builtin_amdgcn_s_setprio(1); _Pragma("unroll") for (int m = 0; m < 4; ++m) _Pragma("unroll") for (int n = 0; n < 2; ++n) _Pragma("unroll") for (int k = 0; k < 2; ++k) \
;         acc[ai][bj][m][n] = __builtin_amdgcn_mfma_f32_16x16x32_bf16(Bt[n][k], At[m][k], acc[ai][bj][m][n], 0, 0, 0); __builtin_amdgcn_s_setprio(0); } while (0)
; #define PG8_WAIT_V(n) asm volatile("s_waitcnt vmcnt(" #n ")" ::: "memory")
; #define PG8_WAIT_L(n) asm volatile("s_waitcnt lgkmcnt(" #n ")" ::: "memory")
; #define PG8_BAR __builtin_amdgcn_s_barrier()
; #define PG8_SCHED __builtin_amdgcn_sched_barrier(0)
; template <class Epi, class Sched, bool ALIGN_EPI, bool LAST_FUSED = false, bool PERM = false, bool CARRY = false>
; __device__ __forceinline__ void gemm_phase(LAS unsigned char* lds, const int tid, const int K, const int lda, const int ldb, const Sched& S, const Epi& E) {
;     ...
;             PG8_LDA(At, 1, 1); PG8_STAGE(PG8_SB(1, 0), b3, voffB); PG8_STAGE(PG8_SB(1, 1), b3 + hstepB, voffB); PG8_STAGE(PG8_SA(1, 0), a3, voffA);
;             PG8_WAIT_V(8); PG8_WAIT_L(0); PG8_BAR; PG8_MMA(1, 0, At, B0); PG8_MMA(1, 1, At, B1); PG8_BAR; PG8_SCHED;
;         }
;         if constexpr (ALIGN_EPI) { if (wr == 0) PG8_BAR; }
	s_setprio 0
	s_add_i32 s52, s96, s87
	v_lshl_add_u64 v[208:209], v[208:209], 0, s[68:69]
	s_mov_b32 m0, s52
	ds_read_b128 v[176:179], v141 offset:49152
	ds_read_b128 v[180:183], v141 offset:50176
	ds_read_b128 v[184:187], v141 offset:51200
	ds_read_b128 v[188:191], v141 offset:52224
	ds_read_b128 v[192:195], v141 offset:53248
	ds_read_b128 v[196:199], v141 offset:54272
	ds_read_b128 v[200:203], v141 offset:55296
	ds_read_b128 v[204:207], v141 offset:56320
	global_load_lds_dwordx4 v[208:209], off
	s_add_i32 m0, s52, 0x2000
	s_add_u32 s52, s76, 0x80080
	v_lshl_add_u64 v[208:209], v[210:211], 0, s[68:69]
	s_addc_u32 s53, s77, 0
	s_add_i32 s76, s97, s87
	global_load_lds_dwordx4 v[208:209], off
	v_lshl_add_u64 v[208:209], s[52:53], 0, v[0:1]
	s_mov_b32 m0, s76
	s_nop 0
	global_load_lds_dwordx4 v[208:209], off
	v_lshl_add_u64 v[208:209], s[52:53], 0, v[122:123]
	s_add_i32 m0, s76, 0x2000
	s_nop 0
	global_load_lds_dwordx4 v[208:209], off
	v_lshl_add_u64 v[208:209], v[212:213], 0, s[68:69]
	s_mov_b32 m0, s85
	s_nop 0
	global_load_lds_dwordx4 v[208:209], off
	v_lshl_add_u64 v[208:209], v[214:215], 0, s[68:69]
	s_mov_b32 m0, s89
	s_nop 0
	global_load_lds_dwordx4 v[208:209], off
	s_waitcnt vmcnt(8)
	s_waitcnt lgkmcnt(0)
	s_barrier
	v_mfma_f32_16x16x32_bf16 v[78:81], v[142:145], v[176:179], v[78:81]
	s_setprio 1
	v_mfma_f32_16x16x32_bf16 v[74:77], v[150:153], v[176:179], v[74:77]
	v_mfma_f32_16x16x32_bf16 v[98:101], v[142:145], v[184:187], v[98:101]
	v_mfma_f32_16x16x32_bf16 v[94:97], v[150:153], v[184:187], v[94:97]
	v_mfma_f32_16x16x32_bf16 v[118:121], v[142:145], v[192:195], v[118:121]
	v_mfma_f32_16x16x32_bf16 v[114:117], v[150:153], v[192:195], v[114:117]
	v_mfma_f32_16x16x32_bf16 v[134:137], v[142:145], v[200:203], v[134:137]
	v_mfma_f32_16x16x32_bf16 v[130:133], v[150:153], v[200:203], v[130:133]
	v_mfma_f32_16x16x32_bf16 v[78:81], v[146:149], v[180:183], v[78:81]
	v_mfma_f32_16x16x32_bf16 v[74:77], v[156:159], v[180:183], v[74:77]
	v_mfma_f32_16x16x32_bf16 v[98:101], v[146:149], v[188:191], v[98:101]
	v_mfma_f32_16x16x32_bf16 v[94:97], v[156:159], v[188:191], v[94:97]
	v_mfma_f32_16x16x32_bf16 v[118:121], v[146:149], v[196:199], v[118:121]
	v_mfma_f32_16x16x32_bf16 v[114:117], v[156:159], v[196:199], v[114:117]
	v_mfma_f32_16x16x32_bf16 v[134:137], v[146:149], v[204:207], v[134:137]
	v_mfma_f32_16x16x32_bf16 v[130:133], v[156:159], v[204:207], v[130:133]
	s_setprio 0
	s_setprio 1
	v_mfma_f32_16x16x32_bf16 v[70:73], v[160:163], v[176:179], v[70:73]
	v_mfma_f32_16x16x32_bf16 v[66:69], v[168:171], v[176:179], v[66:69]
	v_mfma_f32_16x16x32_bf16 v[90:93], v[160:163], v[184:187], v[90:93]
	v_mfma_f32_16x16x32_bf16 v[86:89], v[168:171], v[184:187], v[86:89]
	v_mfma_f32_16x16x32_bf16 v[110:113], v[160:163], v[192:195], v[110:113]
	v_mfma_f32_16x16x32_bf16 v[106:109], v[168:171], v[192:195], v[106:109]
	v_mfma_f32_16x16x32_bf16 v[102:105], v[160:163], v[200:203], v[102:105]
	v_mfma_f32_16x16x32_bf16 v[82:85], v[168:171], v[200:203], v[82:85]
	v_mfma_f32_16x16x32_bf16 v[70:73], v[164:167], v[180:183], v[70:73]
	v_mfma_f32_16x16x32_bf16 v[66:69], v[172:175], v[180:183], v[66:69]
	v_mfma_f32_16x16x32_bf16 v[90:93], v[164:167], v[188:191], v[90:93]
	v_mfma_f32_16x16x32_bf16 v[86:89], v[172:175], v[188:191], v[86:89]
	v_mfma_f32_16x16x32_bf16 v[110:113], v[164:167], v[196:199], v[110:113]
	v_mfma_f32_16x16x32_bf16 v[106:109], v[172:175], v[196:199], v[106:109]
	v_mfma_f32_16x16x32_bf16 v[102:105], v[164:167], v[204:207], v[102:105]
	v_mfma_f32_16x16x32_bf16 v[82:85], v[172:175], v[204:207], v[82:85]
	s_barrier
	s_setprio 0
	s_add_i32 s52, s95, 2
	s_add_u32 s48, s48, 0x100
	s_addc_u32 s49, s49, 0
	v_lshl_add_u64 v[138:139], v[138:139], 0, s[72:73]
	v_lshl_add_u64 v[128:129], v[128:129], 0, s[72:73]
	s_cmp_ge_i32 s95, s3
	s_mov_b32 s95, s52
	s_cbranch_scc0 .LBB0_1585
	s_and_b64 vcc, exec, s[36:37]
	s_cbranch_vccz .LBB0_1588
	s_barrier

; #define PG8_STAGE(bufoff, gbase, voff) do { _Pragma("unroll") for (int _i = 0; _i < 2; ++_i) \
;         __builtin_amdgcn_global_load_lds((const unsigned*)((const char*)(gbase) + (voff)[_i]), (LAS unsigned*)(lds + (bufoff) + ldsw + _i * 8192), 16, 0, 0); } while (0)
; #define PG8_LDA(dst, b, h) do { _Pragma("unroll") for (int m = 0; m < 4; ++m) _Pragma("unroll") for (int k = 0; k < 2; ++k) dst[m][k] = *(const LAS bf16x8*)(lds + PG8_SA(b, h) + aoff + m * 2048 + k * 1024); } while (0)
; #define PG8_LDB(dst, b, h) do { _Pragma("unroll") for (int n = 0; n < 2; ++n) _Pragma("unroll") for (int k = 0; k < 2; ++k) dst[n][k] = *(const LAS bf16x8*)(lds + PG8_SB(b, h) + boff + n * 2048 + k * 1024); } while (0)
; #define PG8_WAIT_V(n) asm volatile("s_waitcnt vmcnt(" #n ")" ::: "memory")
; #define PG8_WAIT_L(n) asm volatile("s_waitcnt lgkmcnt(" #n ")" ::: "memory")
; #define PG8_BAR __builtin_amdgcn_s_barrier()
; #define PG8_SCHED __builtin_amdgcn_sched_barrier(0)
; template <class Epi, class Sched, bool ALIGN_EPI, bool LAST_FUSED = false, bool PERM = false, bool CARRY = false>
; __device__ __forceinline__ void gemm_phase(LAS unsigned char* lds, const int tid, const int K, const int lda, const int ldb, const Sched& S, const Epi& E) {
;     ...
;         const bool has_next = S.next(KD_IDX(ui + 1), nxt);
;         const char* nA = has_next ? nxt.a : cA; const char* nB = has_next ? nxt.b : cB; const int nt = cur.nt;
; #pragma unroll 1
;         for (int t = 0; t < nt; t += 2) {
;             const bool last = (t == nt - 2);
;             const char* a1 = cA + (size_t)(t + 1) * kstep;
;             const char* a2 = last ? nA : cA + (size_t)(t + 2) * kstep; const char* b2 = last ? nB : cB + (size_t)(t + 2) * kstep;
;             const char* a3 = a2 + kstep; const char* b3 = b2 + kstep;
;             PG8_LDB(B0, 0, 0); PG8_LDB(B1, 0, 1); PG8_SCHED; PG8_LDA(At, 0, 0); PG8_STAGE(PG8_SA(1, 1), a1 + hstepA, voffA);
;             PG8_WAIT_V(8); PG8_WAIT_L(0); PG8_BAR; PG8_MMA(0, 0, At, B0); PG8_MMA(0, 1, At, B1); PG8_BAR; PG8_SCHED;
;             PG8_LDA(At, 0, 1); PG8_STAGE(PG8_SB(0, 0), b2, voffB); PG8_STAGE(PG8_SB(0, 1), b2 + hstepB, voffB); PG8_STAGE(PG8_SA(0, 0), a2, voffA);
;             PG8_WAIT_V(8); PG8_WAIT_L(0); PG8_BAR; PG8_MMA(1, 0, At, B0); PG8_MMA(1, 1, At, B1); PG8_BAR; PG8_SCHED;
.LBB0_1662:
	s_add_u32 s52, s38, s48
	s_addc_u32 s53, s39, s49
	s_add_u32 s66, s40, s48
	s_addc_u32 s67, s41, s49
	s_waitcnt lgkmcnt(0)
	s_add_i32 s90, 0, 0x10000
	s_cmp_eq_u32 s3, s89
	s_cselect_b32 s53, s24, s53
	s_cselect_b32 s52, s85, s52
	s_cselect_b32 s67, s86, s67
	s_cselect_b32 s66, s87, s66
	s_add_i32 s92, 0, 0x14000
	v_add_u32_e32 v156, s90, v140
	v_add_u32_e32 v172, s92, v140
	ds_read_b128 v[142:145], v156
	ds_read_b128 v[146:149], v156 offset:1024
	ds_read_b128 v[150:153], v156 offset:2048
	ds_read_b128 v[156:159], v156 offset:3072
	ds_read_b128 v[160:163], v172
	ds_read_b128 v[164:167], v172 offset:1024
	ds_read_b128 v[168:171], v172 offset:2048
	ds_read_b128 v[172:175], v172 offset:3072
	v_lshl_add_u64 v[208:209], s[38:39], 0, v[138:139]
	s_add_i32 m0, s35, 0xc000
	ds_read_b128 v[176:179], v141
	ds_read_b128 v[180:183], v141 offset:1024
	ds_read_b128 v[184:187], v141 offset:2048
	ds_read_b128 v[188:191], v141 offset:3072
	ds_read_b128 v[192:195], v141 offset:4096
	ds_read_b128 v[196:199], v141 offset:5120
	ds_read_b128 v[200:203], v141 offset:6144
	ds_read_b128 v[204:207], v141 offset:7168
	global_load_lds_dwordx4 v[208:209], off
	v_lshl_add_u64 v[208:209], s[38:39], 0, v[128:129]
	s_add_i32 m0, s35, 0xe000
	s_nop 0
	global_load_lds_dwordx4 v[208:209], off
	s_waitcnt vmcnt(8)
	s_waitcnt lgkmcnt(0)
	s_barrier
	v_mfma_f32_16x16x32_bf16 v[62:65], v[142:145], v[176:179], v[62:65]
	s_setprio 1
	v_mfma_f32_16x16x32_bf16 v[42:45], v[150:153], v[176:179], v[42:45]
	v_mfma_f32_16x16x32_bf16 v[18:21], v[142:145], v[184:187], v[18:21]
	v_mfma_f32_16x16x32_bf16 v[14:17], v[150:153], v[184:187], v[14:17]
	v_mfma_f32_16x16x32_bf16 v[38:41], v[142:145], v[192:195], v[38:41]
	v_mfma_f32_16x16x32_bf16 v[30:33], v[150:153], v[192:195], v[30:33]
	v_mfma_f32_16x16x32_bf16 v[58:61], v[142:145], v[200:203], v[58:61]
	v_mfma_f32_16x16x32_bf16 v[54:57], v[150:153], v[200:203], v[54:57]
	v_mfma_f32_16x16x32_bf16 v[62:65], v[146:149], v[180:183], v[62:65]
	v_mfma_f32_16x16x32_bf16 v[42:45], v[156:159], v[180:183], v[42:45]
	v_mfma_f32_16x16x32_bf16 v[18:21], v[146:149], v[188:191], v[18:21]
	v_mfma_f32_16x16x32_bf16 v[14:17], v[156:159], v[188:191], v[14:17]
	v_mfma_f32_16x16x32_bf16 v[38:41], v[146:149], v[196:199], v[38:41]
	v_mfma_f32_16x16x32_bf16 v[30:33], v[156:159], v[196:199], v[30:33]
	v_mfma_f32_16x16x32_bf16 v[58:61], v[146:149], v[204:207], v[58:61]
	v_mfma_f32_16x16x32_bf16 v[54:57], v[156:159], v[204:207], v[54:57]
	s_setprio 0
	s_setprio 1
	v_mfma_f32_16x16x32_bf16 v[34:37], v[160:163], v[176:179], v[34:37]
	v_mfma_f32_16x16x32_bf16 v[2:5], v[168:171], v[176:179], v[2:5]
	v_mfma_f32_16x16x32_bf16 v[10:13], v[160:163], v[184:187], v[10:13]
	v_mfma_f32_16x16x32_bf16 v[6:9], v[168:171], v[184:187], v[6:9]
	v_mfma_f32_16x16x32_bf16 v[26:29], v[160:163], v[192:195], v[26:29]
	v_mfma_f32_16x16x32_bf16 v[22:25], v[168:171], v[192:195], v[22:25]
	v_mfma_f32_16x16x32_bf16 v[50:53], v[160:163], v[200:203], v[50:53]
	v_mfma_f32_16x16x32_bf16 v[46:49], v[168:171], v[200:203], v[46:49]
	v_mfma_f32_16x16x32_bf16 v[34:37], v[164:167], v[180:183], v[34:37]
	v_mfma_f32_16x16x32_bf16 v[2:5], v[172:175], v[180:183], v[2:5]
	v_mfma_f32_16x16x32_bf16 v[10:13], v[164:167], v[188:191], v[10:13]
	v_mfma_f32_16x16x32_bf16 v[6:9], v[172:175], v[188:191], v[6:9]
	v_mfma_f32_16x16x32_bf16 v[26:29], v[164:167], v[196:199], v[26:29]
	v_mfma_f32_16x16x32_bf16 v[22:25], v[172:175], v[196:199], v[22:25]
	v_mfma_f32_16x16x32_bf16 v[50:53], v[164:167], v[204:207], v[50:53]
	v_mfma_f32_16x16x32_bf16 v[46:49], v[172:175], v[204:207], v[46:49]
	s_barrier
	s_setprio 0
	s_add_i32 s90, s90, s76
	v_lshl_add_u64 v[208:209], s[66:67], 0, v[0:1]
	s_mov_b32 m0, s90
	ds_read_b128 v[176:179], v141 offset:16384
	ds_read_b128 v[180:183], v141 offset:17408
	ds_read_b128 v[184:187], v141 offset:18432
	ds_read_b128 v[188:191], v141 offset:19456
	ds_read_b128 v[192:195], v141 offset:20480
	ds_read_b128 v[196:199], v141 offset:21504
	ds_read_b128 v[200:203], v141 offset:22528
	ds_read_b128 v[204:207], v141 offset:23552
	global_load_lds_dwordx4 v[208:209], off
	s_add_i32 m0, s90, 0x2000
	s_add_u32 s90, s66, 0x100000
	v_lshl_add_u64 v[210:211], s[66:67], 0, v[122:123]
	s_addc_u32 s91, s67, 0
	s_add_i32 s92, s92, s76
	global_load_lds_dwordx4 v[210:211], off
	v_lshl_add_u64 v[212:213], s[90:91], 0, v[0:1]
	s_mov_b32 m0, s92
	v_lshl_add_u64 v[214:215], s[52:53], 0, v[122:123]
	global_load_lds_dwordx4 v[212:213], off
	v_lshl_add_u64 v[212:213], s[90:91], 0, v[122:123]
	s_add_i32 m0, s92, 0x2000
	s_nop 0
	global_load_lds_dwordx4 v[212:213], off
	v_lshl_add_u64 v[212:213], s[52:53], 0, v[0:1]
	s_mov_b32 m0, s35
	s_nop 0
	global_load_lds_dwordx4 v[212:213], off
	s_mov_b32 m0, s28
	s_nop 0
	global_load_lds_dwordx4 v[214:215], off
	s_waitcnt vmcnt(8)
	s_waitcnt lgkmcnt(0)
	s_barrier
; #define PG8_STAGE(bufoff, gbase, voff) do { _Pragma("unroll") for (int _i = 0; _i < 2; ++_i) \
;         __builtin_amdgcn_global_load_lds((const unsigned*)((const char*)(gbase) + (voff)[_i]), (LAS unsigned*)(lds + (bufoff) + ldsw + _i * 8192), 16, 0, 0); } while (0)
; #define PG8_LDA(dst, b, h) do { _Pragma("unroll") for (int m = 0; m < 4; ++m) _Pragma("unroll") for (int k = 0; k < 2; ++k) dst[m][k] = *(const LAS bf16x8*)(lds + PG8_SA(b, h) + aoff + m * 2048 + k * 1024); } while (0)
; #define PG8_LDB(dst, b, h) do { _Pragma("unroll") for (int n = 0; n < 2; ++n) _Pragma("unroll") for (int k = 0; k < 2; ++k) dst[n][k] = *(const LAS bf16x8*)(lds + PG8_SB(b, h) + boff + n * 2048 + k * 1024); } while (0)
; #define PG8_MMA(ai, bj, At, Bt) do { __builtin_amdgcn_s_setprio(1); _Pragma("unroll") for (int m = 0; m < 4; ++m) _Pragma("unroll") for (int n = 0; n < 2; ++n) _Pragma("unroll") for (int k = 0; k < 2; ++k) \
;         acc[ai][bj][m][n] = __builtin_amdgcn_mfma_f32_16x16x32_bf16(Bt[n][k], At[m][k], acc[ai][bj][m][n], 0, 0, 0); __builtin_amdgcn_s_setprio(0); } while (0)
; #define PG8_WAIT_V(n) asm volatile("s_waitcnt vmcnt(" #n ")" ::: "memory")
; #define PG8_WAIT_L(n) asm volatile("s_waitcnt lgkmcnt(" #n ")" ::: "memory")
; #define PG8_BAR __builtin_amdgcn_s_barrier()
; #define PG8_SCHED __builtin_amdgcn_sched_barrier(0)
; template <class Epi, class Sched, bool ALIGN_EPI, bool LAST_FUSED = false, bool PERM = false, bool CARRY = false>
; __device__ __forceinline__ void gemm_phase(LAS unsigned char* lds, const int tid, const int K, const int lda, const int ldb, const Sched& S, const Epi& E) {
;     ...
;             PG8_WAIT_V(8); PG8_WAIT_L(0); PG8_BAR; PG8_MMA(1, 0, At, B0); PG8_MMA(1, 1, At, B1); PG8_BAR; PG8_SCHED;
;             PG8_LDB(B0, 1, 0); PG8_LDB(B1, 1, 1); PG8_SCHED; PG8_LDA(At, 1, 0); PG8_STAGE(PG8_SA(0, 1), a2 + hstepA, voffA);
;             PG8_WAIT_V(8); PG8_WAIT_L(0); PG8_BAR; PG8_MMA(0, 0, At, B0); PG8_MMA(0, 1, At, B1); PG8_BAR; PG8_SCHED;
	v_mfma_f32_16x16x32_bf16 v[78:81], v[142:145], v[176:179], v[78:81]
	s_setprio 1
	v_mfma_f32_16x16x32_bf16 v[74:77], v[150:153], v[176:179], v[74:77]
	v_mfma_f32_16x16x32_bf16 v[98:101], v[142:145], v[184:187], v[98:101]
	v_mfma_f32_16x16x32_bf16 v[94:97], v[150:153], v[184:187], v[94:97]
	v_mfma_f32_16x16x32_bf16 v[118:121], v[142:145], v[192:195], v[118:121]
	v_mfma_f32_16x16x32_bf16 v[114:117], v[150:153], v[192:195], v[114:117]
	v_mfma_f32_16x16x32_bf16 v[134:137], v[142:145], v[200:203], v[134:137]
	v_mfma_f32_16x16x32_bf16 v[130:133], v[150:153], v[200:203], v[130:133]
	v_mfma_f32_16x16x32_bf16 v[78:81], v[146:149], v[180:183], v[78:81]
	v_mfma_f32_16x16x32_bf16 v[74:77], v[156:159], v[180:183], v[74:77]
	v_mfma_f32_16x16x32_bf16 v[98:101], v[146:149], v[188:191], v[98:101]
	v_mfma_f32_16x16x32_bf16 v[94:97], v[156:159], v[188:191], v[94:97]
	v_mfma_f32_16x16x32_bf16 v[118:121], v[146:149], v[196:199], v[118:121]
	v_mfma_f32_16x16x32_bf16 v[114:117], v[156:159], v[196:199], v[114:117]
	v_mfma_f32_16x16x32_bf16 v[134:137], v[146:149], v[204:207], v[134:137]
	v_mfma_f32_16x16x32_bf16 v[130:133], v[156:159], v[204:207], v[130:133]
	s_setprio 0
	s_setprio 1
	v_mfma_f32_16x16x32_bf16 v[70:73], v[160:163], v[176:179], v[70:73]
	v_mfma_f32_16x16x32_bf16 v[66:69], v[168:171], v[176:179], v[66:69]
	v_mfma_f32_16x16x32_bf16 v[90:93], v[160:163], v[184:187], v[90:93]
	v_mfma_f32_16x16x32_bf16 v[86:89], v[168:171], v[184:187], v[86:89]
	v_mfma_f32_16x16x32_bf16 v[110:113], v[160:163], v[192:195], v[110:113]
	v_mfma_f32_16x16x32_bf16 v[106:109], v[168:171], v[192:195], v[106:109]
	v_mfma_f32_16x16x32_bf16 v[102:105], v[160:163], v[200:203], v[102:105]
	v_mfma_f32_16x16x32_bf16 v[82:85], v[168:171], v[200:203], v[82:85]
	v_mfma_f32_16x16x32_bf16 v[70:73], v[164:167], v[180:183], v[70:73]
	v_mfma_f32_16x16x32_bf16 v[66:69], v[172:175], v[180:183], v[66:69]
	v_mfma_f32_16x16x32_bf16 v[90:93], v[164:167], v[188:191], v[90:93]
	v_mfma_f32_16x16x32_bf16 v[86:89], v[172:175], v[188:191], v[86:89]
	v_mfma_f32_16x16x32_bf16 v[110:113], v[164:167], v[196:199], v[110:113]
	v_mfma_f32_16x16x32_bf16 v[106:109], v[172:175], v[196:199], v[106:109]
	v_mfma_f32_16x16x32_bf16 v[102:105], v[164:167], v[204:207], v[102:105]
	v_mfma_f32_16x16x32_bf16 v[82:85], v[172:175], v[204:207], v[82:85]
	s_barrier
	s_setprio 0
	s_add_i32 s90, 0, 0x18000
	s_add_i32 s91, 0, 0x1c000
	v_add_u32_e32 v156, s90, v140
	v_add_u32_e32 v172, s91, v140
	ds_read_b128 v[142:145], v156
	ds_read_b128 v[146:149], v156 offset:1024
	ds_read_b128 v[150:153], v156 offset:2048
	ds_read_b128 v[156:159], v156 offset:3072
	ds_read_b128 v[160:163], v172
	ds_read_b128 v[164:167], v172 offset:1024
	ds_read_b128 v[168:171], v172 offset:2048
	ds_read_b128 v[172:175], v172 offset:3072
	s_add_u32 s52, s52, 0x100000
	s_addc_u32 s53, s53, 0
	s_mov_b32 m0, s29
	v_lshl_add_u64 v[216:217], s[52:53], 0, v[0:1]
	ds_read_b128 v[176:179], v141 offset:32768
	ds_read_b128 v[180:183], v141 offset:33792
	ds_read_b128 v[184:187], v141 offset:34816
	ds_read_b128 v[188:191], v141 offset:35840
	ds_read_b128 v[192:195], v141 offset:36864
	ds_read_b128 v[196:199], v141 offset:37888
	ds_read_b128 v[200:203], v141 offset:38912
	ds_read_b128 v[204:207], v141 offset:39936
	global_load_lds_dwordx4 v[216:217], off
	v_lshl_add_u64 v[216:217], s[52:53], 0, v[122:123]
	s_mov_b32 m0, s14
	s_nop 0
	global_load_lds_dwordx4 v[216:217], off
	s_waitcnt vmcnt(8)
	s_waitcnt lgkmcnt(0)
	s_barrier
	v_mfma_f32_16x16x32_bf16 v[62:65], v[142:145], v[176:179], v[62:65]
	s_setprio 1
	v_mfma_f32_16x16x32_bf16 v[42:45], v[150:153], v[176:179], v[42:45]
	v_mfma_f32_16x16x32_bf16 v[18:21], v[142:145], v[184:187], v[18:21]
	v_mfma_f32_16x16x32_bf16 v[14:17], v[150:153], v[184:187], v[14:17]
	v_mfma_f32_16x16x32_bf16 v[38:41], v[142:145], v[192:195], v[38:41]
	v_mfma_f32_16x16x32_bf16 v[30:33], v[150:153], v[192:195], v[30:33]
	v_mfma_f32_16x16x32_bf16 v[58:61], v[142:145], v[200:203], v[58:61]
	v_mfma_f32_16x16x32_bf16 v[54:57], v[150:153], v[200:203], v[54:57]
	v_mfma_f32_16x16x32_bf16 v[62:65], v[146:149], v[180:183], v[62:65]
	v_mfma_f32_16x16x32_bf16 v[42:45], v[156:159], v[180:183], v[42:45]
	v_mfma_f32_16x16x32_bf16 v[18:21], v[146:149], v[188:191], v[18:21]
	v_mfma_f32_16x16x32_bf16 v[14:17], v[156:159], v[188:191], v[14:17]
	v_mfma_f32_16x16x32_bf16 v[38:41], v[146:149], v[196:199], v[38:41]
	v_mfma_f32_16x16x32_bf16 v[30:33], v[156:159], v[196:199], v[30:33]
	v_mfma_f32_16x16x32_bf16 v[58:61], v[146:149], v[204:207], v[58:61]
	v_mfma_f32_16x16x32_bf16 v[54:57], v[156:159], v[204:207], v[54:57]
	s_setprio 0
	s_setprio 1
	v_mfma_f32_16x16x32_bf16 v[34:37], v[160:163], v[176:179], v[34:37]
	v_mfma_f32_16x16x32_bf16 v[2:5], v[168:171], v[176:179], v[2:5]
	v_mfma_f32_16x16x32_bf16 v[10:13], v[160:163], v[184:187], v[10:13]
	v_mfma_f32_16x16x32_bf16 v[6:9], v[168:171], v[184:187], v[6:9]
	v_mfma_f32_16x16x32_bf16 v[26:29], v[160:163], v[192:195], v[26:29]
	v_mfma_f32_16x16x32_bf16 v[22:25], v[168:171], v[192:195], v[22:25]
	v_mfma_f32_16x16x32_bf16 v[50:53], v[160:163], v[200:203], v[50:53]
	v_mfma_f32_16x16x32_bf16 v[46:49], v[168:171], v[200:203], v[46:49]
	v_mfma_f32_16x16x32_bf16 v[34:37], v[164:167], v[180:183], v[34:37]
	v_mfma_f32_16x16x32_bf16 v[2:5], v[172:175], v[180:183], v[2:5]
	v_mfma_f32_16x16x32_bf16 v[10:13], v[164:167], v[188:191], v[10:13]
	v_mfma_f32_16x16x32_bf16 v[6:9], v[172:175], v[188:191], v[6:9]
	v_mfma_f32_16x16x32_bf16 v[26:29], v[164:167], v[196:199], v[26:29]
	v_mfma_f32_16x16x32_bf16 v[22:25], v[172:175], v[196:199], v[22:25]
	v_mfma_f32_16x16x32_bf16 v[50:53], v[164:167], v[204:207], v[50:53]
	v_mfma_f32_16x16x32_bf16 v[46:49], v[172:175], v[204:207], v[46:49]
	s_barrier
; #define PG8_STAGE(bufoff, gbase, voff) do { _Pragma("unroll") for (int _i = 0; _i < 2; ++_i) \
;         __builtin_amdgcn_global_load_lds((const unsigned*)((const char*)(gbase) + (voff)[_i]), (LAS unsigned*)(lds + (bufoff) + ldsw + _i * 8192), 16, 0, 0); } while (0)
; #define PG8_LDA(dst, b, h) do { _Pragma("unroll") for (int m = 0; m < 4; ++m) _Pragma("unroll") for (int k = 0; k < 2; ++k) dst[m][k] = *(const LAS bf16x8*)(lds + PG8_SA(b, h) + aoff + m * 2048 + k * 1024); } while (0)
; #define PG8_MMA(ai, bj, At, Bt) do { __builtin_amdgcn_s_setprio(1); _Pragma("unroll") for (int m = 0; m < 4; ++m) _Pragma("unroll") for (int n = 0; n < 2; ++n) _Pragma("unroll") for (int k = 0; k < 2; ++k) \
;         acc[ai][bj][m][n] = __builtin_amdgcn_mfma_f32_16x16x32_bf16(Bt[n][k], At[m][k], acc[ai][bj][m][n], 0, 0, 0); __builtin_amdgcn_s_setprio(0); } while (0)
; #define PG8_WAIT_V(n) asm volatile("s_waitcnt vmcnt(" #n ")" ::: "memory")
; #define PG8_WAIT_L(n) asm volatile("s_waitcnt lgkmcnt(" #n ")" ::: "memory")
; #define PG8_BAR __builtin_amdgcn_s_barrier()
; #define PG8_SCHED __builtin_amdgcn_sched_barrier(0)
; template <class Epi, class Sched, bool ALIGN_EPI, bool LAST_FUSED = false, bool PERM = false, bool CARRY = false>
; __device__ __forceinline__ void gemm_phase(LAS unsigned char* lds, const int tid, const int K, const int lda, const int ldb, const Sched& S, const Epi& E) {
;     ...
;             PG8_LDA(At, 1, 1); PG8_STAGE(PG8_SB(1, 0), b3, voffB); PG8_STAGE(PG8_SB(1, 1), b3 + hstepB, voffB); PG8_STAGE(PG8_SA(1, 0), a3, voffA);
;             PG8_WAIT_V(8); PG8_WAIT_L(0); PG8_BAR; PG8_MMA(1, 0, At, B0); PG8_MMA(1, 1, At, B1); PG8_BAR; PG8_SCHED;
;         }
;         if constexpr (ALIGN_EPI) { if (wr == 0) PG8_BAR; }
	s_setprio 0
	s_add_i32 s52, s90, s76
	v_lshl_add_u64 v[208:209], v[208:209], 0, s[68:69]
	s_mov_b32 m0, s52
	ds_read_b128 v[176:179], v141 offset:49152
	ds_read_b128 v[180:183], v141 offset:50176
	ds_read_b128 v[184:187], v141 offset:51200
	ds_read_b128 v[188:191], v141 offset:52224
	ds_read_b128 v[192:195], v141 offset:53248
	ds_read_b128 v[196:199], v141 offset:54272
	ds_read_b128 v[200:203], v141 offset:55296
	ds_read_b128 v[204:207], v141 offset:56320
	global_load_lds_dwordx4 v[208:209], off
	s_add_i32 m0, s52, 0x2000
	s_add_u32 s52, s66, 0x100080
	v_lshl_add_u64 v[208:209], v[210:211], 0, s[68:69]
	s_addc_u32 s53, s67, 0
	s_add_i32 s66, s91, s76
	global_load_lds_dwordx4 v[208:209], off
	v_lshl_add_u64 v[208:209], s[52:53], 0, v[0:1]
	s_mov_b32 m0, s66
	s_nop 0
	global_load_lds_dwordx4 v[208:209], off
	v_lshl_add_u64 v[208:209], s[52:53], 0, v[122:123]
	s_add_i32 m0, s66, 0x2000
	s_nop 0
	global_load_lds_dwordx4 v[208:209], off
	v_lshl_add_u64 v[208:209], v[212:213], 0, s[68:69]
	s_mov_b32 m0, s77
	s_nop 0
	global_load_lds_dwordx4 v[208:209], off
	v_lshl_add_u64 v[208:209], v[214:215], 0, s[68:69]
	s_mov_b32 m0, s79
	s_nop 0
	global_load_lds_dwordx4 v[208:209], off
	s_waitcnt vmcnt(8)
	s_waitcnt lgkmcnt(0)
	s_barrier
	v_mfma_f32_16x16x32_bf16 v[78:81], v[142:145], v[176:179], v[78:81]
	s_setprio 1
	v_mfma_f32_16x16x32_bf16 v[74:77], v[150:153], v[176:179], v[74:77]
	v_mfma_f32_16x16x32_bf16 v[98:101], v[142:145], v[184:187], v[98:101]
	v_mfma_f32_16x16x32_bf16 v[94:97], v[150:153], v[184:187], v[94:97]
	v_mfma_f32_16x16x32_bf16 v[118:121], v[142:145], v[192:195], v[118:121]
	v_mfma_f32_16x16x32_bf16 v[114:117], v[150:153], v[192:195], v[114:117]
	v_mfma_f32_16x16x32_bf16 v[134:137], v[142:145], v[200:203], v[134:137]
	v_mfma_f32_16x16x32_bf16 v[130:133], v[150:153], v[200:203], v[130:133]
	v_mfma_f32_16x16x32_bf16 v[78:81], v[146:149], v[180:183], v[78:81]
	v_mfma_f32_16x16x32_bf16 v[74:77], v[156:159], v[180:183], v[74:77]
	v_mfma_f32_16x16x32_bf16 v[98:101], v[146:149], v[188:191], v[98:101]
	v_mfma_f32_16x16x32_bf16 v[94:97], v[156:159], v[188:191], v[94:97]
	v_mfma_f32_16x16x32_bf16 v[118:121], v[146:149], v[196:199], v[118:121]
	v_mfma_f32_16x16x32_bf16 v[114:117], v[156:159], v[196:199], v[114:117]
	v_mfma_f32_16x16x32_bf16 v[134:137], v[146:149], v[204:207], v[134:137]
	v_mfma_f32_16x16x32_bf16 v[130:133], v[156:159], v[204:207], v[130:133]
	s_setprio 0
	s_setprio 1
	v_mfma_f32_16x16x32_bf16 v[70:73], v[160:163], v[176:179], v[70:73]
	v_mfma_f32_16x16x32_bf16 v[66:69], v[168:171], v[176:179], v[66:69]
	v_mfma_f32_16x16x32_bf16 v[90:93], v[160:163], v[184:187], v[90:93]
	v_mfma_f32_16x16x32_bf16 v[86:89], v[168:171], v[184:187], v[86:89]
	v_mfma_f32_16x16x32_bf16 v[110:113], v[160:163], v[192:195], v[110:113]
	v_mfma_f32_16x16x32_bf16 v[106:109], v[168:171], v[192:195], v[106:109]
	v_mfma_f32_16x16x32_bf16 v[102:105], v[160:163], v[200:203], v[102:105]
	v_mfma_f32_16x16x32_bf16 v[82:85], v[168:171], v[200:203], v[82:85]
	v_mfma_f32_16x16x32_bf16 v[70:73], v[164:167], v[180:183], v[70:73]
	v_mfma_f32_16x16x32_bf16 v[66:69], v[172:175], v[180:183], v[66:69]
	v_mfma_f32_16x16x32_bf16 v[90:93], v[164:167], v[188:191], v[90:93]
	v_mfma_f32_16x16x32_bf16 v[86:89], v[172:175], v[188:191], v[86:89]
	v_mfma_f32_16x16x32_bf16 v[110:113], v[164:167], v[196:199], v[110:113]
	v_mfma_f32_16x16x32_bf16 v[106:109], v[172:175], v[196:199], v[106:109]
	v_mfma_f32_16x16x32_bf16 v[102:105], v[164:167], v[204:207], v[102:105]
	v_mfma_f32_16x16x32_bf16 v[82:85], v[172:175], v[204:207], v[82:85]
	s_barrier
	s_setprio 0
	s_add_i32 s52, s89, 2
	s_add_u32 s48, s48, 0x100
	s_addc_u32 s49, s49, 0
	v_lshl_add_u64 v[138:139], v[138:139], 0, s[72:73]
	v_lshl_add_u64 v[128:129], v[128:129], 0, s[72:73]
	s_cmp_ge_i32 s89, s3
	s_mov_b32 s89, s52
	s_cbranch_scc0 .LBB0_1662
	s_and_b64 vcc, exec, s[36:37]
	s_cbranch_vccz .LBB0_1665
	s_barrier

; #define PG8_STAGE(bufoff, gbase, voff) do { _Pragma("unroll") for (int _i = 0; _i < 2; ++_i) \
;         __builtin_amdgcn_global_load_lds((const unsigned*)((const char*)(gbase) + (voff)[_i]), (LAS unsigned*)(lds + (bufoff) + ldsw + _i * 8192), 16, 0, 0); } while (0)
; #define PG8_LDA(dst, b, h) do { _Pragma("unroll") for (int m = 0; m < 4; ++m) _Pragma("unroll") for (int k = 0; k < 2; ++k) dst[m][k] = *(const LAS bf16x8*)(lds + PG8_SA(b, h) + aoff + m * 2048 + k * 1024); } while (0)
; #define PG8_LDB(dst, b, h) do { _Pragma("unroll") for (int n = 0; n < 2; ++n) _Pragma("unroll") for (int k = 0; k < 2; ++k) dst[n][k] = *(const LAS bf16x8*)(lds + PG8_SB(b, h) + boff + n * 2048 + k * 1024); } while (0)
; #define PG8_WAIT_V(n) asm volatile("s_waitcnt vmcnt(" #n ")" ::: "memory")
; #define PG8_WAIT_L(n) asm volatile("s_waitcnt lgkmcnt(" #n ")" ::: "memory")
; #define PG8_BAR __builtin_amdgcn_s_barrier()
; #define PG8_SCHED __builtin_amdgcn_sched_barrier(0)
; template <class Epi, class Sched, bool ALIGN_EPI, bool LAST_FUSED = false, bool PERM = false, bool CARRY = false>
; __device__ __forceinline__ void gemm_phase(LAS unsigned char* lds, const int tid, const int K, const int lda, const int ldb, const Sched& S, const Epi& E) {
;     ...
;         const bool has_next = S.next(KD_IDX(ui + 1), nxt);
;         const char* nA = has_next ? nxt.a : cA; const char* nB = has_next ? nxt.b : cB; const int nt = cur.nt;
; #pragma unroll 1
;         for (int t = 0; t < nt; t += 2) {
;             const bool last = (t == nt - 2);
;             const char* a1 = cA + (size_t)(t + 1) * kstep;
;             const char* a2 = last ? nA : cA + (size_t)(t + 2) * kstep; const char* b2 = last ? nB : cB + (size_t)(t + 2) * kstep;
;             const char* a3 = a2 + kstep; const char* b3 = b2 + kstep;
;             PG8_LDB(B0, 0, 0); PG8_LDB(B1, 0, 1); PG8_SCHED; PG8_LDA(At, 0, 0); PG8_STAGE(PG8_SA(1, 1), a1 + hstepA, voffA);
;             PG8_WAIT_V(8); PG8_WAIT_L(0); PG8_BAR; PG8_MMA(0, 0, At, B0); PG8_MMA(0, 1, At, B1); PG8_BAR; PG8_SCHED;
;             PG8_LDA(At, 0, 1); PG8_STAGE(PG8_SB(0, 0), b2, voffB); PG8_STAGE(PG8_SB(0, 1), b2 + hstepB, voffB); PG8_STAGE(PG8_SA(0, 0), a2, voffA);
;             PG8_WAIT_V(8); PG8_WAIT_L(0); PG8_BAR; PG8_MMA(1, 0, At, B0); PG8_MMA(1, 1, At, B1); PG8_BAR; PG8_SCHED;
.LBB0_1763:
	s_add_u32 s16, s48, 0xfff80080
	s_addc_u32 s17, s49, -1
	s_add_i32 s67, 0, 0x10000
	s_cmp_eq_u32 s41, 28
	s_cselect_b32 s53, s43, s17
	s_cselect_b32 s52, s42, s16
	v_add_u32_e32 v140, s67, v146
	s_cselect_b32 s55, s51, s39
	s_cselect_b32 s54, s50, s27
	s_add_i32 s16, 0, 0x14000
	ds_read_b128 v[148:151], v140
	ds_read_b128 v[152:155], v140 offset:1024
	ds_read_b128 v[156:159], v140 offset:2048
	ds_read_b128 v[160:163], v140 offset:3072
	v_add_u32_e32 v140, s16, v146
	ds_read_b128 v[164:167], v140
	ds_read_b128 v[168:171], v140 offset:1024
	ds_read_b128 v[172:175], v140 offset:2048
	ds_read_b128 v[176:179], v140 offset:3072
	v_lshl_add_u64 v[140:141], s[48:49], 0, v[136:137]
	s_add_i32 m0, s47, 0xc000
	ds_read_b128 v[180:183], v147
	ds_read_b128 v[184:187], v147 offset:1024
	ds_read_b128 v[188:191], v147 offset:2048
	ds_read_b128 v[192:195], v147 offset:3072
	ds_read_b128 v[196:199], v147 offset:4096
	ds_read_b128 v[200:203], v147 offset:5120
	ds_read_b128 v[204:207], v147 offset:6144
	ds_read_b128 v[208:211], v147 offset:7168
	global_load_lds_dwordx4 v[140:141], off
	v_lshl_add_u64 v[140:141], s[48:49], 0, v[138:139]
	s_add_i32 m0, s47, 0xe000
	s_nop 0
	global_load_lds_dwordx4 v[140:141], off
	s_waitcnt vmcnt(8)
	s_waitcnt lgkmcnt(0)
	s_barrier
	v_mfma_f32_16x16x32_bf16 v[126:129], v[148:151], v[180:183], v[126:129]
	s_setprio 1
	v_mfma_f32_16x16x32_bf16 v[122:125], v[156:159], v[180:183], v[122:125]
	v_mfma_f32_16x16x32_bf16 v[110:113], v[148:151], v[188:191], v[110:113]
	v_mfma_f32_16x16x32_bf16 v[106:109], v[156:159], v[188:191], v[106:109]
	v_mfma_f32_16x16x32_bf16 v[94:97], v[148:151], v[196:199], v[94:97]
	v_mfma_f32_16x16x32_bf16 v[90:93], v[156:159], v[196:199], v[90:93]
	v_mfma_f32_16x16x32_bf16 v[78:81], v[148:151], v[204:207], v[78:81]
	v_mfma_f32_16x16x32_bf16 v[74:77], v[156:159], v[204:207], v[74:77]
	v_mfma_f32_16x16x32_bf16 v[126:129], v[152:155], v[184:187], v[126:129]
	v_mfma_f32_16x16x32_bf16 v[122:125], v[160:163], v[184:187], v[122:125]
	v_mfma_f32_16x16x32_bf16 v[110:113], v[152:155], v[192:195], v[110:113]
	v_mfma_f32_16x16x32_bf16 v[106:109], v[160:163], v[192:195], v[106:109]
	v_mfma_f32_16x16x32_bf16 v[94:97], v[152:155], v[200:203], v[94:97]
	v_mfma_f32_16x16x32_bf16 v[90:93], v[160:163], v[200:203], v[90:93]
	v_mfma_f32_16x16x32_bf16 v[78:81], v[152:155], v[208:211], v[78:81]
	v_mfma_f32_16x16x32_bf16 v[74:77], v[160:163], v[208:211], v[74:77]
	s_setprio 0
	s_setprio 1
	v_mfma_f32_16x16x32_bf16 v[118:121], v[164:167], v[180:183], v[118:121]
	v_mfma_f32_16x16x32_bf16 v[114:117], v[172:175], v[180:183], v[114:117]
	v_mfma_f32_16x16x32_bf16 v[102:105], v[164:167], v[188:191], v[102:105]
	v_mfma_f32_16x16x32_bf16 v[98:101], v[172:175], v[188:191], v[98:101]
	v_mfma_f32_16x16x32_bf16 v[86:89], v[164:167], v[196:199], v[86:89]
	v_mfma_f32_16x16x32_bf16 v[82:85], v[172:175], v[196:199], v[82:85]
	v_mfma_f32_16x16x32_bf16 v[70:73], v[164:167], v[204:207], v[70:73]
	v_mfma_f32_16x16x32_bf16 v[66:69], v[172:175], v[204:207], v[66:69]
	v_mfma_f32_16x16x32_bf16 v[118:121], v[168:171], v[184:187], v[118:121]
	v_mfma_f32_16x16x32_bf16 v[114:117], v[176:179], v[184:187], v[114:117]
	v_mfma_f32_16x16x32_bf16 v[102:105], v[168:171], v[192:195], v[102:105]
	v_mfma_f32_16x16x32_bf16 v[98:101], v[176:179], v[192:195], v[98:101]
	v_mfma_f32_16x16x32_bf16 v[86:89], v[168:171], v[200:203], v[86:89]
	v_mfma_f32_16x16x32_bf16 v[82:85], v[176:179], v[200:203], v[82:85]
	v_mfma_f32_16x16x32_bf16 v[70:73], v[168:171], v[208:211], v[70:73]
	v_mfma_f32_16x16x32_bf16 v[66:69], v[176:179], v[208:211], v[66:69]
	s_barrier
	s_setprio 0
	s_add_i32 s17, s67, s45
	v_lshl_add_u64 v[140:141], s[54:55], 0, v[0:1]
	s_mov_b32 m0, s17
	ds_read_b128 v[180:183], v147 offset:16384
	ds_read_b128 v[184:187], v147 offset:17408
	ds_read_b128 v[188:191], v147 offset:18432
	ds_read_b128 v[192:195], v147 offset:19456
	ds_read_b128 v[196:199], v147 offset:20480
	ds_read_b128 v[200:203], v147 offset:21504
	ds_read_b128 v[204:207], v147 offset:22528
	ds_read_b128 v[208:211], v147 offset:23552
	global_load_lds_dwordx4 v[140:141], off
	s_add_i32 m0, s17, 0x2000
	s_add_u32 s70, s54, 0x80000
	v_lshl_add_u64 v[212:213], s[54:55], 0, v[130:131]
	s_addc_u32 s71, s55, 0
	s_add_i32 s16, s16, s45
	global_load_lds_dwordx4 v[212:213], off
	v_lshl_add_u64 v[214:215], s[70:71], 0, v[0:1]
	s_mov_b32 m0, s16
	v_lshl_add_u64 v[216:217], s[52:53], 0, v[132:133]
	global_load_lds_dwordx4 v[214:215], off
	v_lshl_add_u64 v[214:215], s[70:71], 0, v[130:131]
	s_add_i32 m0, s16, 0x2000
	s_nop 0
	global_load_lds_dwordx4 v[214:215], off
	v_lshl_add_u64 v[214:215], s[52:53], 0, v[134:135]
	s_mov_b32 m0, s47
	s_nop 0
	global_load_lds_dwordx4 v[214:215], off
	s_mov_b32 m0, s57
	s_nop 0
	global_load_lds_dwordx4 v[216:217], off
	s_waitcnt vmcnt(8)
	s_waitcnt lgkmcnt(0)
	s_barrier
; #define PG8_STAGE(bufoff, gbase, voff) do { _Pragma("unroll") for (int _i = 0; _i < 2; ++_i) \
;         __builtin_amdgcn_global_load_lds((const unsigned*)((const char*)(gbase) + (voff)[_i]), (LAS unsigned*)(lds + (bufoff) + ldsw + _i * 8192), 16, 0, 0); } while (0)
; #define PG8_LDA(dst, b, h) do { _Pragma("unroll") for (int m = 0; m < 4; ++m) _Pragma("unroll") for (int k = 0; k < 2; ++k) dst[m][k] = *(const LAS bf16x8*)(lds + PG8_SA(b, h) + aoff + m * 2048 + k * 1024); } while (0)
; #define PG8_LDB(dst, b, h) do { _Pragma("unroll") for (int n = 0; n < 2; ++n) _Pragma("unroll") for (int k = 0; k < 2; ++k) dst[n][k] = *(const LAS bf16x8*)(lds + PG8_SB(b, h) + boff + n * 2048 + k * 1024); } while (0)
; #define PG8_MMA(ai, bj, At, Bt) do { __builtin_amdgcn_s_setprio(1); _Pragma("unroll") for (int m = 0; m < 4; ++m) _Pragma("unroll") for (int n = 0; n < 2; ++n) _Pragma("unroll") for (int k = 0; k < 2; ++k) \
;         acc[ai][bj][m][n] = __builtin_amdgcn_mfma_f32_16x16x32_bf16(Bt[n][k], At[m][k], acc[ai][bj][m][n], 0, 0, 0); __builtin_amdgcn_s_setprio(0); } while (0)
; #define PG8_WAIT_V(n) asm volatile("s_waitcnt vmcnt(" #n ")" ::: "memory")
; #define PG8_WAIT_L(n) asm volatile("s_waitcnt lgkmcnt(" #n ")" ::: "memory")
; #define PG8_BAR __builtin_amdgcn_s_barrier()
; #define PG8_SCHED __builtin_amdgcn_sched_barrier(0)
; template <class Epi, class Sched, bool ALIGN_EPI, bool LAST_FUSED = false, bool PERM = false, bool CARRY = false>
; __device__ __forceinline__ void gemm_phase(LAS unsigned char* lds, const int tid, const int K, const int lda, const int ldb, const Sched& S, const Epi& E) {
;     ...
;             PG8_WAIT_V(8); PG8_WAIT_L(0); PG8_BAR; PG8_MMA(1, 0, At, B0); PG8_MMA(1, 1, At, B1); PG8_BAR; PG8_SCHED;
;             PG8_LDB(B0, 1, 0); PG8_LDB(B1, 1, 1); PG8_SCHED; PG8_LDA(At, 1, 0); PG8_STAGE(PG8_SA(0, 1), a2 + hstepA, voffA);
;             PG8_WAIT_V(8); PG8_WAIT_L(0); PG8_BAR; PG8_MMA(0, 0, At, B0); PG8_MMA(0, 1, At, B1); PG8_BAR; PG8_SCHED;
	v_mfma_f32_16x16x32_bf16 v[62:65], v[148:151], v[180:183], v[62:65]
	s_setprio 1
	v_mfma_f32_16x16x32_bf16 v[58:61], v[156:159], v[180:183], v[58:61]
	v_mfma_f32_16x16x32_bf16 v[46:49], v[148:151], v[188:191], v[46:49]
	v_mfma_f32_16x16x32_bf16 v[42:45], v[156:159], v[188:191], v[42:45]
	v_mfma_f32_16x16x32_bf16 v[30:33], v[148:151], v[196:199], v[30:33]
	v_mfma_f32_16x16x32_bf16 v[26:29], v[156:159], v[196:199], v[26:29]
	v_mfma_f32_16x16x32_bf16 v[14:17], v[148:151], v[204:207], v[14:17]
	v_mfma_f32_16x16x32_bf16 v[10:13], v[156:159], v[204:207], v[10:13]
	v_mfma_f32_16x16x32_bf16 v[62:65], v[152:155], v[184:187], v[62:65]
	v_mfma_f32_16x16x32_bf16 v[58:61], v[160:163], v[184:187], v[58:61]
	v_mfma_f32_16x16x32_bf16 v[46:49], v[152:155], v[192:195], v[46:49]
	v_mfma_f32_16x16x32_bf16 v[42:45], v[160:163], v[192:195], v[42:45]
	v_mfma_f32_16x16x32_bf16 v[30:33], v[152:155], v[200:203], v[30:33]
	v_mfma_f32_16x16x32_bf16 v[26:29], v[160:163], v[200:203], v[26:29]
	v_mfma_f32_16x16x32_bf16 v[14:17], v[152:155], v[208:211], v[14:17]
	v_mfma_f32_16x16x32_bf16 v[10:13], v[160:163], v[208:211], v[10:13]
	s_setprio 0
	s_setprio 1
	v_mfma_f32_16x16x32_bf16 v[54:57], v[164:167], v[180:183], v[54:57]
	v_mfma_f32_16x16x32_bf16 v[50:53], v[172:175], v[180:183], v[50:53]
	v_mfma_f32_16x16x32_bf16 v[38:41], v[164:167], v[188:191], v[38:41]
	v_mfma_f32_16x16x32_bf16 v[34:37], v[172:175], v[188:191], v[34:37]
	v_mfma_f32_16x16x32_bf16 v[22:25], v[164:167], v[196:199], v[22:25]
	v_mfma_f32_16x16x32_bf16 v[18:21], v[172:175], v[196:199], v[18:21]
	v_mfma_f32_16x16x32_bf16 v[6:9], v[164:167], v[204:207], v[6:9]
	v_mfma_f32_16x16x32_bf16 v[2:5], v[172:175], v[204:207], v[2:5]
	v_mfma_f32_16x16x32_bf16 v[54:57], v[168:171], v[184:187], v[54:57]
	v_mfma_f32_16x16x32_bf16 v[50:53], v[176:179], v[184:187], v[50:53]
	v_mfma_f32_16x16x32_bf16 v[38:41], v[168:171], v[192:195], v[38:41]
	v_mfma_f32_16x16x32_bf16 v[34:37], v[176:179], v[192:195], v[34:37]
	v_mfma_f32_16x16x32_bf16 v[22:25], v[168:171], v[200:203], v[22:25]
	v_mfma_f32_16x16x32_bf16 v[18:21], v[176:179], v[200:203], v[18:21]
	v_mfma_f32_16x16x32_bf16 v[6:9], v[168:171], v[208:211], v[6:9]
	v_mfma_f32_16x16x32_bf16 v[2:5], v[176:179], v[208:211], v[2:5]
	s_barrier
	s_setprio 0
	s_add_i32 s16, 0, 0x18000
	s_add_i32 s17, 0, 0x1c000
	v_add_u32_e32 v160, s16, v146
	v_add_u32_e32 v176, s17, v146
	ds_read_b128 v[148:151], v160
	ds_read_b128 v[152:155], v160 offset:1024
	ds_read_b128 v[156:159], v160 offset:2048
	ds_read_b128 v[160:163], v160 offset:3072
	ds_read_b128 v[164:167], v176
	ds_read_b128 v[168:171], v176 offset:1024
	ds_read_b128 v[172:175], v176 offset:2048
	ds_read_b128 v[176:179], v176 offset:3072
	s_add_u32 s52, s52, 0x80000
	s_addc_u32 s53, s53, 0
	s_mov_b32 m0, s58
	v_lshl_add_u64 v[218:219], s[52:53], 0, v[134:135]
	ds_read_b128 v[180:183], v147 offset:32768
	ds_read_b128 v[184:187], v147 offset:33792
	ds_read_b128 v[188:191], v147 offset:34816
	ds_read_b128 v[192:195], v147 offset:35840
	ds_read_b128 v[196:199], v147 offset:36864
	ds_read_b128 v[200:203], v147 offset:37888
	ds_read_b128 v[204:207], v147 offset:38912
	ds_read_b128 v[208:211], v147 offset:39936
	global_load_lds_dwordx4 v[218:219], off
	v_lshl_add_u64 v[218:219], s[52:53], 0, v[132:133]
	s_mov_b32 m0, s59
	s_nop 0
	global_load_lds_dwordx4 v[218:219], off
	s_waitcnt vmcnt(8)
	s_waitcnt lgkmcnt(0)
	s_barrier
	v_mfma_f32_16x16x32_bf16 v[126:129], v[148:151], v[180:183], v[126:129]
	s_setprio 1
	v_mfma_f32_16x16x32_bf16 v[122:125], v[156:159], v[180:183], v[122:125]
	v_mfma_f32_16x16x32_bf16 v[110:113], v[148:151], v[188:191], v[110:113]
	v_mfma_f32_16x16x32_bf16 v[106:109], v[156:159], v[188:191], v[106:109]
	v_mfma_f32_16x16x32_bf16 v[94:97], v[148:151], v[196:199], v[94:97]
	v_mfma_f32_16x16x32_bf16 v[90:93], v[156:159], v[196:199], v[90:93]
	v_mfma_f32_16x16x32_bf16 v[78:81], v[148:151], v[204:207], v[78:81]
	v_mfma_f32_16x16x32_bf16 v[74:77], v[156:159], v[204:207], v[74:77]
	v_mfma_f32_16x16x32_bf16 v[126:129], v[152:155], v[184:187], v[126:129]
	v_mfma_f32_16x16x32_bf16 v[122:125], v[160:163], v[184:187], v[122:125]
	v_mfma_f32_16x16x32_bf16 v[110:113], v[152:155], v[192:195], v[110:113]
	v_mfma_f32_16x16x32_bf16 v[106:109], v[160:163], v[192:195], v[106:109]
	v_mfma_f32_16x16x32_bf16 v[94:97], v[152:155], v[200:203], v[94:97]
	v_mfma_f32_16x16x32_bf16 v[90:93], v[160:163], v[200:203], v[90:93]
	v_mfma_f32_16x16x32_bf16 v[78:81], v[152:155], v[208:211], v[78:81]
	v_mfma_f32_16x16x32_bf16 v[74:77], v[160:163], v[208:211], v[74:77]
	s_setprio 0
	s_setprio 1
	v_mfma_f32_16x16x32_bf16 v[118:121], v[164:167], v[180:183], v[118:121]
	v_mfma_f32_16x16x32_bf16 v[114:117], v[172:175], v[180:183], v[114:117]
	v_mfma_f32_16x16x32_bf16 v[102:105], v[164:167], v[188:191], v[102:105]
	v_mfma_f32_16x16x32_bf16 v[98:101], v[172:175], v[188:191], v[98:101]
	v_mfma_f32_16x16x32_bf16 v[86:89], v[164:167], v[196:199], v[86:89]
	v_mfma_f32_16x16x32_bf16 v[82:85], v[172:175], v[196:199], v[82:85]
	v_mfma_f32_16x16x32_bf16 v[70:73], v[164:167], v[204:207], v[70:73]
	v_mfma_f32_16x16x32_bf16 v[66:69], v[172:175], v[204:207], v[66:69]
	v_mfma_f32_16x16x32_bf16 v[118:121], v[168:171], v[184:187], v[118:121]
	v_mfma_f32_16x16x32_bf16 v[114:117], v[176:179], v[184:187], v[114:117]
	v_mfma_f32_16x16x32_bf16 v[102:105], v[168:171], v[192:195], v[102:105]
	v_mfma_f32_16x16x32_bf16 v[98:101], v[176:179], v[192:195], v[98:101]
	v_mfma_f32_16x16x32_bf16 v[86:89], v[168:171], v[200:203], v[86:89]
	v_mfma_f32_16x16x32_bf16 v[82:85], v[176:179], v[200:203], v[82:85]
	v_mfma_f32_16x16x32_bf16 v[70:73], v[168:171], v[208:211], v[70:73]
	v_mfma_f32_16x16x32_bf16 v[66:69], v[176:179], v[208:211], v[66:69]
	s_barrier
; #define PG8_STAGE(bufoff, gbase, voff) do { _Pragma("unroll") for (int _i = 0; _i < 2; ++_i) \
;         __builtin_amdgcn_global_load_lds((const unsigned*)((const char*)(gbase) + (voff)[_i]), (LAS unsigned*)(lds + (bufoff) + ldsw + _i * 8192), 16, 0, 0); } while (0)
; #define PG8_LDA(dst, b, h) do { _Pragma("unroll") for (int m = 0; m < 4; ++m) _Pragma("unroll") for (int k = 0; k < 2; ++k) dst[m][k] = *(const LAS bf16x8*)(lds + PG8_SA(b, h) + aoff + m * 2048 + k * 1024); } while (0)
; #define PG8_MMA(ai, bj, At, Bt) do { __builtin_amdgcn_s_setprio(1); _Pragma("unroll") for (int m = 0; m < 4; ++m) _Pragma("unroll") for (int n = 0; n < 2; ++n) _Pragma("unroll") for (int k = 0; k < 2; ++k) \
;         acc[ai][bj][m][n] = __builtin_amdgcn_mfma_f32_16x16x32_bf16(Bt[n][k], At[m][k], acc[ai][bj][m][n], 0, 0, 0); __builtin_amdgcn_s_setprio(0); } while (0)
; #define PG8_WAIT_V(n) asm volatile("s_waitcnt vmcnt(" #n ")" ::: "memory")
; #define PG8_WAIT_L(n) asm volatile("s_waitcnt lgkmcnt(" #n ")" ::: "memory")
; #define PG8_BAR __builtin_amdgcn_s_barrier()
; #define PG8_SCHED __builtin_amdgcn_sched_barrier(0)
; template <class Epi, class Sched, bool ALIGN_EPI, bool LAST_FUSED = false, bool PERM = false, bool CARRY = false>
; __device__ __forceinline__ void gemm_phase(LAS unsigned char* lds, const int tid, const int K, const int lda, const int ldb, const Sched& S, const Epi& E) {
;     ...
;             PG8_LDA(At, 1, 1); PG8_STAGE(PG8_SB(1, 0), b3, voffB); PG8_STAGE(PG8_SB(1, 1), b3 + hstepB, voffB); PG8_STAGE(PG8_SA(1, 0), a3, voffA);
;             PG8_WAIT_V(8); PG8_WAIT_L(0); PG8_BAR; PG8_MMA(1, 0, At, B0); PG8_MMA(1, 1, At, B1); PG8_BAR; PG8_SCHED;
;         }
;         if constexpr (ALIGN_EPI) { if (wr == 0) PG8_BAR; }
	s_setprio 0
	s_add_i32 s16, s16, s45
	v_lshl_add_u64 v[140:141], v[140:141], 0, s[68:69]
	s_mov_b32 m0, s16
	ds_read_b128 v[180:183], v147 offset:49152
	ds_read_b128 v[184:187], v147 offset:50176
	ds_read_b128 v[188:191], v147 offset:51200
	ds_read_b128 v[192:195], v147 offset:52224
	ds_read_b128 v[196:199], v147 offset:53248
	ds_read_b128 v[200:203], v147 offset:54272
	ds_read_b128 v[204:207], v147 offset:55296
	ds_read_b128 v[208:211], v147 offset:56320
	global_load_lds_dwordx4 v[140:141], off
	s_add_i32 m0, s16, 0x2000
	s_add_u32 s52, s54, 0x80080
	v_lshl_add_u64 v[140:141], v[212:213], 0, s[68:69]
	s_addc_u32 s53, s55, 0
	s_add_i32 s16, s17, s45
	global_load_lds_dwordx4 v[140:141], off
	v_lshl_add_u64 v[140:141], s[52:53], 0, v[0:1]
	s_mov_b32 m0, s16
	s_nop 0
	global_load_lds_dwordx4 v[140:141], off
	v_lshl_add_u64 v[140:141], s[52:53], 0, v[130:131]
	s_add_i32 m0, s16, 0x2000
	s_nop 0
	global_load_lds_dwordx4 v[140:141], off
	v_lshl_add_u64 v[140:141], v[214:215], 0, s[68:69]
	s_mov_b32 m0, s61
	s_nop 0
	global_load_lds_dwordx4 v[140:141], off
	v_lshl_add_u64 v[140:141], v[216:217], 0, s[68:69]
	s_mov_b32 m0, s62
	s_nop 0
	global_load_lds_dwordx4 v[140:141], off
	s_waitcnt vmcnt(8)
	s_waitcnt lgkmcnt(0)
	s_barrier
	v_mfma_f32_16x16x32_bf16 v[62:65], v[148:151], v[180:183], v[62:65]
	s_setprio 1
	v_mfma_f32_16x16x32_bf16 v[58:61], v[156:159], v[180:183], v[58:61]
	v_mfma_f32_16x16x32_bf16 v[46:49], v[148:151], v[188:191], v[46:49]
	v_mfma_f32_16x16x32_bf16 v[42:45], v[156:159], v[188:191], v[42:45]
	v_mfma_f32_16x16x32_bf16 v[30:33], v[148:151], v[196:199], v[30:33]
	v_mfma_f32_16x16x32_bf16 v[26:29], v[156:159], v[196:199], v[26:29]
	v_mfma_f32_16x16x32_bf16 v[14:17], v[148:151], v[204:207], v[14:17]
	v_mfma_f32_16x16x32_bf16 v[10:13], v[156:159], v[204:207], v[10:13]
	v_mfma_f32_16x16x32_bf16 v[62:65], v[152:155], v[184:187], v[62:65]
	v_mfma_f32_16x16x32_bf16 v[58:61], v[160:163], v[184:187], v[58:61]
	v_mfma_f32_16x16x32_bf16 v[46:49], v[152:155], v[192:195], v[46:49]
	v_mfma_f32_16x16x32_bf16 v[42:45], v[160:163], v[192:195], v[42:45]
	v_mfma_f32_16x16x32_bf16 v[30:33], v[152:155], v[200:203], v[30:33]
	v_mfma_f32_16x16x32_bf16 v[26:29], v[160:163], v[200:203], v[26:29]
	v_mfma_f32_16x16x32_bf16 v[14:17], v[152:155], v[208:211], v[14:17]
	v_mfma_f32_16x16x32_bf16 v[10:13], v[160:163], v[208:211], v[10:13]
	s_setprio 0
	s_setprio 1
	v_mfma_f32_16x16x32_bf16 v[54:57], v[164:167], v[180:183], v[54:57]
	v_mfma_f32_16x16x32_bf16 v[50:53], v[172:175], v[180:183], v[50:53]
	v_mfma_f32_16x16x32_bf16 v[38:41], v[164:167], v[188:191], v[38:41]
	v_mfma_f32_16x16x32_bf16 v[34:37], v[172:175], v[188:191], v[34:37]
	v_mfma_f32_16x16x32_bf16 v[22:25], v[164:167], v[196:199], v[22:25]
	v_mfma_f32_16x16x32_bf16 v[18:21], v[172:175], v[196:199], v[18:21]
	v_mfma_f32_16x16x32_bf16 v[6:9], v[164:167], v[204:207], v[6:9]
	v_mfma_f32_16x16x32_bf16 v[2:5], v[172:175], v[204:207], v[2:5]
	v_mfma_f32_16x16x32_bf16 v[54:57], v[168:171], v[184:187], v[54:57]
	v_mfma_f32_16x16x32_bf16 v[50:53], v[176:179], v[184:187], v[50:53]
	v_mfma_f32_16x16x32_bf16 v[38:41], v[168:171], v[192:195], v[38:41]
	v_mfma_f32_16x16x32_bf16 v[34:37], v[176:179], v[192:195], v[34:37]
	v_mfma_f32_16x16x32_bf16 v[22:25], v[168:171], v[200:203], v[22:25]
	v_mfma_f32_16x16x32_bf16 v[18:21], v[176:179], v[200:203], v[18:21]
	v_mfma_f32_16x16x32_bf16 v[6:9], v[168:171], v[208:211], v[6:9]
	v_mfma_f32_16x16x32_bf16 v[2:5], v[176:179], v[208:211], v[2:5]
	s_barrier
	s_setprio 0
	s_add_i32 s41, s41, 2
	s_add_u32 s48, s48, 0x100
	s_addc_u32 s49, s49, 0
	s_add_u32 s27, s27, 0x100
	s_addc_u32 s39, s39, 0
	s_cmp_gt_u32 s41, 29
	s_cbranch_scc0 .LBB0_1763
	s_and_b64 vcc, exec, s[36:37]
	s_cbranch_vccz .LBB0_1766
	s_barrier

; #define PG8_STAGE(bufoff, gbase, voff) do { _Pragma("unroll") for (int _i = 0; _i < 2; ++_i) \
;         __builtin_amdgcn_global_load_lds((const unsigned*)((const char*)(gbase) + (voff)[_i]), (LAS unsigned*)(lds + (bufoff) + ldsw + _i * 8192), 16, 0, 0); } while (0)
; #define PG8_LDA(dst, b, h) do { _Pragma("unroll") for (int m = 0; m < 4; ++m) _Pragma("unroll") for (int k = 0; k < 2; ++k) dst[m][k] = *(const LAS bf16x8*)(lds + PG8_SA(b, h) + aoff + m * 2048 + k * 1024); } while (0)
; #define PG8_LDB(dst, b, h) do { _Pragma("unroll") for (int n = 0; n < 2; ++n) _Pragma("unroll") for (int k = 0; k < 2; ++k) dst[n][k] = *(const LAS bf16x8*)(lds + PG8_SB(b, h) + boff + n * 2048 + k * 1024); } while (0)
; #define PG8_WAIT_V(n) asm volatile("s_waitcnt vmcnt(" #n ")" ::: "memory")
; #define PG8_WAIT_L(n) asm volatile("s_waitcnt lgkmcnt(" #n ")" ::: "memory")
; #define PG8_BAR __builtin_amdgcn_s_barrier()
; #define PG8_SCHED __builtin_amdgcn_sched_barrier(0)
; template <class Epi, class Sched, bool ALIGN_EPI, bool LAST_FUSED = false, bool PERM = false, bool CARRY = false>
; __device__ __forceinline__ void gemm_phase(LAS unsigned char* lds, const int tid, const int K, const int lda, const int ldb, const Sched& S, const Epi& E) {
;     ...
;         const bool has_next = S.next(KD_IDX(ui + 1), nxt);
;         const char* nA = has_next ? nxt.a : cA; const char* nB = has_next ? nxt.b : cB; const int nt = cur.nt;
; #pragma unroll 1
;         for (int t = 0; t < nt; t += 2) {
;             const bool last = (t == nt - 2);
;             const char* a1 = cA + (size_t)(t + 1) * kstep;
;             const char* a2 = last ? nA : cA + (size_t)(t + 2) * kstep; const char* b2 = last ? nB : cB + (size_t)(t + 2) * kstep;
;             const char* a3 = a2 + kstep; const char* b3 = b2 + kstep;
;             PG8_LDB(B0, 0, 0); PG8_LDB(B1, 0, 1); PG8_SCHED; PG8_LDA(At, 0, 0); PG8_STAGE(PG8_SA(1, 1), a1 + hstepA, voffA);
;             PG8_WAIT_V(8); PG8_WAIT_L(0); PG8_BAR; PG8_MMA(0, 0, At, B0); PG8_MMA(0, 1, At, B1); PG8_BAR; PG8_SCHED;
;             PG8_LDA(At, 0, 1); PG8_STAGE(PG8_SB(0, 0), b2, voffB); PG8_STAGE(PG8_SB(0, 1), b2 + hstepB, voffB); PG8_STAGE(PG8_SA(0, 0), a2, voffA);
;             PG8_WAIT_V(8); PG8_WAIT_L(0); PG8_BAR; PG8_MMA(1, 0, At, B0); PG8_MMA(1, 1, At, B1); PG8_BAR; PG8_SCHED;
.LBB0_1854:
	s_add_u32 s16, s66, vcc_lo
	s_addc_u32 s17, s67, vcc_hi
	s_add_u32 s52, s50, vcc_lo
	s_addc_u32 s53, s51, vcc_hi
	s_add_i32 s92, 0, 0x10000
	s_cmp_eq_u32 s87, s60
	s_cselect_b32 s57, s24, s17
	s_cselect_b32 s56, s91, s16
	v_add_u32_e32 v154, s92, v140
	s_cselect_b32 s53, s70, s53
	s_cselect_b32 s52, s71, s52
	s_add_i32 s93, 0, 0x14000
	ds_read_b128 v[142:145], v154
	ds_read_b128 v[146:149], v154 offset:1024
	ds_read_b128 v[150:153], v154 offset:2048
	ds_read_b128 v[158:161], v154 offset:3072
	v_add_u32_e32 v154, s93, v140
	ds_read_b128 v[162:165], v154
	ds_read_b128 v[166:169], v154 offset:1024
	ds_read_b128 v[170:173], v154 offset:2048
	ds_read_b128 v[174:177], v154 offset:3072
	v_lshl_add_u64 v[154:155], s[66:67], 0, v[138:139]
	s_add_i32 m0, s28, 0xc000
	ds_read_b128 v[178:181], v141
	ds_read_b128 v[182:185], v141 offset:1024
	ds_read_b128 v[186:189], v141 offset:2048
	ds_read_b128 v[190:193], v141 offset:3072
	ds_read_b128 v[194:197], v141 offset:4096
	ds_read_b128 v[198:201], v141 offset:5120
	ds_read_b128 v[202:205], v141 offset:6144
	ds_read_b128 v[206:209], v141 offset:7168
	global_load_lds_dwordx4 v[154:155], off
	v_lshl_add_u64 v[154:155], s[66:67], 0, v[128:129]
	s_add_i32 m0, s28, 0xe000
	s_nop 0
	global_load_lds_dwordx4 v[154:155], off
	s_waitcnt vmcnt(8)
	s_waitcnt lgkmcnt(0)
	s_barrier
	v_mfma_f32_16x16x32_bf16 v[118:121], v[142:145], v[178:181], v[118:121]
	s_setprio 1
	v_mfma_f32_16x16x32_bf16 v[114:117], v[150:153], v[178:181], v[114:117]
	v_mfma_f32_16x16x32_bf16 v[110:113], v[142:145], v[186:189], v[110:113]
	v_mfma_f32_16x16x32_bf16 v[106:109], v[150:153], v[186:189], v[106:109]
	v_mfma_f32_16x16x32_bf16 v[86:89], v[142:145], v[194:197], v[86:89]
	v_mfma_f32_16x16x32_bf16 v[82:85], v[150:153], v[194:197], v[82:85]
	v_mfma_f32_16x16x32_bf16 v[78:81], v[142:145], v[202:205], v[78:81]
	v_mfma_f32_16x16x32_bf16 v[74:77], v[150:153], v[202:205], v[74:77]
	v_mfma_f32_16x16x32_bf16 v[118:121], v[146:149], v[182:185], v[118:121]
	v_mfma_f32_16x16x32_bf16 v[114:117], v[158:161], v[182:185], v[114:117]
	v_mfma_f32_16x16x32_bf16 v[110:113], v[146:149], v[190:193], v[110:113]
	v_mfma_f32_16x16x32_bf16 v[106:109], v[158:161], v[190:193], v[106:109]
	v_mfma_f32_16x16x32_bf16 v[86:89], v[146:149], v[198:201], v[86:89]
	v_mfma_f32_16x16x32_bf16 v[82:85], v[158:161], v[198:201], v[82:85]
	v_mfma_f32_16x16x32_bf16 v[78:81], v[146:149], v[206:209], v[78:81]
	v_mfma_f32_16x16x32_bf16 v[74:77], v[158:161], v[206:209], v[74:77]
	s_setprio 0
	s_setprio 1
	v_mfma_f32_16x16x32_bf16 v[98:101], v[162:165], v[178:181], v[98:101]
	v_mfma_f32_16x16x32_bf16 v[102:105], v[170:173], v[178:181], v[102:105]
	v_mfma_f32_16x16x32_bf16 v[90:93], v[162:165], v[186:189], v[90:93]
	v_mfma_f32_16x16x32_bf16 v[94:97], v[170:173], v[186:189], v[94:97]
	v_mfma_f32_16x16x32_bf16 v[66:69], v[162:165], v[194:197], v[66:69]
	v_mfma_f32_16x16x32_bf16 v[70:73], v[170:173], v[194:197], v[70:73]
	v_mfma_f32_16x16x32_bf16 v[50:53], v[162:165], v[202:205], v[50:53]
	v_mfma_f32_16x16x32_bf16 v[54:57], v[170:173], v[202:205], v[54:57]
	v_mfma_f32_16x16x32_bf16 v[98:101], v[166:169], v[182:185], v[98:101]
	v_mfma_f32_16x16x32_bf16 v[102:105], v[174:177], v[182:185], v[102:105]
	v_mfma_f32_16x16x32_bf16 v[90:93], v[166:169], v[190:193], v[90:93]
	v_mfma_f32_16x16x32_bf16 v[94:97], v[174:177], v[190:193], v[94:97]
	v_mfma_f32_16x16x32_bf16 v[66:69], v[166:169], v[198:201], v[66:69]
	v_mfma_f32_16x16x32_bf16 v[70:73], v[174:177], v[198:201], v[70:73]
	v_mfma_f32_16x16x32_bf16 v[50:53], v[166:169], v[206:209], v[50:53]
	v_mfma_f32_16x16x32_bf16 v[54:57], v[174:177], v[206:209], v[54:57]
	s_barrier
	s_setprio 0
	s_add_i32 s16, s92, s95
	v_lshl_add_u64 v[154:155], s[52:53], 0, v[0:1]
	s_mov_b32 m0, s16
	ds_read_b128 v[178:181], v141 offset:16384
	ds_read_b128 v[182:185], v141 offset:17408
	ds_read_b128 v[186:189], v141 offset:18432
	ds_read_b128 v[190:193], v141 offset:19456
	ds_read_b128 v[194:197], v141 offset:20480
	ds_read_b128 v[198:201], v141 offset:21504
	ds_read_b128 v[202:205], v141 offset:22528
	ds_read_b128 v[206:209], v141 offset:23552
	global_load_lds_dwordx4 v[154:155], off
	s_add_i32 m0, s16, 0x2000
	s_add_u32 s16, s52, 0x200000
	v_lshl_add_u64 v[210:211], s[52:53], 0, v[122:123]
	s_addc_u32 s17, s53, 0
	s_add_i32 s92, s93, s95
	global_load_lds_dwordx4 v[210:211], off
	v_lshl_add_u64 v[212:213], s[16:17], 0, v[0:1]
	s_mov_b32 m0, s92
	v_lshl_add_u64 v[214:215], s[56:57], 0, v[122:123]
	global_load_lds_dwordx4 v[212:213], off
	v_lshl_add_u64 v[212:213], s[16:17], 0, v[122:123]
	s_add_i32 m0, s92, 0x2000
	s_nop 0
	global_load_lds_dwordx4 v[212:213], off
	v_lshl_add_u64 v[212:213], s[56:57], 0, v[0:1]
	s_mov_b32 m0, s28
	s_nop 0
	global_load_lds_dwordx4 v[212:213], off
	s_mov_b32 m0, s29
	s_nop 0
	global_load_lds_dwordx4 v[214:215], off
	s_waitcnt vmcnt(8)
	s_waitcnt lgkmcnt(0)
	s_barrier
; #define PG8_STAGE(bufoff, gbase, voff) do { _Pragma("unroll") for (int _i = 0; _i < 2; ++_i) \
;         __builtin_amdgcn_global_load_lds((const unsigned*)((const char*)(gbase) + (voff)[_i]), (LAS unsigned*)(lds + (bufoff) + ldsw + _i * 8192), 16, 0, 0); } while (0)
; #define PG8_LDA(dst, b, h) do { _Pragma("unroll") for (int m = 0; m < 4; ++m) _Pragma("unroll") for (int k = 0; k < 2; ++k) dst[m][k] = *(const LAS bf16x8*)(lds + PG8_SA(b, h) + aoff + m * 2048 + k * 1024); } while (0)
; #define PG8_LDB(dst, b, h) do { _Pragma("unroll") for (int n = 0; n < 2; ++n) _Pragma("unroll") for (int k = 0; k < 2; ++k) dst[n][k] = *(const LAS bf16x8*)(lds + PG8_SB(b, h) + boff + n * 2048 + k * 1024); } while (0)
; #define PG8_MMA(ai, bj, At, Bt) do { __builtin_amdgcn_s_setprio(1); _Pragma("unroll") for (int m = 0; m < 4; ++m) _Pragma("unroll") for (int n = 0; n < 2; ++n) _Pragma("unroll") for (int k = 0; k < 2; ++k) \
;         acc[ai][bj][m][n] = __builtin_amdgcn_mfma_f32_16x16x32_bf16(Bt[n][k], At[m][k], acc[ai][bj][m][n], 0, 0, 0); __builtin_amdgcn_s_setprio(0); } while (0)
; #define PG8_WAIT_V(n) asm volatile("s_waitcnt vmcnt(" #n ")" ::: "memory")
; #define PG8_WAIT_L(n) asm volatile("s_waitcnt lgkmcnt(" #n ")" ::: "memory")
; #define PG8_BAR __builtin_amdgcn_s_barrier()
; #define PG8_SCHED __builtin_amdgcn_sched_barrier(0)
; template <class Epi, class Sched, bool ALIGN_EPI, bool LAST_FUSED = false, bool PERM = false, bool CARRY = false>
; __device__ __forceinline__ void gemm_phase(LAS unsigned char* lds, const int tid, const int K, const int lda, const int ldb, const Sched& S, const Epi& E) {
;     ...
;             PG8_WAIT_V(8); PG8_WAIT_L(0); PG8_BAR; PG8_MMA(1, 0, At, B0); PG8_MMA(1, 1, At, B1); PG8_BAR; PG8_SCHED;
;             PG8_LDB(B0, 1, 0); PG8_LDB(B1, 1, 1); PG8_SCHED; PG8_LDA(At, 1, 0); PG8_STAGE(PG8_SA(0, 1), a2 + hstepA, voffA);
;             PG8_WAIT_V(8); PG8_WAIT_L(0); PG8_BAR; PG8_MMA(0, 0, At, B0); PG8_MMA(0, 1, At, B1); PG8_BAR; PG8_SCHED;
	v_mfma_f32_16x16x32_bf16 v[62:65], v[142:145], v[178:181], v[62:65]
	s_setprio 1
	v_mfma_f32_16x16x32_bf16 v[58:61], v[150:153], v[178:181], v[58:61]
	v_mfma_f32_16x16x32_bf16 v[38:41], v[142:145], v[186:189], v[38:41]
	v_mfma_f32_16x16x32_bf16 v[34:37], v[150:153], v[186:189], v[34:37]
	v_mfma_f32_16x16x32_bf16 v[22:25], v[142:145], v[194:197], v[22:25]
	v_mfma_f32_16x16x32_bf16 v[18:21], v[150:153], v[194:197], v[18:21]
	v_mfma_f32_16x16x32_bf16 v[134:137], v[142:145], v[202:205], v[134:137]
	v_mfma_f32_16x16x32_bf16 v[130:133], v[150:153], v[202:205], v[130:133]
	v_mfma_f32_16x16x32_bf16 v[62:65], v[146:149], v[182:185], v[62:65]
	v_mfma_f32_16x16x32_bf16 v[58:61], v[158:161], v[182:185], v[58:61]
	v_mfma_f32_16x16x32_bf16 v[38:41], v[146:149], v[190:193], v[38:41]
	v_mfma_f32_16x16x32_bf16 v[34:37], v[158:161], v[190:193], v[34:37]
	v_mfma_f32_16x16x32_bf16 v[22:25], v[146:149], v[198:201], v[22:25]
	v_mfma_f32_16x16x32_bf16 v[18:21], v[158:161], v[198:201], v[18:21]
	v_mfma_f32_16x16x32_bf16 v[134:137], v[146:149], v[206:209], v[134:137]
	v_mfma_f32_16x16x32_bf16 v[130:133], v[158:161], v[206:209], v[130:133]
	s_setprio 0
	s_setprio 1
	v_mfma_f32_16x16x32_bf16 v[42:45], v[162:165], v[178:181], v[42:45]
	v_mfma_f32_16x16x32_bf16 v[46:49], v[170:173], v[178:181], v[46:49]
	v_mfma_f32_16x16x32_bf16 v[26:29], v[162:165], v[186:189], v[26:29]
	v_mfma_f32_16x16x32_bf16 v[30:33], v[170:173], v[186:189], v[30:33]
	v_mfma_f32_16x16x32_bf16 v[14:17], v[162:165], v[194:197], v[14:17]
	v_mfma_f32_16x16x32_bf16 v[10:13], v[170:173], v[194:197], v[10:13]
	v_mfma_f32_16x16x32_bf16 v[6:9], v[162:165], v[202:205], v[6:9]
	v_mfma_f32_16x16x32_bf16 v[2:5], v[170:173], v[202:205], v[2:5]
	v_mfma_f32_16x16x32_bf16 v[42:45], v[166:169], v[182:185], v[42:45]
	v_mfma_f32_16x16x32_bf16 v[46:49], v[174:177], v[182:185], v[46:49]
	v_mfma_f32_16x16x32_bf16 v[26:29], v[166:169], v[190:193], v[26:29]
	v_mfma_f32_16x16x32_bf16 v[30:33], v[174:177], v[190:193], v[30:33]
	v_mfma_f32_16x16x32_bf16 v[14:17], v[166:169], v[198:201], v[14:17]
	v_mfma_f32_16x16x32_bf16 v[10:13], v[174:177], v[198:201], v[10:13]
	v_mfma_f32_16x16x32_bf16 v[6:9], v[166:169], v[206:209], v[6:9]
	v_mfma_f32_16x16x32_bf16 v[2:5], v[174:177], v[206:209], v[2:5]
	s_barrier
	s_setprio 0
	s_add_i32 s92, 0, 0x18000
	s_add_i32 s93, 0, 0x1c000
	v_add_u32_e32 v158, s92, v140
	v_add_u32_e32 v174, s93, v140
	ds_read_b128 v[142:145], v158
	ds_read_b128 v[146:149], v158 offset:1024
	ds_read_b128 v[150:153], v158 offset:2048
	ds_read_b128 v[158:161], v158 offset:3072
	ds_read_b128 v[162:165], v174
	ds_read_b128 v[166:169], v174 offset:1024
	ds_read_b128 v[170:173], v174 offset:2048
	ds_read_b128 v[174:177], v174 offset:3072
	s_add_u32 s16, s56, 0x200000
	s_addc_u32 s17, s57, 0
	s_mov_b32 m0, s14
	v_lshl_add_u64 v[216:217], s[16:17], 0, v[0:1]
	ds_read_b128 v[178:181], v141 offset:32768
	ds_read_b128 v[182:185], v141 offset:33792
	ds_read_b128 v[186:189], v141 offset:34816
	ds_read_b128 v[190:193], v141 offset:35840
	ds_read_b128 v[194:197], v141 offset:36864
	ds_read_b128 v[198:201], v141 offset:37888
	ds_read_b128 v[202:205], v141 offset:38912
	ds_read_b128 v[206:209], v141 offset:39936
	global_load_lds_dwordx4 v[216:217], off
	v_lshl_add_u64 v[216:217], s[16:17], 0, v[122:123]
	s_mov_b32 m0, s22
	s_nop 0
	global_load_lds_dwordx4 v[216:217], off
	s_waitcnt vmcnt(8)
	s_waitcnt lgkmcnt(0)
	s_barrier
	v_mfma_f32_16x16x32_bf16 v[118:121], v[142:145], v[178:181], v[118:121]
	s_setprio 1
	v_mfma_f32_16x16x32_bf16 v[114:117], v[150:153], v[178:181], v[114:117]
	v_mfma_f32_16x16x32_bf16 v[110:113], v[142:145], v[186:189], v[110:113]
	v_mfma_f32_16x16x32_bf16 v[106:109], v[150:153], v[186:189], v[106:109]
	v_mfma_f32_16x16x32_bf16 v[86:89], v[142:145], v[194:197], v[86:89]
	v_mfma_f32_16x16x32_bf16 v[82:85], v[150:153], v[194:197], v[82:85]
	v_mfma_f32_16x16x32_bf16 v[78:81], v[142:145], v[202:205], v[78:81]
	v_mfma_f32_16x16x32_bf16 v[74:77], v[150:153], v[202:205], v[74:77]
	v_mfma_f32_16x16x32_bf16 v[118:121], v[146:149], v[182:185], v[118:121]
	v_mfma_f32_16x16x32_bf16 v[114:117], v[158:161], v[182:185], v[114:117]
	v_mfma_f32_16x16x32_bf16 v[110:113], v[146:149], v[190:193], v[110:113]
	v_mfma_f32_16x16x32_bf16 v[106:109], v[158:161], v[190:193], v[106:109]
	v_mfma_f32_16x16x32_bf16 v[86:89], v[146:149], v[198:201], v[86:89]
	v_mfma_f32_16x16x32_bf16 v[82:85], v[158:161], v[198:201], v[82:85]
	v_mfma_f32_16x16x32_bf16 v[78:81], v[146:149], v[206:209], v[78:81]
	v_mfma_f32_16x16x32_bf16 v[74:77], v[158:161], v[206:209], v[74:77]
	s_setprio 0
	s_setprio 1
	v_mfma_f32_16x16x32_bf16 v[98:101], v[162:165], v[178:181], v[98:101]
	v_mfma_f32_16x16x32_bf16 v[102:105], v[170:173], v[178:181], v[102:105]
	v_mfma_f32_16x16x32_bf16 v[90:93], v[162:165], v[186:189], v[90:93]
	v_mfma_f32_16x16x32_bf16 v[94:97], v[170:173], v[186:189], v[94:97]
	v_mfma_f32_16x16x32_bf16 v[66:69], v[162:165], v[194:197], v[66:69]
	v_mfma_f32_16x16x32_bf16 v[70:73], v[170:173], v[194:197], v[70:73]
	v_mfma_f32_16x16x32_bf16 v[50:53], v[162:165], v[202:205], v[50:53]
	v_mfma_f32_16x16x32_bf16 v[54:57], v[170:173], v[202:205], v[54:57]
	v_mfma_f32_16x16x32_bf16 v[98:101], v[166:169], v[182:185], v[98:101]
	v_mfma_f32_16x16x32_bf16 v[102:105], v[174:177], v[182:185], v[102:105]
	v_mfma_f32_16x16x32_bf16 v[90:93], v[166:169], v[190:193], v[90:93]
	v_mfma_f32_16x16x32_bf16 v[94:97], v[174:177], v[190:193], v[94:97]
	v_mfma_f32_16x16x32_bf16 v[66:69], v[166:169], v[198:201], v[66:69]
	v_mfma_f32_16x16x32_bf16 v[70:73], v[174:177], v[198:201], v[70:73]
	v_mfma_f32_16x16x32_bf16 v[50:53], v[166:169], v[206:209], v[50:53]
	v_mfma_f32_16x16x32_bf16 v[54:57], v[174:177], v[206:209], v[54:57]
	s_barrier
; #define PG8_STAGE(bufoff, gbase, voff) do { _Pragma("unroll") for (int _i = 0; _i < 2; ++_i) \
;         __builtin_amdgcn_global_load_lds((const unsigned*)((const char*)(gbase) + (voff)[_i]), (LAS unsigned*)(lds + (bufoff) + ldsw + _i * 8192), 16, 0, 0); } while (0)
; #define PG8_LDA(dst, b, h) do { _Pragma("unroll") for (int m = 0; m < 4; ++m) _Pragma("unroll") for (int k = 0; k < 2; ++k) dst[m][k] = *(const LAS bf16x8*)(lds + PG8_SA(b, h) + aoff + m * 2048 + k * 1024); } while (0)
; #define PG8_MMA(ai, bj, At, Bt) do { __builtin_amdgcn_s_setprio(1); _Pragma("unroll") for (int m = 0; m < 4; ++m) _Pragma("unroll") for (int n = 0; n < 2; ++n) _Pragma("unroll") for (int k = 0; k < 2; ++k) \
;         acc[ai][bj][m][n] = __builtin_amdgcn_mfma_f32_16x16x32_bf16(Bt[n][k], At[m][k], acc[ai][bj][m][n], 0, 0, 0); __builtin_amdgcn_s_setprio(0); } while (0)
; #define PG8_WAIT_V(n) asm volatile("s_waitcnt vmcnt(" #n ")" ::: "memory")
; #define PG8_WAIT_L(n) asm volatile("s_waitcnt lgkmcnt(" #n ")" ::: "memory")
; #define PG8_BAR __builtin_amdgcn_s_barrier()
; #define PG8_SCHED __builtin_amdgcn_sched_barrier(0)
; template <class Epi, class Sched, bool ALIGN_EPI, bool LAST_FUSED = false, bool PERM = false, bool CARRY = false>
; __device__ __forceinline__ void gemm_phase(LAS unsigned char* lds, const int tid, const int K, const int lda, const int ldb, const Sched& S, const Epi& E) {
;     ...
;             PG8_LDA(At, 1, 1); PG8_STAGE(PG8_SB(1, 0), b3, voffB); PG8_STAGE(PG8_SB(1, 1), b3 + hstepB, voffB); PG8_STAGE(PG8_SA(1, 0), a3, voffA);
;             PG8_WAIT_V(8); PG8_WAIT_L(0); PG8_BAR; PG8_MMA(1, 0, At, B0); PG8_MMA(1, 1, At, B1); PG8_BAR; PG8_SCHED;
;         }
;         if constexpr (ALIGN_EPI) { if (wr == 0) PG8_BAR; }
	s_setprio 0
	s_add_i32 s16, s92, s95
	v_lshl_add_u64 v[154:155], v[154:155], 0, s[68:69]
	s_mov_b32 m0, s16
	ds_read_b128 v[178:181], v141 offset:49152
	ds_read_b128 v[182:185], v141 offset:50176
	ds_read_b128 v[186:189], v141 offset:51200
	ds_read_b128 v[190:193], v141 offset:52224
	ds_read_b128 v[194:197], v141 offset:53248
	ds_read_b128 v[198:201], v141 offset:54272
	ds_read_b128 v[202:205], v141 offset:55296
	ds_read_b128 v[206:209], v141 offset:56320
	global_load_lds_dwordx4 v[154:155], off
	s_add_i32 m0, s16, 0x2000
	s_add_u32 s16, s52, 0x200080
	v_lshl_add_u64 v[154:155], v[210:211], 0, s[68:69]
	s_addc_u32 s17, s53, 0
	s_add_i32 s52, s93, s95
	global_load_lds_dwordx4 v[154:155], off
	v_lshl_add_u64 v[154:155], s[16:17], 0, v[0:1]
	s_mov_b32 m0, s52
	s_nop 0
	global_load_lds_dwordx4 v[154:155], off
	v_lshl_add_u64 v[154:155], s[16:17], 0, v[122:123]
	s_add_i32 m0, s52, 0x2000
	s_nop 0
	global_load_lds_dwordx4 v[154:155], off
	v_lshl_add_u64 v[154:155], v[212:213], 0, s[68:69]
	s_mov_b32 m0, s96
	s_nop 0
	global_load_lds_dwordx4 v[154:155], off
	v_lshl_add_u64 v[154:155], v[214:215], 0, s[68:69]
	s_mov_b32 m0, s97
	s_nop 0
	global_load_lds_dwordx4 v[154:155], off
	s_waitcnt vmcnt(8)
	s_waitcnt lgkmcnt(0)
	s_barrier
	v_mfma_f32_16x16x32_bf16 v[62:65], v[142:145], v[178:181], v[62:65]
	s_setprio 1
	v_mfma_f32_16x16x32_bf16 v[58:61], v[150:153], v[178:181], v[58:61]
	v_mfma_f32_16x16x32_bf16 v[38:41], v[142:145], v[186:189], v[38:41]
	v_mfma_f32_16x16x32_bf16 v[34:37], v[150:153], v[186:189], v[34:37]
	v_mfma_f32_16x16x32_bf16 v[22:25], v[142:145], v[194:197], v[22:25]
	v_mfma_f32_16x16x32_bf16 v[18:21], v[150:153], v[194:197], v[18:21]
	v_mfma_f32_16x16x32_bf16 v[134:137], v[142:145], v[202:205], v[134:137]
	v_mfma_f32_16x16x32_bf16 v[130:133], v[150:153], v[202:205], v[130:133]
	v_mfma_f32_16x16x32_bf16 v[62:65], v[146:149], v[182:185], v[62:65]
	v_mfma_f32_16x16x32_bf16 v[58:61], v[158:161], v[182:185], v[58:61]
	v_mfma_f32_16x16x32_bf16 v[38:41], v[146:149], v[190:193], v[38:41]
	v_mfma_f32_16x16x32_bf16 v[34:37], v[158:161], v[190:193], v[34:37]
	v_mfma_f32_16x16x32_bf16 v[22:25], v[146:149], v[198:201], v[22:25]
	v_mfma_f32_16x16x32_bf16 v[18:21], v[158:161], v[198:201], v[18:21]
	v_mfma_f32_16x16x32_bf16 v[134:137], v[146:149], v[206:209], v[134:137]
	v_mfma_f32_16x16x32_bf16 v[130:133], v[158:161], v[206:209], v[130:133]
	s_setprio 0
	s_setprio 1
	v_mfma_f32_16x16x32_bf16 v[42:45], v[162:165], v[178:181], v[42:45]
	v_mfma_f32_16x16x32_bf16 v[46:49], v[170:173], v[178:181], v[46:49]
	v_mfma_f32_16x16x32_bf16 v[26:29], v[162:165], v[186:189], v[26:29]
	v_mfma_f32_16x16x32_bf16 v[30:33], v[170:173], v[186:189], v[30:33]
	v_mfma_f32_16x16x32_bf16 v[14:17], v[162:165], v[194:197], v[14:17]
	v_mfma_f32_16x16x32_bf16 v[10:13], v[170:173], v[194:197], v[10:13]
	v_mfma_f32_16x16x32_bf16 v[6:9], v[162:165], v[202:205], v[6:9]
	v_mfma_f32_16x16x32_bf16 v[2:5], v[170:173], v[202:205], v[2:5]
	v_mfma_f32_16x16x32_bf16 v[42:45], v[166:169], v[182:185], v[42:45]
	v_mfma_f32_16x16x32_bf16 v[46:49], v[174:177], v[182:185], v[46:49]
	v_mfma_f32_16x16x32_bf16 v[26:29], v[166:169], v[190:193], v[26:29]
	v_mfma_f32_16x16x32_bf16 v[30:33], v[174:177], v[190:193], v[30:33]
	v_mfma_f32_16x16x32_bf16 v[14:17], v[166:169], v[198:201], v[14:17]
	v_mfma_f32_16x16x32_bf16 v[10:13], v[174:177], v[198:201], v[10:13]
	v_mfma_f32_16x16x32_bf16 v[6:9], v[166:169], v[206:209], v[6:9]
	v_mfma_f32_16x16x32_bf16 v[2:5], v[174:177], v[206:209], v[2:5]
	s_barrier
	s_setprio 0
	s_add_i32 s16, s60, 2
	s_add_u32 vcc_lo, vcc_lo, 0x100
	s_addc_u32 vcc_hi, vcc_hi, 0
	v_lshl_add_u64 v[138:139], v[138:139], 0, s[72:73]
	v_lshl_add_u64 v[128:129], v[128:129], 0, s[72:73]
	s_cmp_ge_i32 s60, s87
	s_mov_b32 s60, s16
	s_cbranch_scc0 .LBB0_1854
	s_and_b64 vcc, exec, s[40:41]
	s_cbranch_vccz .LBB0_1857
	s_barrier
